# accumulator zeroing removed in the remaining six GEMM loops too (peeled first two phases with C=0)
# speedup vs baseline: 1.0056x; 1.0020x over previous
.LBB0_607:
	v_and_b32_e32 v14, 15, v0
	v_and_b32_e32 v15, 48, v0
	v_lshlrev_b32_e32 v16, 2, v0
	v_lshl_or_b32 v1, s2, 6, v14
	v_lshl_or_b32 v14, v14, 6, v15
	s_lshl_b32 s2, s2, 13
	v_and_b32_e32 v16, 32, v16
	s_mov_b64 s[20:21], 0x80
	s_and_b32 s30, s4, 3
	v_bitop3_b32 v14, v14, s2, v16 bitop3:0xde
	v_lshlrev_b32_e32 v17, 6, v0
	s_movk_i32 s2, 0x3c0
	s_add_i32 m0, s33, 0x18000
	v_lshl_add_u64 v[8:9], v[8:9], 0, s[20:21]
	v_and_or_b32 v15, v17, s2, v15
	s_lshl_b32 s2, s30, 12
	s_waitcnt vmcnt(2)
	s_barrier
	global_load_lds_dwordx4 v[8:9], off
	v_lshl_add_u64 v[6:7], v[6:7], 0, s[20:21]
	s_add_i32 m0, s33, 0x1a000
	s_add_i32 s42, s33, 0x8000
	s_add_i32 s43, s33, 0xa000
	global_load_lds_dwordx4 v[6:7], off
	v_lshl_add_u64 v[4:5], v[4:5], 0, s[20:21]
	s_mov_b32 m0, s42
	s_add_u32 s6, s24, 0xb0080
	global_load_lds_dwordx4 v[4:5], off
	v_lshl_add_u64 v[2:3], v[2:3], 0, s[20:21]
	s_mov_b32 m0, s43
	s_addc_u32 s7, s25, 0
	global_load_lds_dwordx4 v[2:3], off
	s_add_i32 m0, s33, 0x1c000
	v_lshl_add_u64 v[2:3], s[6:7], 0, v[132:133]
	global_load_lds_dwordx4 v[2:3], off
	v_lshl_add_u64 v[2:3], s[6:7], 0, v[136:137]
	s_add_i32 m0, s33, 0x1e000
	s_sext_i32_i8 s10, s5
	global_load_lds_dwordx4 v[2:3], off
	v_add_u16_e32 v2, v10, v11
	v_lshrrev_b16_e32 v4, 1, v2
	s_mov_b64 s[4:5], 0xb0080
	s_waitcnt vmcnt(6)
	v_add_lshl_u32 v2, v12, v4, 1
	v_mov_b32_e32 v3, v133
	v_lshl_add_u64 v[138:139], v[2:3], 0, s[4:5]
	v_add_lshl_u32 v2, v13, v4, 1
	v_bitop3_b32 v151, s2, v15, v16 bitop3:0xf6
	v_lshl_add_u64 v[140:141], v[2:3], 0, s[4:5]
	v_mov_b64_e32 v[142:143], 0x100
	v_mov_b64_e32 v[144:145], 0xff
	s_add_i32 s44, 0, 0x10000
	s_add_i32 s45, 0, 0x14000
	v_add_u32_e32 v152, 0, v14
	v_mov_b32_e32 v2, v133
	v_mov_b32_e32 v4, v133
	v_mov_b32_e32 v13, v133
	v_mov_b32_e32 v14, v133
	v_mov_b32_e32 v15, v133
	v_mov_b32_e32 v16, v133
	s_barrier

.LBB0_618:
	s_add_u32 s48, s24, 0x100
	s_addc_u32 s49, s25, 0
	v_lshl_add_u64 v[146:147], s[18:19], 0, v[138:139]
	v_lshl_add_u64 v[148:149], s[18:19], 0, v[140:141]
	s_mov_b32 s50, -2
	s_mov_b64 s[24:25], 0
	v_add_u32_e32 v153, s44, v151
	ds_read_b128 v[154:157], v153
	ds_read_b128 v[158:161], v153 offset:1024
	ds_read_b128 v[162:165], v153 offset:2048
	ds_read_b128 v[166:169], v153 offset:3072
	v_add_u32_e32 v153, s45, v151
	s_add_u32 s26, s18, s24
	ds_read_b128 v[170:173], v153
	ds_read_b128 v[174:177], v153 offset:1024
	ds_read_b128 v[178:181], v153 offset:2048
	ds_read_b128 v[182:185], v153 offset:3072
	s_addc_u32 s27, s19, s25
	s_add_u32 s26, s26, 0x100
	s_addc_u32 s27, s27, 0
	s_add_u32 s51, s48, s24
	s_addc_u32 s52, s49, s25
	s_cmpk_eq_i32 s24, 0x1500
	s_cselect_b32 s29, s23, s27
	s_cselect_b32 s28, s22, s26
	s_cselect_b32 s27, s9, s52
	s_cselect_b32 s26, s8, s51
	v_lshl_add_u64 v[218:219], v[146:147], 0, s[24:25]
	s_add_i32 m0, s33, 0xc000
	ds_read_b128 v[186:189], v152
	ds_read_b128 v[190:193], v152 offset:1024
	ds_read_b128 v[194:197], v152 offset:2048
	ds_read_b128 v[198:201], v152 offset:3072
	ds_read_b128 v[202:205], v152 offset:4096
	ds_read_b128 v[206:209], v152 offset:5120
	ds_read_b128 v[210:213], v152 offset:6144
	ds_read_b128 v[214:217], v152 offset:7168
	global_load_lds_dwordx4 v[218:219], off
	v_lshl_add_u64 v[218:219], v[148:149], 0, s[24:25]
	s_add_i32 m0, s33, 0xe000
	s_nop 0
	global_load_lds_dwordx4 v[218:219], off
	s_waitcnt vmcnt(8) lgkmcnt(0)
	s_barrier
	v_mfma_f32_16x16x32_bf16 v[126:129], v[154:157], v[186:189], 0
	v_mfma_f32_16x16x32_bf16 v[122:125], v[162:165], v[186:189], 0
	v_mfma_f32_16x16x32_bf16 v[110:113], v[154:157], v[194:197], 0
	v_mfma_f32_16x16x32_bf16 v[106:109], v[162:165], v[194:197], 0
	v_mfma_f32_16x16x32_bf16 v[94:97], v[154:157], v[202:205], 0
	v_mfma_f32_16x16x32_bf16 v[90:93], v[162:165], v[202:205], 0
	v_mfma_f32_16x16x32_bf16 v[78:81], v[154:157], v[210:213], 0
	v_mfma_f32_16x16x32_bf16 v[74:77], v[162:165], v[210:213], 0
	v_mfma_f32_16x16x32_bf16 v[126:129], v[158:161], v[190:193], v[126:129]
	v_mfma_f32_16x16x32_bf16 v[122:125], v[166:169], v[190:193], v[122:125]
	v_mfma_f32_16x16x32_bf16 v[110:113], v[158:161], v[198:201], v[110:113]
	v_mfma_f32_16x16x32_bf16 v[106:109], v[166:169], v[198:201], v[106:109]
	v_mfma_f32_16x16x32_bf16 v[94:97], v[158:161], v[206:209], v[94:97]
	v_mfma_f32_16x16x32_bf16 v[90:93], v[166:169], v[206:209], v[90:93]
	v_mfma_f32_16x16x32_bf16 v[78:81], v[158:161], v[214:217], v[78:81]
	v_mfma_f32_16x16x32_bf16 v[74:77], v[166:169], v[214:217], v[74:77]
	v_mfma_f32_16x16x32_bf16 v[118:121], v[170:173], v[186:189], 0
	v_mfma_f32_16x16x32_bf16 v[114:117], v[178:181], v[186:189], 0
	v_mfma_f32_16x16x32_bf16 v[102:105], v[170:173], v[194:197], 0
	v_mfma_f32_16x16x32_bf16 v[98:101], v[178:181], v[194:197], 0
	v_mfma_f32_16x16x32_bf16 v[86:89], v[170:173], v[202:205], 0
	v_mfma_f32_16x16x32_bf16 v[82:85], v[178:181], v[202:205], 0
	v_mfma_f32_16x16x32_bf16 v[70:73], v[170:173], v[210:213], 0
	v_mfma_f32_16x16x32_bf16 v[66:69], v[178:181], v[210:213], 0
	v_mfma_f32_16x16x32_bf16 v[118:121], v[174:177], v[190:193], v[118:121]
	v_mfma_f32_16x16x32_bf16 v[114:117], v[182:185], v[190:193], v[114:117]
	v_mfma_f32_16x16x32_bf16 v[102:105], v[174:177], v[198:201], v[102:105]
	v_mfma_f32_16x16x32_bf16 v[98:101], v[182:185], v[198:201], v[98:101]
	v_mfma_f32_16x16x32_bf16 v[86:89], v[174:177], v[206:209], v[86:89]
	v_mfma_f32_16x16x32_bf16 v[82:85], v[182:185], v[206:209], v[82:85]
	v_mfma_f32_16x16x32_bf16 v[70:73], v[174:177], v[214:217], v[70:73]
	v_mfma_f32_16x16x32_bf16 v[66:69], v[182:185], v[214:217], v[66:69]
	s_barrier
	s_add_i32 s51, s44, s13
	s_add_u32 s98, s26, s20
	s_addc_u32 s99, s27, s21
	s_mov_b32 m0, s51
	ds_read_b128 v[186:189], v152 offset:16384
	ds_read_b128 v[190:193], v152 offset:17408
	ds_read_b128 v[194:197], v152 offset:18432
	ds_read_b128 v[198:201], v152 offset:19456
	ds_read_b128 v[202:205], v152 offset:20480
	ds_read_b128 v[206:209], v152 offset:21504
	ds_read_b128 v[210:213], v152 offset:22528
	ds_read_b128 v[214:217], v152 offset:23552
	global_load_lds_dwordx4 v132, s[26:27]
	s_add_i32 m0, s51, 0x2000
	s_add_u32 s52, s26, 0xb0000
	s_addc_u32 s53, s27, 0
	s_add_i32 s51, s45, s13
	global_load_lds_dwordx4 v136, s[26:27]
	s_mov_b32 m0, s51
	s_nop 0
	global_load_lds_dwordx4 v132, s[52:53]
	s_add_i32 m0, s51, 0x2000
	s_nop 0
	global_load_lds_dwordx4 v136, s[52:53]
	s_add_u32 s100, s28, s20
	s_addc_u32 s101, s29, s21
	s_mov_b32 m0, s33
	s_nop 0
	global_load_lds_dwordx4 v130, s[28:29]
	s_mov_b32 m0, s14
	s_nop 0
	global_load_lds_dwordx4 v134, s[28:29]
	s_waitcnt vmcnt(8) lgkmcnt(0)
	s_barrier
	v_mfma_f32_16x16x32_bf16 v[62:65], v[154:157], v[186:189], 0
	v_mfma_f32_16x16x32_bf16 v[58:61], v[162:165], v[186:189], 0
	v_mfma_f32_16x16x32_bf16 v[46:49], v[154:157], v[194:197], 0
	v_mfma_f32_16x16x32_bf16 v[42:45], v[162:165], v[194:197], 0
	v_mfma_f32_16x16x32_bf16 v[30:33], v[154:157], v[202:205], 0
	v_mfma_f32_16x16x32_bf16 v[26:29], v[162:165], v[202:205], 0
	v_mfma_f32_16x16x32_bf16 v[14:17], v[154:157], v[210:213], 0
	v_mfma_f32_16x16x32_bf16 v[10:13], v[162:165], v[210:213], 0
	v_mfma_f32_16x16x32_bf16 v[62:65], v[158:161], v[190:193], v[62:65]
	v_mfma_f32_16x16x32_bf16 v[58:61], v[166:169], v[190:193], v[58:61]
	v_mfma_f32_16x16x32_bf16 v[46:49], v[158:161], v[198:201], v[46:49]
	v_mfma_f32_16x16x32_bf16 v[42:45], v[166:169], v[198:201], v[42:45]
	v_mfma_f32_16x16x32_bf16 v[30:33], v[158:161], v[206:209], v[30:33]
	v_mfma_f32_16x16x32_bf16 v[26:29], v[166:169], v[206:209], v[26:29]
	v_mfma_f32_16x16x32_bf16 v[14:17], v[158:161], v[214:217], v[14:17]
	v_mfma_f32_16x16x32_bf16 v[10:13], v[166:169], v[214:217], v[10:13]
	v_mfma_f32_16x16x32_bf16 v[54:57], v[170:173], v[186:189], 0
	v_mfma_f32_16x16x32_bf16 v[50:53], v[178:181], v[186:189], 0
	v_mfma_f32_16x16x32_bf16 v[38:41], v[170:173], v[194:197], 0
	v_mfma_f32_16x16x32_bf16 v[34:37], v[178:181], v[194:197], 0
	v_mfma_f32_16x16x32_bf16 v[22:25], v[170:173], v[202:205], 0
	v_mfma_f32_16x16x32_bf16 v[18:21], v[178:181], v[202:205], 0
	v_mfma_f32_16x16x32_bf16 v[6:9], v[170:173], v[210:213], 0
	v_mfma_f32_16x16x32_bf16 v[2:5], v[178:181], v[210:213], 0
	v_mfma_f32_16x16x32_bf16 v[54:57], v[174:177], v[190:193], v[54:57]
	v_mfma_f32_16x16x32_bf16 v[50:53], v[182:185], v[190:193], v[50:53]
	v_mfma_f32_16x16x32_bf16 v[38:41], v[174:177], v[198:201], v[38:41]
	v_mfma_f32_16x16x32_bf16 v[34:37], v[182:185], v[198:201], v[34:37]
	v_mfma_f32_16x16x32_bf16 v[22:25], v[174:177], v[206:209], v[22:25]
	v_mfma_f32_16x16x32_bf16 v[18:21], v[182:185], v[206:209], v[18:21]
	v_mfma_f32_16x16x32_bf16 v[6:9], v[174:177], v[214:217], v[6:9]
	v_mfma_f32_16x16x32_bf16 v[2:5], v[182:185], v[214:217], v[2:5]
	s_barrier
	s_branch .Lpeel2_p3

.Lpeel2_p3:
	s_add_i32 s51, 0, 0x18000
	v_add_u32_e32 v153, s51, v151
	s_add_i32 s52, 0, 0x1c000
	ds_read_b128 v[154:157], v153
	ds_read_b128 v[158:161], v153 offset:1024
	ds_read_b128 v[162:165], v153 offset:2048
	ds_read_b128 v[166:169], v153 offset:3072
	v_add_u32_e32 v153, s52, v151
	ds_read_b128 v[170:173], v153
	ds_read_b128 v[174:177], v153 offset:1024
	ds_read_b128 v[178:181], v153 offset:2048
	ds_read_b128 v[182:185], v153 offset:3072
	s_add_u32 s28, s28, 0xb0000
	s_addc_u32 s29, s29, 0
	s_mov_b32 m0, s15
	ds_read_b128 v[186:189], v152 offset:32768
	ds_read_b128 v[190:193], v152 offset:33792
	ds_read_b128 v[194:197], v152 offset:34816
	ds_read_b128 v[198:201], v152 offset:35840
	ds_read_b128 v[202:205], v152 offset:36864
	ds_read_b128 v[206:209], v152 offset:37888
	ds_read_b128 v[210:213], v152 offset:38912
	ds_read_b128 v[214:217], v152 offset:39936
	global_load_lds_dwordx4 v130, s[28:29]
	s_mov_b32 m0, s40
	s_nop 0
	global_load_lds_dwordx4 v134, s[28:29]
	s_waitcnt vmcnt(8) lgkmcnt(0)
	s_barrier
	v_mfma_f32_16x16x32_bf16 v[126:129], v[154:157], v[186:189], v[126:129]
	v_mfma_f32_16x16x32_bf16 v[122:125], v[162:165], v[186:189], v[122:125]
	v_mfma_f32_16x16x32_bf16 v[110:113], v[154:157], v[194:197], v[110:113]
	v_mfma_f32_16x16x32_bf16 v[106:109], v[162:165], v[194:197], v[106:109]
	v_mfma_f32_16x16x32_bf16 v[94:97], v[154:157], v[202:205], v[94:97]
	v_mfma_f32_16x16x32_bf16 v[90:93], v[162:165], v[202:205], v[90:93]
	v_mfma_f32_16x16x32_bf16 v[78:81], v[154:157], v[210:213], v[78:81]
	v_mfma_f32_16x16x32_bf16 v[74:77], v[162:165], v[210:213], v[74:77]
	v_mfma_f32_16x16x32_bf16 v[126:129], v[158:161], v[190:193], v[126:129]
	v_mfma_f32_16x16x32_bf16 v[122:125], v[166:169], v[190:193], v[122:125]
	v_mfma_f32_16x16x32_bf16 v[110:113], v[158:161], v[198:201], v[110:113]
	v_mfma_f32_16x16x32_bf16 v[106:109], v[166:169], v[198:201], v[106:109]
	v_mfma_f32_16x16x32_bf16 v[94:97], v[158:161], v[206:209], v[94:97]
	v_mfma_f32_16x16x32_bf16 v[90:93], v[166:169], v[206:209], v[90:93]
	v_mfma_f32_16x16x32_bf16 v[78:81], v[158:161], v[214:217], v[78:81]
	v_mfma_f32_16x16x32_bf16 v[74:77], v[166:169], v[214:217], v[74:77]
	v_mfma_f32_16x16x32_bf16 v[118:121], v[170:173], v[186:189], v[118:121]
	v_mfma_f32_16x16x32_bf16 v[114:117], v[178:181], v[186:189], v[114:117]
	v_mfma_f32_16x16x32_bf16 v[102:105], v[170:173], v[194:197], v[102:105]
	v_mfma_f32_16x16x32_bf16 v[98:101], v[178:181], v[194:197], v[98:101]
	v_mfma_f32_16x16x32_bf16 v[86:89], v[170:173], v[202:205], v[86:89]
	v_mfma_f32_16x16x32_bf16 v[82:85], v[178:181], v[202:205], v[82:85]
	v_mfma_f32_16x16x32_bf16 v[70:73], v[170:173], v[210:213], v[70:73]
	v_mfma_f32_16x16x32_bf16 v[66:69], v[178:181], v[210:213], v[66:69]
	v_mfma_f32_16x16x32_bf16 v[118:121], v[174:177], v[190:193], v[118:121]
	v_mfma_f32_16x16x32_bf16 v[114:117], v[182:185], v[190:193], v[114:117]
	v_mfma_f32_16x16x32_bf16 v[102:105], v[174:177], v[198:201], v[102:105]
	v_mfma_f32_16x16x32_bf16 v[98:101], v[182:185], v[198:201], v[98:101]
	v_mfma_f32_16x16x32_bf16 v[86:89], v[174:177], v[206:209], v[86:89]
	v_mfma_f32_16x16x32_bf16 v[82:85], v[182:185], v[206:209], v[82:85]
	v_mfma_f32_16x16x32_bf16 v[70:73], v[174:177], v[214:217], v[70:73]
	v_mfma_f32_16x16x32_bf16 v[66:69], v[182:185], v[214:217], v[66:69]
	s_barrier
	s_add_i32 s28, s51, s13
	s_mov_b32 m0, s28
	ds_read_b128 v[186:189], v152 offset:49152
	ds_read_b128 v[190:193], v152 offset:50176
	ds_read_b128 v[194:197], v152 offset:51200
	ds_read_b128 v[198:201], v152 offset:52224
	ds_read_b128 v[202:205], v152 offset:53248
	ds_read_b128 v[206:209], v152 offset:54272
	ds_read_b128 v[210:213], v152 offset:55296
	ds_read_b128 v[214:217], v152 offset:56320
	global_load_lds_dwordx4 v132, s[98:99]
	s_add_i32 m0, s28, 0x2000
	s_add_u32 s26, s26, 0xb0080
	s_addc_u32 s27, s27, 0
	s_add_i32 s28, s52, s13
	global_load_lds_dwordx4 v136, s[98:99]
	s_mov_b32 m0, s28
	s_nop 0
	global_load_lds_dwordx4 v132, s[26:27]
	s_add_i32 m0, s28, 0x2000
	s_nop 0
	global_load_lds_dwordx4 v136, s[26:27]
	s_mov_b32 m0, s42
	s_nop 0
	global_load_lds_dwordx4 v130, s[100:101]
	s_mov_b32 m0, s43
	s_nop 0
	global_load_lds_dwordx4 v134, s[100:101]
	s_waitcnt vmcnt(8) lgkmcnt(0)
	s_barrier
	v_mfma_f32_16x16x32_bf16 v[62:65], v[154:157], v[186:189], v[62:65]
	v_mfma_f32_16x16x32_bf16 v[58:61], v[162:165], v[186:189], v[58:61]
	v_mfma_f32_16x16x32_bf16 v[46:49], v[154:157], v[194:197], v[46:49]
	v_mfma_f32_16x16x32_bf16 v[42:45], v[162:165], v[194:197], v[42:45]
	v_mfma_f32_16x16x32_bf16 v[30:33], v[154:157], v[202:205], v[30:33]
	v_mfma_f32_16x16x32_bf16 v[26:29], v[162:165], v[202:205], v[26:29]
	v_mfma_f32_16x16x32_bf16 v[14:17], v[154:157], v[210:213], v[14:17]
	v_mfma_f32_16x16x32_bf16 v[10:13], v[162:165], v[210:213], v[10:13]
	v_mfma_f32_16x16x32_bf16 v[62:65], v[158:161], v[190:193], v[62:65]
	v_mfma_f32_16x16x32_bf16 v[58:61], v[166:169], v[190:193], v[58:61]
	v_mfma_f32_16x16x32_bf16 v[46:49], v[158:161], v[198:201], v[46:49]
	v_mfma_f32_16x16x32_bf16 v[42:45], v[166:169], v[198:201], v[42:45]
	v_mfma_f32_16x16x32_bf16 v[30:33], v[158:161], v[206:209], v[30:33]
	v_mfma_f32_16x16x32_bf16 v[26:29], v[166:169], v[206:209], v[26:29]
	v_mfma_f32_16x16x32_bf16 v[14:17], v[158:161], v[214:217], v[14:17]
	v_mfma_f32_16x16x32_bf16 v[10:13], v[166:169], v[214:217], v[10:13]
	v_mfma_f32_16x16x32_bf16 v[54:57], v[170:173], v[186:189], v[54:57]
	v_mfma_f32_16x16x32_bf16 v[50:53], v[178:181], v[186:189], v[50:53]
	v_mfma_f32_16x16x32_bf16 v[38:41], v[170:173], v[194:197], v[38:41]
	v_mfma_f32_16x16x32_bf16 v[34:37], v[178:181], v[194:197], v[34:37]
	v_mfma_f32_16x16x32_bf16 v[22:25], v[170:173], v[202:205], v[22:25]
	v_mfma_f32_16x16x32_bf16 v[18:21], v[178:181], v[202:205], v[18:21]
	v_mfma_f32_16x16x32_bf16 v[6:9], v[170:173], v[210:213], v[6:9]
	v_mfma_f32_16x16x32_bf16 v[2:5], v[178:181], v[210:213], v[2:5]
	v_mfma_f32_16x16x32_bf16 v[54:57], v[174:177], v[190:193], v[54:57]
	v_mfma_f32_16x16x32_bf16 v[50:53], v[182:185], v[190:193], v[50:53]
	v_mfma_f32_16x16x32_bf16 v[38:41], v[174:177], v[198:201], v[38:41]
	v_mfma_f32_16x16x32_bf16 v[34:37], v[182:185], v[198:201], v[34:37]
	v_mfma_f32_16x16x32_bf16 v[22:25], v[174:177], v[206:209], v[22:25]
	v_mfma_f32_16x16x32_bf16 v[18:21], v[182:185], v[206:209], v[18:21]
	v_mfma_f32_16x16x32_bf16 v[6:9], v[174:177], v[214:217], v[6:9]
	v_mfma_f32_16x16x32_bf16 v[2:5], v[182:185], v[214:217], v[2:5]
	s_barrier
	s_add_i32 s50, s50, 2
	s_add_u32 s24, s24, 0x100
	s_addc_u32 s25, s25, 0
	s_cmp_gt_u32 s50, 41
	s_cbranch_scc0 .LBB0_619
	s_add_u32 s24, s48, 0xffffff00
	s_addc_u32 s25, s49, -1
	s_and_b64 vcc, exec, s[6:7]
	s_cbranch_vccnz .LBB0_622
	v_mov_b32_e32 v2, 0
	s_mov_b32 s10, s46
	s_mov_b32 s31, s47
	s_mov_b64 s[18:19], s[22:23]
	s_mov_b32 s41, s2
	v_mov_b32_e32 v3, v2
	v_mov_b32_e32 v4, v2
	v_mov_b32_e32 v5, v2
	v_mov_b32_e32 v6, v2
	v_mov_b32_e32 v7, v2
	v_mov_b32_e32 v8, v2
	v_mov_b32_e32 v9, v2
	v_mov_b32_e32 v18, v2
	v_mov_b32_e32 v19, v2
	v_mov_b32_e32 v20, v2
	v_mov_b32_e32 v21, v2
	v_mov_b32_e32 v22, v2
	v_mov_b32_e32 v23, v2
	v_mov_b32_e32 v24, v2
	v_mov_b32_e32 v25, v2
	v_mov_b32_e32 v34, v2
	v_mov_b32_e32 v35, v2
	v_mov_b32_e32 v36, v2
	v_mov_b32_e32 v37, v2
	v_mov_b32_e32 v38, v2
	v_mov_b32_e32 v39, v2
	v_mov_b32_e32 v40, v2
	v_mov_b32_e32 v41, v2
	v_mov_b32_e32 v50, v2
	v_mov_b32_e32 v51, v2
	v_mov_b32_e32 v52, v2
	v_mov_b32_e32 v53, v2
	v_mov_b32_e32 v54, v2
	v_mov_b32_e32 v55, v2
	v_mov_b32_e32 v56, v2
	v_mov_b32_e32 v57, v2
	v_mov_b32_e32 v10, v2
	v_mov_b32_e32 v11, v2
	v_mov_b32_e32 v12, v2
	v_mov_b32_e32 v13, v2
	v_mov_b32_e32 v14, v2
	v_mov_b32_e32 v15, v2
	v_mov_b32_e32 v16, v2
	v_mov_b32_e32 v17, v2
	v_mov_b32_e32 v26, v2
	v_mov_b32_e32 v27, v2
	v_mov_b32_e32 v28, v2
	v_mov_b32_e32 v29, v2
	v_mov_b32_e32 v30, v2
	v_mov_b32_e32 v31, v2
	v_mov_b32_e32 v32, v2
	v_mov_b32_e32 v33, v2
	v_mov_b32_e32 v42, v2
	v_mov_b32_e32 v43, v2
	v_mov_b32_e32 v44, v2
	v_mov_b32_e32 v45, v2
	v_mov_b32_e32 v46, v2
	v_mov_b32_e32 v47, v2
	v_mov_b32_e32 v48, v2
	v_mov_b32_e32 v49, v2
	v_mov_b32_e32 v58, v2
	v_mov_b32_e32 v59, v2
	v_mov_b32_e32 v60, v2
	v_mov_b32_e32 v61, v2
	v_mov_b32_e32 v62, v2
	v_mov_b32_e32 v63, v2
	v_mov_b32_e32 v64, v2
	v_mov_b32_e32 v65, v2
	v_mov_b32_e32 v66, v2
	v_mov_b32_e32 v67, v2
	v_mov_b32_e32 v68, v2
	v_mov_b32_e32 v69, v2
	v_mov_b32_e32 v70, v2
	v_mov_b32_e32 v71, v2
	v_mov_b32_e32 v72, v2
	v_mov_b32_e32 v73, v2
	v_mov_b32_e32 v82, v2
	v_mov_b32_e32 v83, v2
	v_mov_b32_e32 v84, v2
	v_mov_b32_e32 v85, v2
	v_mov_b32_e32 v86, v2
	v_mov_b32_e32 v87, v2
	v_mov_b32_e32 v88, v2
	v_mov_b32_e32 v89, v2
	v_mov_b32_e32 v98, v2
	v_mov_b32_e32 v99, v2
	v_mov_b32_e32 v100, v2
	v_mov_b32_e32 v101, v2
	v_mov_b32_e32 v102, v2
	v_mov_b32_e32 v103, v2
	v_mov_b32_e32 v104, v2
	v_mov_b32_e32 v105, v2
	v_mov_b32_e32 v114, v2
	v_mov_b32_e32 v115, v2
	v_mov_b32_e32 v116, v2
	v_mov_b32_e32 v117, v2
	v_mov_b32_e32 v118, v2
	v_mov_b32_e32 v119, v2
	v_mov_b32_e32 v120, v2
	v_mov_b32_e32 v121, v2
	v_mov_b32_e32 v74, v2
	v_mov_b32_e32 v75, v2
	v_mov_b32_e32 v76, v2
	v_mov_b32_e32 v77, v2
	v_mov_b32_e32 v78, v2
	v_mov_b32_e32 v79, v2
	v_mov_b32_e32 v80, v2
	v_mov_b32_e32 v81, v2
	v_mov_b32_e32 v90, v2
	v_mov_b32_e32 v91, v2
	v_mov_b32_e32 v92, v2
	v_mov_b32_e32 v93, v2
	v_mov_b32_e32 v94, v2
	v_mov_b32_e32 v95, v2
	v_mov_b32_e32 v96, v2
	v_mov_b32_e32 v97, v2
	v_mov_b32_e32 v106, v2
	v_mov_b32_e32 v107, v2
	v_mov_b32_e32 v108, v2
	v_mov_b32_e32 v109, v2
	v_mov_b32_e32 v110, v2
	v_mov_b32_e32 v111, v2
	v_mov_b32_e32 v112, v2
	v_mov_b32_e32 v113, v2
	v_mov_b32_e32 v122, v2
	v_mov_b32_e32 v123, v2
	v_mov_b32_e32 v124, v2
	v_mov_b32_e32 v125, v2
	v_mov_b32_e32 v126, v2
	v_mov_b32_e32 v127, v2
	v_mov_b32_e32 v128, v2
	v_mov_b32_e32 v129, v2
	s_andn2_b64 vcc, exec, s[4:5]
	s_cbranch_vccnz .LBB0_623
	s_branch .LBB0_624

.LBB0_773:
	s_ashr_i32 s51, s50, 31
	s_lshl_b64 s[0:1], s[50:51], 19
	v_readlane_b32 s12, v255, 8
	v_readlane_b32 s13, v255, 9
	s_add_u32 s52, s12, s0
	s_addc_u32 s53, s13, s1
	s_and_b64 s[0:1], s[4:5], exec
	s_cselect_b32 s0, s53, s11
	s_cselect_b32 s1, s52, s10
	s_ashr_i32 s49, s48, 31
	s_lshl_b64 s[12:13], s[48:49], 19
	s_add_u32 s54, s64, s12
	s_addc_u32 s55, s65, s13
	s_and_b64 s[12:13], s[4:5], exec
	s_cselect_b32 s2, s55, s57
	s_cselect_b32 s7, s54, s56
	s_add_u32 s10, s10, 0x40080
	s_addc_u32 s11, s11, 0
	s_add_u32 s9, s56, 0x100
	s_addc_u32 s12, s57, 0
	s_mov_b32 s13, -2
	ds_read_b128 v[38:41], v231
	ds_read_b128 v[42:45], v231 offset:1024
	ds_read_b128 v[54:57], v231 offset:2048
	ds_read_b128 v[58:61], v231 offset:3072
	ds_read_b128 v[126:129], v232
	ds_read_b128 v[146:149], v232 offset:1024
	ds_read_b128 v[166:169], v232 offset:2048
	ds_read_b128 v[170:173], v232 offset:3072
	s_add_u32 s14, s10, 0xfffc0080
	s_addc_u32 s15, s11, -1
	s_cmp_eq_u32 s13, 12
	s_cselect_b32 s59, s0, s15
	s_cselect_b32 s58, s1, s14
	s_cselect_b32 s57, s2, s12
	s_cselect_b32 s56, s7, s9
	s_add_i32 m0, s67, 0xc000
	ds_read_b128 v[174:177], v233
	ds_read_b128 v[194:197], v233 offset:1024
	ds_read_b128 v[198:201], v233 offset:2048
	ds_read_b128 v[202:205], v233 offset:3072
	ds_read_b128 v[206:209], v233 offset:4096
	ds_read_b128 v[210:213], v233 offset:5120
	ds_read_b128 v[214:217], v233 offset:6144
	ds_read_b128 v[218:221], v233 offset:7168
	global_load_lds_dwordx4 v186, s[10:11]
	s_add_i32 m0, s67, 0xe000
	s_nop 0
	global_load_lds_dwordx4 v188, s[10:11]
	s_waitcnt vmcnt(8) lgkmcnt(0)
	s_barrier
	v_mfma_f32_16x16x32_bf16 v[162:165], v[38:41], v[174:177], 0
	v_mfma_f32_16x16x32_bf16 v[158:161], v[54:57], v[174:177], 0
	v_mfma_f32_16x16x32_bf16 v[142:145], v[38:41], v[198:201], 0
	v_mfma_f32_16x16x32_bf16 v[138:141], v[54:57], v[198:201], 0
	v_mfma_f32_16x16x32_bf16 v[122:125], v[38:41], v[206:209], 0
	v_mfma_f32_16x16x32_bf16 v[118:121], v[54:57], v[206:209], 0
	v_mfma_f32_16x16x32_bf16 v[106:109], v[38:41], v[214:217], 0
	v_mfma_f32_16x16x32_bf16 v[102:105], v[54:57], v[214:217], 0
	v_mfma_f32_16x16x32_bf16 v[162:165], v[42:45], v[194:197], v[162:165]
	v_mfma_f32_16x16x32_bf16 v[158:161], v[58:61], v[194:197], v[158:161]
	v_mfma_f32_16x16x32_bf16 v[142:145], v[42:45], v[202:205], v[142:145]
	v_mfma_f32_16x16x32_bf16 v[138:141], v[58:61], v[202:205], v[138:141]
	v_mfma_f32_16x16x32_bf16 v[122:125], v[42:45], v[210:213], v[122:125]
	v_mfma_f32_16x16x32_bf16 v[118:121], v[58:61], v[210:213], v[118:121]
	v_mfma_f32_16x16x32_bf16 v[106:109], v[42:45], v[218:221], v[106:109]
	v_mfma_f32_16x16x32_bf16 v[102:105], v[58:61], v[218:221], v[102:105]
	v_mfma_f32_16x16x32_bf16 v[154:157], v[126:129], v[174:177], 0
	v_mfma_f32_16x16x32_bf16 v[150:153], v[166:169], v[174:177], 0
	v_mfma_f32_16x16x32_bf16 v[134:137], v[126:129], v[198:201], 0
	v_mfma_f32_16x16x32_bf16 v[130:133], v[166:169], v[198:201], 0
	v_mfma_f32_16x16x32_bf16 v[114:117], v[126:129], v[206:209], 0
	v_mfma_f32_16x16x32_bf16 v[110:113], v[166:169], v[206:209], 0
	v_mfma_f32_16x16x32_bf16 v[98:101], v[126:129], v[214:217], 0
	v_mfma_f32_16x16x32_bf16 v[94:97], v[166:169], v[214:217], 0
	v_mfma_f32_16x16x32_bf16 v[154:157], v[146:149], v[194:197], v[154:157]
	v_mfma_f32_16x16x32_bf16 v[150:153], v[170:173], v[194:197], v[150:153]
	v_mfma_f32_16x16x32_bf16 v[134:137], v[146:149], v[202:205], v[134:137]
	v_mfma_f32_16x16x32_bf16 v[130:133], v[170:173], v[202:205], v[130:133]
	v_mfma_f32_16x16x32_bf16 v[114:117], v[146:149], v[210:213], v[114:117]
	v_mfma_f32_16x16x32_bf16 v[110:113], v[170:173], v[210:213], v[110:113]
	v_mfma_f32_16x16x32_bf16 v[98:101], v[146:149], v[218:221], v[98:101]
	v_mfma_f32_16x16x32_bf16 v[94:97], v[170:173], v[218:221], v[94:97]
	s_barrier
	s_add_i32 s14, s84, s66
	s_add_u32 s98, s56, s20
	s_addc_u32 s99, s57, s21
	s_mov_b32 m0, s14
	ds_read_b128 v[174:177], v233 offset:16384
	ds_read_b128 v[194:197], v233 offset:17408
	ds_read_b128 v[198:201], v233 offset:18432
	ds_read_b128 v[202:205], v233 offset:19456
	ds_read_b128 v[206:209], v233 offset:20480
	ds_read_b128 v[210:213], v233 offset:21504
	ds_read_b128 v[214:217], v233 offset:22528
	ds_read_b128 v[218:221], v233 offset:23552
	global_load_lds_dwordx4 v180, s[56:57]
	s_add_i32 m0, s14, 0x2000
	s_add_u32 s14, s56, 0x40000
	s_addc_u32 s15, s57, 0
	s_add_i32 s33, s85, s66
	global_load_lds_dwordx4 v184, s[56:57]
	s_mov_b32 m0, s33
	s_add_u32 s100, s58, s20
	s_addc_u32 s101, s59, s21
	global_load_lds_dwordx4 v180, s[14:15]
	s_add_i32 m0, s33, 0x2000
	s_nop 0
	global_load_lds_dwordx4 v184, s[14:15]
	s_mov_b32 m0, s67
	s_nop 0
	global_load_lds_dwordx4 v178, s[58:59]
	s_mov_b32 m0, s68
	s_nop 0
	global_load_lds_dwordx4 v182, s[58:59]
	s_waitcnt vmcnt(8) lgkmcnt(0)
	s_barrier
	v_mfma_f32_16x16x32_bf16 v[90:93], v[38:41], v[174:177], 0
	v_mfma_f32_16x16x32_bf16 v[86:89], v[54:57], v[174:177], 0
	v_mfma_f32_16x16x32_bf16 v[74:77], v[38:41], v[198:201], 0
	v_mfma_f32_16x16x32_bf16 v[70:73], v[54:57], v[198:201], 0
	v_mfma_f32_16x16x32_bf16 v[50:53], v[38:41], v[206:209], 0
	v_mfma_f32_16x16x32_bf16 v[46:49], v[54:57], v[206:209], 0
	v_mfma_f32_16x16x32_bf16 v[26:29], v[38:41], v[214:217], 0
	v_mfma_f32_16x16x32_bf16 v[22:25], v[54:57], v[214:217], 0
	v_mfma_f32_16x16x32_bf16 v[90:93], v[42:45], v[194:197], v[90:93]
	v_mfma_f32_16x16x32_bf16 v[86:89], v[58:61], v[194:197], v[86:89]
	v_mfma_f32_16x16x32_bf16 v[74:77], v[42:45], v[202:205], v[74:77]
	v_mfma_f32_16x16x32_bf16 v[70:73], v[58:61], v[202:205], v[70:73]
	v_mfma_f32_16x16x32_bf16 v[50:53], v[42:45], v[210:213], v[50:53]
	v_mfma_f32_16x16x32_bf16 v[46:49], v[58:61], v[210:213], v[46:49]
	v_mfma_f32_16x16x32_bf16 v[26:29], v[42:45], v[218:221], v[26:29]
	v_mfma_f32_16x16x32_bf16 v[22:25], v[58:61], v[218:221], v[22:25]
	v_mfma_f32_16x16x32_bf16 v[34:37], v[126:129], v[206:209], 0
	v_mfma_f32_16x16x32_bf16 v[30:33], v[166:169], v[206:209], 0
	v_mfma_f32_16x16x32_bf16 v[18:21], v[126:129], v[214:217], 0
	v_mfma_f32_16x16x32_bf16 v[12:15], v[166:169], v[214:217], 0
	v_mfma_f32_16x16x32_bf16 v[38:41], v[126:129], v[174:177], 0
	v_mfma_f32_16x16x32_bf16 v[42:45], v[166:169], v[174:177], 0
	v_mfma_f32_16x16x32_bf16 v[54:57], v[126:129], v[198:201], 0
	v_mfma_f32_16x16x32_bf16 v[58:61], v[166:169], v[198:201], 0
	v_mfma_f32_16x16x32_bf16 v[34:37], v[146:149], v[210:213], v[34:37]
	v_mfma_f32_16x16x32_bf16 v[30:33], v[170:173], v[210:213], v[30:33]
	v_mfma_f32_16x16x32_bf16 v[18:21], v[146:149], v[218:221], v[18:21]
	v_mfma_f32_16x16x32_bf16 v[12:15], v[170:173], v[218:221], v[12:15]
	v_mfma_f32_16x16x32_bf16 v[38:41], v[146:149], v[194:197], v[38:41]
	v_mfma_f32_16x16x32_bf16 v[42:45], v[170:173], v[194:197], v[42:45]
	v_mfma_f32_16x16x32_bf16 v[54:57], v[146:149], v[202:205], v[54:57]
	v_mfma_f32_16x16x32_bf16 v[58:61], v[170:173], v[202:205], v[58:61]
	s_barrier
	s_branch .Lpeel3_p3

.Lpeel3_p3:
	s_add_i32 s33, 0, 0x18000
	v_add_u32_e32 v3, s33, v230
	s_add_i32 s40, 0, 0x1c000
	ds_read_b128 v[62:65], v3
	ds_read_b128 v[66:69], v3 offset:1024
	ds_read_b128 v[78:81], v3 offset:2048
	ds_read_b128 v[82:85], v3 offset:3072
	v_add_u32_e32 v3, s40, v230
	ds_read_b128 v[126:129], v3
	ds_read_b128 v[146:149], v3 offset:1024
	ds_read_b128 v[166:169], v3 offset:2048
	ds_read_b128 v[170:173], v3 offset:3072
	s_add_u32 s14, s58, 0x40000
	s_addc_u32 s15, s59, 0
	s_mov_b32 m0, s69
	ds_read_b128 v[174:177], v233 offset:32768
	ds_read_b128 v[194:197], v233 offset:33792
	ds_read_b128 v[198:201], v233 offset:34816
	ds_read_b128 v[202:205], v233 offset:35840
	ds_read_b128 v[206:209], v233 offset:36864
	ds_read_b128 v[210:213], v233 offset:37888
	ds_read_b128 v[214:217], v233 offset:38912
	ds_read_b128 v[218:221], v233 offset:39936
	global_load_lds_dwordx4 v178, s[14:15]
	s_mov_b32 m0, s70
	s_nop 0
	global_load_lds_dwordx4 v182, s[14:15]
	s_waitcnt vmcnt(8) lgkmcnt(0)
	s_barrier
	v_mfma_f32_16x16x32_bf16 v[162:165], v[62:65], v[174:177], v[162:165]
	v_mfma_f32_16x16x32_bf16 v[158:161], v[78:81], v[174:177], v[158:161]
	v_mfma_f32_16x16x32_bf16 v[142:145], v[62:65], v[198:201], v[142:145]
	v_mfma_f32_16x16x32_bf16 v[138:141], v[78:81], v[198:201], v[138:141]
	v_mfma_f32_16x16x32_bf16 v[122:125], v[62:65], v[206:209], v[122:125]
	v_mfma_f32_16x16x32_bf16 v[118:121], v[78:81], v[206:209], v[118:121]
	v_mfma_f32_16x16x32_bf16 v[106:109], v[62:65], v[214:217], v[106:109]
	v_mfma_f32_16x16x32_bf16 v[102:105], v[78:81], v[214:217], v[102:105]
	v_mfma_f32_16x16x32_bf16 v[162:165], v[66:69], v[194:197], v[162:165]
	v_mfma_f32_16x16x32_bf16 v[158:161], v[82:85], v[194:197], v[158:161]
	v_mfma_f32_16x16x32_bf16 v[142:145], v[66:69], v[202:205], v[142:145]
	v_mfma_f32_16x16x32_bf16 v[138:141], v[82:85], v[202:205], v[138:141]
	v_mfma_f32_16x16x32_bf16 v[122:125], v[66:69], v[210:213], v[122:125]
	v_mfma_f32_16x16x32_bf16 v[118:121], v[82:85], v[210:213], v[118:121]
	v_mfma_f32_16x16x32_bf16 v[106:109], v[66:69], v[218:221], v[106:109]
	v_mfma_f32_16x16x32_bf16 v[102:105], v[82:85], v[218:221], v[102:105]
	v_mfma_f32_16x16x32_bf16 v[154:157], v[126:129], v[174:177], v[154:157]
	v_mfma_f32_16x16x32_bf16 v[150:153], v[166:169], v[174:177], v[150:153]
	v_mfma_f32_16x16x32_bf16 v[134:137], v[126:129], v[198:201], v[134:137]
	v_mfma_f32_16x16x32_bf16 v[130:133], v[166:169], v[198:201], v[130:133]
	v_mfma_f32_16x16x32_bf16 v[114:117], v[126:129], v[206:209], v[114:117]
	v_mfma_f32_16x16x32_bf16 v[110:113], v[166:169], v[206:209], v[110:113]
	v_mfma_f32_16x16x32_bf16 v[98:101], v[126:129], v[214:217], v[98:101]
	v_mfma_f32_16x16x32_bf16 v[94:97], v[166:169], v[214:217], v[94:97]
	v_mfma_f32_16x16x32_bf16 v[154:157], v[146:149], v[194:197], v[154:157]
	v_mfma_f32_16x16x32_bf16 v[150:153], v[170:173], v[194:197], v[150:153]
	v_mfma_f32_16x16x32_bf16 v[134:137], v[146:149], v[202:205], v[134:137]
	v_mfma_f32_16x16x32_bf16 v[130:133], v[170:173], v[202:205], v[130:133]
	v_mfma_f32_16x16x32_bf16 v[114:117], v[146:149], v[210:213], v[114:117]
	v_mfma_f32_16x16x32_bf16 v[110:113], v[170:173], v[210:213], v[110:113]
	v_mfma_f32_16x16x32_bf16 v[98:101], v[146:149], v[218:221], v[98:101]
	v_mfma_f32_16x16x32_bf16 v[94:97], v[170:173], v[218:221], v[94:97]
	s_barrier
	s_add_i32 s14, s33, s66
	s_mov_b32 m0, s14
	ds_read_b128 v[174:177], v233 offset:49152
	ds_read_b128 v[194:197], v233 offset:50176
	ds_read_b128 v[198:201], v233 offset:51200
	ds_read_b128 v[202:205], v233 offset:52224
	ds_read_b128 v[206:209], v233 offset:53248
	ds_read_b128 v[210:213], v233 offset:54272
	ds_read_b128 v[214:217], v233 offset:55296
	ds_read_b128 v[218:221], v233 offset:56320
	global_load_lds_dwordx4 v180, s[98:99]
	s_add_i32 m0, s14, 0x2000
	s_add_u32 s14, s56, 0x40080
	s_addc_u32 s15, s57, 0
	s_add_i32 s33, s40, s66
	global_load_lds_dwordx4 v184, s[98:99]
	s_mov_b32 m0, s33
	s_nop 0
	global_load_lds_dwordx4 v180, s[14:15]
	s_add_i32 m0, s33, 0x2000
	s_nop 0
	global_load_lds_dwordx4 v184, s[14:15]
	s_mov_b32 m0, s76
	s_nop 0
	global_load_lds_dwordx4 v178, s[100:101]
	s_mov_b32 m0, s77
	s_nop 0
	global_load_lds_dwordx4 v182, s[100:101]
	s_waitcnt vmcnt(8) lgkmcnt(0)
	s_barrier
	v_mfma_f32_16x16x32_bf16 v[90:93], v[62:65], v[174:177], v[90:93]
	v_mfma_f32_16x16x32_bf16 v[86:89], v[78:81], v[174:177], v[86:89]
	v_mfma_f32_16x16x32_bf16 v[74:77], v[62:65], v[198:201], v[74:77]
	v_mfma_f32_16x16x32_bf16 v[70:73], v[78:81], v[198:201], v[70:73]
	v_mfma_f32_16x16x32_bf16 v[50:53], v[62:65], v[206:209], v[50:53]
	v_mfma_f32_16x16x32_bf16 v[46:49], v[78:81], v[206:209], v[46:49]
	v_mfma_f32_16x16x32_bf16 v[26:29], v[62:65], v[214:217], v[26:29]
	v_mfma_f32_16x16x32_bf16 v[22:25], v[78:81], v[214:217], v[22:25]
	v_mfma_f32_16x16x32_bf16 v[90:93], v[66:69], v[194:197], v[90:93]
	v_mfma_f32_16x16x32_bf16 v[86:89], v[82:85], v[194:197], v[86:89]
	v_mfma_f32_16x16x32_bf16 v[74:77], v[66:69], v[202:205], v[74:77]
	v_mfma_f32_16x16x32_bf16 v[70:73], v[82:85], v[202:205], v[70:73]
	v_mfma_f32_16x16x32_bf16 v[50:53], v[66:69], v[210:213], v[50:53]
	v_mfma_f32_16x16x32_bf16 v[46:49], v[82:85], v[210:213], v[46:49]
	v_mfma_f32_16x16x32_bf16 v[26:29], v[66:69], v[218:221], v[26:29]
	v_mfma_f32_16x16x32_bf16 v[22:25], v[82:85], v[218:221], v[22:25]
	v_mfma_f32_16x16x32_bf16 v[38:41], v[126:129], v[174:177], v[38:41]
	v_mfma_f32_16x16x32_bf16 v[82:85], v[146:149], v[194:197], v[38:41]
	v_mfma_f32_16x16x32_bf16 v[38:41], v[166:169], v[174:177], v[42:45]
	v_mfma_f32_16x16x32_bf16 v[78:81], v[170:173], v[194:197], v[38:41]
	v_mfma_f32_16x16x32_bf16 v[38:41], v[126:129], v[198:201], v[54:57]
	v_mfma_f32_16x16x32_bf16 v[66:69], v[146:149], v[202:205], v[38:41]
	v_mfma_f32_16x16x32_bf16 v[38:41], v[166:169], v[198:201], v[58:61]
	v_mfma_f32_16x16x32_bf16 v[34:37], v[126:129], v[206:209], v[34:37]
	v_mfma_f32_16x16x32_bf16 v[30:33], v[166:169], v[206:209], v[30:33]
	v_mfma_f32_16x16x32_bf16 v[16:19], v[126:129], v[214:217], v[18:21]
	v_mfma_f32_16x16x32_bf16 v[12:15], v[166:169], v[214:217], v[12:15]
	v_mfma_f32_16x16x32_bf16 v[62:65], v[170:173], v[202:205], v[38:41]
	v_mfma_f32_16x16x32_bf16 v[34:37], v[146:149], v[210:213], v[34:37]
	v_mfma_f32_16x16x32_bf16 v[30:33], v[170:173], v[210:213], v[30:33]
	v_mfma_f32_16x16x32_bf16 v[18:21], v[146:149], v[218:221], v[16:19]
	v_mfma_f32_16x16x32_bf16 v[14:17], v[170:173], v[218:221], v[12:15]
	s_barrier
	s_add_i32 s13, s13, 2
	s_add_u32 s10, s10, 0x100
	s_addc_u32 s11, s11, 0
	s_add_u32 s9, s9, 0x100
	s_addc_u32 s12, s12, 0
	s_cmp_gt_u32 s13, 13
	s_cbranch_scc0 .LBB0_774
	s_and_b64 vcc, exec, s[22:23]
	s_cbranch_vccz .LBB0_777
	s_barrier

.LBB0_1037:
	s_ashr_i32 s31, s30, 31
	s_lshl_b64 s[8:9], s[30:31], 17
	s_add_u32 s48, s62, s8
	s_addc_u32 s49, s63, s9
	s_and_b64 s[6:7], s[6:7], exec
	s_cselect_b32 s1, s49, s53
	s_cselect_b32 s2, s48, s52
	s_cmp_lt_i32 s50, 3
	s_cselect_b64 s[8:9], -1, 0
	s_and_b64 s[6:7], s[8:9], exec
	s_cselect_b32 s12, 4, 2
	s_add_i32 s13, s12, -2
	s_add_u32 s6, s54, 0x30080
	s_addc_u32 s7, s55, 0
	s_add_u32 s14, s52, 0x100
	s_addc_u32 s15, s53, 0
	s_mov_b32 s31, 0
	ds_read_b128 v[26:29], v214
	ds_read_b128 v[30:33], v214 offset:1024
	ds_read_b128 v[34:37], v214 offset:2048
	ds_read_b128 v[38:41], v214 offset:3072
	ds_read_b128 v[122:125], v215
	ds_read_b128 v[142:145], v215 offset:1024
	ds_read_b128 v[162:165], v215 offset:2048
	ds_read_b128 v[166:169], v215 offset:3072
	s_add_i32 s33, s31, 2
	s_add_u32 s40, s6, 0xfffd0080
	s_addc_u32 s41, s7, -1
	s_cmp_eq_u32 s13, s31
	s_cselect_b32 s55, s47, s41
	s_cselect_b32 s54, s46, s40
	s_cselect_b32 s53, s1, s15
	s_cselect_b32 s52, s2, s14
	s_add_i32 m0, s66, 0xc000
	ds_read_b128 v[170:173], v216
	ds_read_b128 v[174:177], v216 offset:1024
	ds_read_b128 v[178:181], v216 offset:2048
	ds_read_b128 v[198:201], v216 offset:3072
	ds_read_b128 v[202:205], v216 offset:4096
	ds_read_b128 v[206:209], v216 offset:5120
	ds_read_b128 v[220:223], v216 offset:6144
	ds_read_b128 v[228:231], v216 offset:7168
	global_load_lds_dwordx4 v190, s[6:7]
	s_add_i32 m0, s66, 0xe000
	s_nop 0
	global_load_lds_dwordx4 v192, s[6:7]
	s_waitcnt vmcnt(8) lgkmcnt(0)
	s_barrier
	v_mfma_f32_16x16x32_bf16 v[158:161], v[26:29], v[170:173], 0
	v_mfma_f32_16x16x32_bf16 v[154:157], v[34:37], v[170:173], 0
	v_mfma_f32_16x16x32_bf16 v[138:141], v[26:29], v[178:181], 0
	v_mfma_f32_16x16x32_bf16 v[134:137], v[34:37], v[178:181], 0
	v_mfma_f32_16x16x32_bf16 v[118:121], v[26:29], v[202:205], 0
	v_mfma_f32_16x16x32_bf16 v[114:117], v[34:37], v[202:205], 0
	v_mfma_f32_16x16x32_bf16 v[102:105], v[26:29], v[220:223], 0
	v_mfma_f32_16x16x32_bf16 v[98:101], v[34:37], v[220:223], 0
	v_mfma_f32_16x16x32_bf16 v[158:161], v[30:33], v[174:177], v[158:161]
	v_mfma_f32_16x16x32_bf16 v[154:157], v[38:41], v[174:177], v[154:157]
	v_mfma_f32_16x16x32_bf16 v[138:141], v[30:33], v[198:201], v[138:141]
	v_mfma_f32_16x16x32_bf16 v[134:137], v[38:41], v[198:201], v[134:137]
	v_mfma_f32_16x16x32_bf16 v[118:121], v[30:33], v[206:209], v[118:121]
	v_mfma_f32_16x16x32_bf16 v[114:117], v[38:41], v[206:209], v[114:117]
	v_mfma_f32_16x16x32_bf16 v[102:105], v[30:33], v[228:231], v[102:105]
	v_mfma_f32_16x16x32_bf16 v[98:101], v[38:41], v[228:231], v[98:101]
	v_mfma_f32_16x16x32_bf16 v[150:153], v[122:125], v[170:173], 0
	v_mfma_f32_16x16x32_bf16 v[146:149], v[162:165], v[170:173], 0
	v_mfma_f32_16x16x32_bf16 v[130:133], v[122:125], v[178:181], 0
	v_mfma_f32_16x16x32_bf16 v[126:129], v[162:165], v[178:181], 0
	v_mfma_f32_16x16x32_bf16 v[110:113], v[122:125], v[202:205], 0
	v_mfma_f32_16x16x32_bf16 v[106:109], v[162:165], v[202:205], 0
	v_mfma_f32_16x16x32_bf16 v[94:97], v[122:125], v[220:223], 0
	v_mfma_f32_16x16x32_bf16 v[90:93], v[162:165], v[220:223], 0
	v_mfma_f32_16x16x32_bf16 v[150:153], v[142:145], v[174:177], v[150:153]
	v_mfma_f32_16x16x32_bf16 v[146:149], v[166:169], v[174:177], v[146:149]
	v_mfma_f32_16x16x32_bf16 v[130:133], v[142:145], v[198:201], v[130:133]
	v_mfma_f32_16x16x32_bf16 v[126:129], v[166:169], v[198:201], v[126:129]
	v_mfma_f32_16x16x32_bf16 v[110:113], v[142:145], v[206:209], v[110:113]
	v_mfma_f32_16x16x32_bf16 v[106:109], v[166:169], v[206:209], v[106:109]
	v_mfma_f32_16x16x32_bf16 v[94:97], v[142:145], v[228:231], v[94:97]
	v_mfma_f32_16x16x32_bf16 v[90:93], v[166:169], v[228:231], v[90:93]
	s_barrier
	s_add_i32 s31, s85, s64
	s_add_u32 s98, s52, s18
	s_addc_u32 s99, s53, s19
	s_mov_b32 m0, s31
	ds_read_b128 v[170:173], v216 offset:16384
	ds_read_b128 v[174:177], v216 offset:17408
	ds_read_b128 v[178:181], v216 offset:18432
	ds_read_b128 v[198:201], v216 offset:19456
	ds_read_b128 v[202:205], v216 offset:20480
	ds_read_b128 v[206:209], v216 offset:21504
	ds_read_b128 v[220:223], v216 offset:22528
	ds_read_b128 v[228:231], v216 offset:23552
	global_load_lds_dwordx4 v184, s[52:53]
	s_add_i32 m0, s31, 0x2000
	s_add_u32 s40, s52, 0x10000
	s_addc_u32 s41, s53, 0
	s_add_i32 s31, s86, s64
	global_load_lds_dwordx4 v188, s[52:53]
	s_mov_b32 m0, s31
	s_add_u32 s100, s54, s18
	s_addc_u32 s101, s55, s19
	global_load_lds_dwordx4 v184, s[40:41]
	s_add_i32 m0, s31, 0x2000
	s_nop 0
	global_load_lds_dwordx4 v188, s[40:41]
	s_mov_b32 m0, s66
	s_nop 0
	global_load_lds_dwordx4 v182, s[54:55]
	s_mov_b32 m0, s67
	s_nop 0
	global_load_lds_dwordx4 v186, s[54:55]
	s_waitcnt vmcnt(8) lgkmcnt(0)
	s_barrier
	v_mfma_f32_16x16x32_bf16 v[86:89], v[26:29], v[170:173], 0
	v_mfma_f32_16x16x32_bf16 v[82:85], v[34:37], v[170:173], 0
	v_mfma_f32_16x16x32_bf16 v[70:73], v[26:29], v[178:181], 0
	v_mfma_f32_16x16x32_bf16 v[66:69], v[34:37], v[178:181], 0
	v_mfma_f32_16x16x32_bf16 v[54:57], v[26:29], v[202:205], 0
	v_mfma_f32_16x16x32_bf16 v[50:53], v[34:37], v[202:205], 0
	v_mfma_f32_16x16x32_bf16 v[22:25], v[26:29], v[220:223], 0
	v_mfma_f32_16x16x32_bf16 v[18:21], v[34:37], v[220:223], 0
	v_mfma_f32_16x16x32_bf16 v[86:89], v[30:33], v[174:177], v[86:89]
	v_mfma_f32_16x16x32_bf16 v[82:85], v[38:41], v[174:177], v[82:85]
	v_mfma_f32_16x16x32_bf16 v[70:73], v[30:33], v[198:201], v[70:73]
	v_mfma_f32_16x16x32_bf16 v[66:69], v[38:41], v[198:201], v[66:69]
	v_mfma_f32_16x16x32_bf16 v[54:57], v[30:33], v[206:209], v[54:57]
	v_mfma_f32_16x16x32_bf16 v[50:53], v[38:41], v[206:209], v[50:53]
	v_mfma_f32_16x16x32_bf16 v[22:25], v[30:33], v[228:231], v[22:25]
	v_mfma_f32_16x16x32_bf16 v[18:21], v[38:41], v[228:231], v[18:21]
	v_mfma_f32_16x16x32_bf16 v[46:49], v[122:125], v[202:205], 0
	v_mfma_f32_16x16x32_bf16 v[42:45], v[162:165], v[202:205], 0
	v_mfma_f32_16x16x32_bf16 v[14:17], v[122:125], v[220:223], 0
	v_mfma_f32_16x16x32_bf16 v[8:11], v[162:165], v[220:223], 0
	v_mfma_f32_16x16x32_bf16 v[26:29], v[122:125], v[170:173], 0
	v_mfma_f32_16x16x32_bf16 v[30:33], v[162:165], v[170:173], 0
	v_mfma_f32_16x16x32_bf16 v[34:37], v[122:125], v[178:181], 0
	v_mfma_f32_16x16x32_bf16 v[38:41], v[162:165], v[178:181], 0
	v_mfma_f32_16x16x32_bf16 v[46:49], v[142:145], v[206:209], v[46:49]
	v_mfma_f32_16x16x32_bf16 v[42:45], v[166:169], v[206:209], v[42:45]
	v_mfma_f32_16x16x32_bf16 v[14:17], v[142:145], v[228:231], v[14:17]
	v_mfma_f32_16x16x32_bf16 v[8:11], v[166:169], v[228:231], v[8:11]
	v_mfma_f32_16x16x32_bf16 v[26:29], v[142:145], v[174:177], v[26:29]
	v_mfma_f32_16x16x32_bf16 v[30:33], v[166:169], v[174:177], v[30:33]
	v_mfma_f32_16x16x32_bf16 v[34:37], v[142:145], v[198:201], v[34:37]
	v_mfma_f32_16x16x32_bf16 v[38:41], v[166:169], v[198:201], v[38:41]
	s_barrier
	s_branch .Lpeel4_p3

.Lpeel4_p3:
	s_add_i32 s31, 0, 0x18000
	v_add_u32_e32 v3, s31, v213
	s_add_i32 s42, 0, 0x1c000
	ds_read_b128 v[58:61], v3
	ds_read_b128 v[62:65], v3 offset:1024
	ds_read_b128 v[74:77], v3 offset:2048
	ds_read_b128 v[78:81], v3 offset:3072
	v_add_u32_e32 v3, s42, v213
	ds_read_b128 v[122:125], v3
	ds_read_b128 v[142:145], v3 offset:1024
	ds_read_b128 v[162:165], v3 offset:2048
	ds_read_b128 v[166:169], v3 offset:3072
	s_add_u32 s40, s54, 0x30000
	s_addc_u32 s41, s55, 0
	s_mov_b32 m0, s68
	ds_read_b128 v[170:173], v216 offset:32768
	ds_read_b128 v[174:177], v216 offset:33792
	ds_read_b128 v[178:181], v216 offset:34816
	ds_read_b128 v[198:201], v216 offset:35840
	ds_read_b128 v[202:205], v216 offset:36864
	ds_read_b128 v[206:209], v216 offset:37888
	ds_read_b128 v[220:223], v216 offset:38912
	ds_read_b128 v[228:231], v216 offset:39936
	global_load_lds_dwordx4 v182, s[40:41]
	s_mov_b32 m0, s69
	s_nop 0
	global_load_lds_dwordx4 v186, s[40:41]
	s_waitcnt vmcnt(8) lgkmcnt(0)
	s_barrier
	v_mfma_f32_16x16x32_bf16 v[158:161], v[58:61], v[170:173], v[158:161]
	v_mfma_f32_16x16x32_bf16 v[154:157], v[74:77], v[170:173], v[154:157]
	v_mfma_f32_16x16x32_bf16 v[138:141], v[58:61], v[178:181], v[138:141]
	v_mfma_f32_16x16x32_bf16 v[134:137], v[74:77], v[178:181], v[134:137]
	v_mfma_f32_16x16x32_bf16 v[118:121], v[58:61], v[202:205], v[118:121]
	v_mfma_f32_16x16x32_bf16 v[114:117], v[74:77], v[202:205], v[114:117]
	v_mfma_f32_16x16x32_bf16 v[102:105], v[58:61], v[220:223], v[102:105]
	v_mfma_f32_16x16x32_bf16 v[98:101], v[74:77], v[220:223], v[98:101]
	v_mfma_f32_16x16x32_bf16 v[158:161], v[62:65], v[174:177], v[158:161]
	v_mfma_f32_16x16x32_bf16 v[154:157], v[78:81], v[174:177], v[154:157]
	v_mfma_f32_16x16x32_bf16 v[138:141], v[62:65], v[198:201], v[138:141]
	v_mfma_f32_16x16x32_bf16 v[134:137], v[78:81], v[198:201], v[134:137]
	v_mfma_f32_16x16x32_bf16 v[118:121], v[62:65], v[206:209], v[118:121]
	v_mfma_f32_16x16x32_bf16 v[114:117], v[78:81], v[206:209], v[114:117]
	v_mfma_f32_16x16x32_bf16 v[102:105], v[62:65], v[228:231], v[102:105]
	v_mfma_f32_16x16x32_bf16 v[98:101], v[78:81], v[228:231], v[98:101]
	v_mfma_f32_16x16x32_bf16 v[150:153], v[122:125], v[170:173], v[150:153]
	v_mfma_f32_16x16x32_bf16 v[146:149], v[162:165], v[170:173], v[146:149]
	v_mfma_f32_16x16x32_bf16 v[130:133], v[122:125], v[178:181], v[130:133]
	v_mfma_f32_16x16x32_bf16 v[126:129], v[162:165], v[178:181], v[126:129]
	v_mfma_f32_16x16x32_bf16 v[110:113], v[122:125], v[202:205], v[110:113]
	v_mfma_f32_16x16x32_bf16 v[106:109], v[162:165], v[202:205], v[106:109]
	v_mfma_f32_16x16x32_bf16 v[94:97], v[122:125], v[220:223], v[94:97]
	v_mfma_f32_16x16x32_bf16 v[90:93], v[162:165], v[220:223], v[90:93]
	v_mfma_f32_16x16x32_bf16 v[150:153], v[142:145], v[174:177], v[150:153]
	v_mfma_f32_16x16x32_bf16 v[146:149], v[166:169], v[174:177], v[146:149]
	v_mfma_f32_16x16x32_bf16 v[130:133], v[142:145], v[198:201], v[130:133]
	v_mfma_f32_16x16x32_bf16 v[126:129], v[166:169], v[198:201], v[126:129]
	v_mfma_f32_16x16x32_bf16 v[110:113], v[142:145], v[206:209], v[110:113]
	v_mfma_f32_16x16x32_bf16 v[106:109], v[166:169], v[206:209], v[106:109]
	v_mfma_f32_16x16x32_bf16 v[94:97], v[142:145], v[228:231], v[94:97]
	v_mfma_f32_16x16x32_bf16 v[90:93], v[166:169], v[228:231], v[90:93]
	s_barrier
	s_add_i32 s31, s31, s64
	s_mov_b32 m0, s31
	ds_read_b128 v[170:173], v216 offset:49152
	ds_read_b128 v[174:177], v216 offset:50176
	ds_read_b128 v[178:181], v216 offset:51200
	ds_read_b128 v[198:201], v216 offset:52224
	ds_read_b128 v[202:205], v216 offset:53248
	ds_read_b128 v[206:209], v216 offset:54272
	ds_read_b128 v[220:223], v216 offset:55296
	ds_read_b128 v[228:231], v216 offset:56320
	global_load_lds_dwordx4 v184, s[98:99]
	s_add_i32 m0, s31, 0x2000
	s_add_u32 s40, s52, 0x10080
	s_addc_u32 s41, s53, 0
	s_add_i32 s31, s42, s64
	global_load_lds_dwordx4 v188, s[98:99]
	s_mov_b32 m0, s31
	s_nop 0
	global_load_lds_dwordx4 v184, s[40:41]
	s_add_i32 m0, s31, 0x2000
	s_nop 0
	global_load_lds_dwordx4 v188, s[40:41]
	s_mov_b32 m0, s76
	s_nop 0
	global_load_lds_dwordx4 v182, s[100:101]
	s_mov_b32 m0, s77
	s_nop 0
	global_load_lds_dwordx4 v186, s[100:101]
	s_waitcnt vmcnt(8) lgkmcnt(0)
	s_barrier
	v_mfma_f32_16x16x32_bf16 v[86:89], v[58:61], v[170:173], v[86:89]
	v_mfma_f32_16x16x32_bf16 v[82:85], v[74:77], v[170:173], v[82:85]
	v_mfma_f32_16x16x32_bf16 v[70:73], v[58:61], v[178:181], v[70:73]
	v_mfma_f32_16x16x32_bf16 v[66:69], v[74:77], v[178:181], v[66:69]
	v_mfma_f32_16x16x32_bf16 v[54:57], v[58:61], v[202:205], v[54:57]
	v_mfma_f32_16x16x32_bf16 v[50:53], v[74:77], v[202:205], v[50:53]
	v_mfma_f32_16x16x32_bf16 v[22:25], v[58:61], v[220:223], v[22:25]
	v_mfma_f32_16x16x32_bf16 v[18:21], v[74:77], v[220:223], v[18:21]
	v_mfma_f32_16x16x32_bf16 v[86:89], v[62:65], v[174:177], v[86:89]
	v_mfma_f32_16x16x32_bf16 v[82:85], v[78:81], v[174:177], v[82:85]
	v_mfma_f32_16x16x32_bf16 v[70:73], v[62:65], v[198:201], v[70:73]
	v_mfma_f32_16x16x32_bf16 v[66:69], v[78:81], v[198:201], v[66:69]
	v_mfma_f32_16x16x32_bf16 v[54:57], v[62:65], v[206:209], v[54:57]
	v_mfma_f32_16x16x32_bf16 v[50:53], v[78:81], v[206:209], v[50:53]
	v_mfma_f32_16x16x32_bf16 v[22:25], v[62:65], v[228:231], v[22:25]
	v_mfma_f32_16x16x32_bf16 v[18:21], v[78:81], v[228:231], v[18:21]
	v_mfma_f32_16x16x32_bf16 v[26:29], v[122:125], v[170:173], v[26:29]
	v_mfma_f32_16x16x32_bf16 v[78:81], v[142:145], v[174:177], v[26:29]
	v_mfma_f32_16x16x32_bf16 v[26:29], v[162:165], v[170:173], v[30:33]
	v_mfma_f32_16x16x32_bf16 v[74:77], v[166:169], v[174:177], v[26:29]
	v_mfma_f32_16x16x32_bf16 v[26:29], v[122:125], v[178:181], v[34:37]
	v_mfma_f32_16x16x32_bf16 v[62:65], v[142:145], v[198:201], v[26:29]
	v_mfma_f32_16x16x32_bf16 v[26:29], v[162:165], v[178:181], v[38:41]
	v_mfma_f32_16x16x32_bf16 v[58:61], v[166:169], v[198:201], v[26:29]
	v_mfma_f32_16x16x32_bf16 v[26:29], v[122:125], v[202:205], v[46:49]
	v_mfma_f32_16x16x32_bf16 v[46:49], v[142:145], v[206:209], v[26:29]
	v_mfma_f32_16x16x32_bf16 v[26:29], v[162:165], v[202:205], v[42:45]
	v_mfma_f32_16x16x32_bf16 v[12:15], v[122:125], v[220:223], v[14:17]
	v_mfma_f32_16x16x32_bf16 v[8:11], v[162:165], v[220:223], v[8:11]
	v_mfma_f32_16x16x32_bf16 v[42:45], v[166:169], v[206:209], v[26:29]
	v_mfma_f32_16x16x32_bf16 v[14:17], v[142:145], v[228:231], v[12:15]
	v_mfma_f32_16x16x32_bf16 v[10:13], v[166:169], v[228:231], v[8:11]
	s_barrier
	s_add_u32 s6, s6, 0x100
	s_addc_u32 s7, s7, 0
	s_add_u32 s14, s14, 0x100
	s_addc_u32 s15, s15, 0
	s_cmp_ge_u32 s33, s12
	s_mov_b32 s31, s33
	s_cbranch_scc0 .LBB0_1038
	s_and_b64 vcc, exec, s[20:21]
	s_cbranch_vccz .LBB0_1041
	s_barrier

.LBB0_1623:
	v_and_b32_e32 v14, 15, v0
	v_and_b32_e32 v15, 48, v0
	v_lshlrev_b32_e32 v16, 2, v0
	v_lshl_or_b32 v1, s2, 6, v14
	v_lshl_or_b32 v14, v14, 6, v15
	s_lshl_b32 s2, s2, 13
	v_and_b32_e32 v16, 32, v16
	s_mov_b64 s[20:21], 0x80
	s_and_b32 s17, s5, 3
	v_bitop3_b32 v14, v14, s2, v16 bitop3:0xde
	v_lshlrev_b32_e32 v17, 6, v0
	s_movk_i32 s2, 0x3c0
	s_add_i32 m0, s33, 0x18000
	v_lshl_add_u64 v[8:9], v[8:9], 0, s[20:21]
	v_and_or_b32 v15, v17, s2, v15
	s_lshl_b32 s2, s17, 12
	s_waitcnt vmcnt(2)
	s_barrier
	global_load_lds_dwordx4 v[8:9], off
	v_lshl_add_u64 v[6:7], v[6:7], 0, s[20:21]
	s_add_i32 m0, s33, 0x1a000
	s_add_i32 s42, s33, 0x8000
	s_add_i32 s43, s33, 0xa000
	global_load_lds_dwordx4 v[6:7], off
	v_lshl_add_u64 v[4:5], v[4:5], 0, s[20:21]
	s_mov_b32 m0, s42
	s_add_u32 s6, s30, 0x40080
	global_load_lds_dwordx4 v[4:5], off
	v_lshl_add_u64 v[2:3], v[2:3], 0, s[20:21]
	s_mov_b32 m0, s43
	s_addc_u32 s7, s31, 0
	global_load_lds_dwordx4 v[2:3], off
	s_add_i32 m0, s33, 0x1c000
	v_lshl_add_u64 v[2:3], s[6:7], 0, v[132:133]
	global_load_lds_dwordx4 v[2:3], off
	v_lshl_add_u64 v[2:3], s[6:7], 0, v[136:137]
	s_add_i32 m0, s33, 0x1e000
	v_lshlrev_b32_e32 v4, 11, v12
	global_load_lds_dwordx4 v[2:3], off
	v_lshlrev_b32_e32 v2, 8, v0
	v_and_b32_e32 v2, 0x18000, v2
	v_or3_b32 v2, v10, v2, v4
	s_sext_i32_i8 s10, s4
	s_mov_b64 s[4:5], 0x40080
	v_add_u32_e32 v2, v2, v11
	v_mov_b32_e32 v3, v133
	v_lshl_add_u64 v[138:139], v[2:3], 0, s[4:5]
	v_lshlrev_b32_e32 v2, 4, v13
	v_and_b32_e32 v2, 0x38000, v2
	s_waitcnt vmcnt(6)
	v_or3_b32 v2, v10, v2, v4
	v_add_u32_e32 v2, v2, v11
	v_bitop3_b32 v151, s2, v15, v16 bitop3:0xf6
	v_lshl_add_u64 v[140:141], v[2:3], 0, s[4:5]
	v_mov_b64_e32 v[142:143], 0x100
	v_mov_b64_e32 v[144:145], 0xff
	s_add_i32 s44, 0, 0x10000
	s_add_i32 s45, 0, 0x14000
	v_add_u32_e32 v152, 0, v14
	v_mov_b32_e32 v2, v133
	v_mov_b32_e32 v4, v133
	v_mov_b32_e32 v10, v133
	v_mov_b32_e32 v11, v133
	v_mov_b32_e32 v13, v133
	v_mov_b32_e32 v14, v133
	v_mov_b32_e32 v15, v133
	v_mov_b32_e32 v16, v133
	s_barrier

.LBB0_1630:
	s_add_u32 s50, s30, 0x100
	s_addc_u32 s51, s31, 0
	s_ashr_i32 s25, s24, 31
	s_lshl_b64 s[26:27], s[24:25], 19
	s_add_u32 s28, s91, s26
	s_addc_u32 s29, s95, s27
	s_and_b64 s[26:27], s[6:7], exec
	s_cselect_b32 s25, s29, s19
	s_cselect_b32 s52, s28, s18
	s_ashr_i32 s23, s22, 31
	s_lshl_b64 s[26:27], s[22:23], 19
	s_add_u32 s26, s1, s26
	s_addc_u32 s27, s12, s27
	s_and_b64 s[46:47], s[6:7], exec
	s_cselect_b32 s23, s27, s31
	s_cselect_b32 s53, s26, s30
	v_lshl_add_u64 v[146:147], s[18:19], 0, v[138:139]
	v_lshl_add_u64 v[148:149], s[18:19], 0, v[140:141]
	s_mov_b32 s54, -2
	s_mov_b64 s[30:31], 0
	v_add_u32_e32 v153, s44, v151
	ds_read_b128 v[154:157], v153
	ds_read_b128 v[158:161], v153 offset:1024
	ds_read_b128 v[162:165], v153 offset:2048
	ds_read_b128 v[166:169], v153 offset:3072
	v_add_u32_e32 v153, s45, v151
	s_add_u32 s46, s18, s30
	ds_read_b128 v[170:173], v153
	ds_read_b128 v[174:177], v153 offset:1024
	ds_read_b128 v[178:181], v153 offset:2048
	ds_read_b128 v[182:185], v153 offset:3072
	s_addc_u32 s47, s19, s31
	s_add_u32 s46, s46, 0x100
	s_addc_u32 s47, s47, 0
	s_add_u32 s55, s50, s30
	s_addc_u32 s56, s51, s31
	s_cmpk_eq_i32 s30, 0x700
	s_cselect_b32 s49, s25, s47
	s_cselect_b32 s48, s52, s46
	s_cselect_b32 s47, s23, s56
	s_cselect_b32 s46, s53, s55
	v_lshl_add_u64 v[218:219], v[146:147], 0, s[30:31]
	s_add_i32 m0, s33, 0xc000
	ds_read_b128 v[186:189], v152
	ds_read_b128 v[190:193], v152 offset:1024
	ds_read_b128 v[194:197], v152 offset:2048
	ds_read_b128 v[198:201], v152 offset:3072
	ds_read_b128 v[202:205], v152 offset:4096
	ds_read_b128 v[206:209], v152 offset:5120
	ds_read_b128 v[210:213], v152 offset:6144
	ds_read_b128 v[214:217], v152 offset:7168
	global_load_lds_dwordx4 v[218:219], off
	v_lshl_add_u64 v[218:219], v[148:149], 0, s[30:31]
	s_add_i32 m0, s33, 0xe000
	s_nop 0
	global_load_lds_dwordx4 v[218:219], off
	s_waitcnt vmcnt(8) lgkmcnt(0)
	s_barrier
	v_mfma_f32_16x16x32_bf16 v[126:129], v[154:157], v[186:189], 0
	v_mfma_f32_16x16x32_bf16 v[122:125], v[162:165], v[186:189], 0
	v_mfma_f32_16x16x32_bf16 v[110:113], v[154:157], v[194:197], 0
	v_mfma_f32_16x16x32_bf16 v[106:109], v[162:165], v[194:197], 0
	v_mfma_f32_16x16x32_bf16 v[94:97], v[154:157], v[202:205], 0
	v_mfma_f32_16x16x32_bf16 v[90:93], v[162:165], v[202:205], 0
	v_mfma_f32_16x16x32_bf16 v[78:81], v[154:157], v[210:213], 0
	v_mfma_f32_16x16x32_bf16 v[74:77], v[162:165], v[210:213], 0
	v_mfma_f32_16x16x32_bf16 v[126:129], v[158:161], v[190:193], v[126:129]
	v_mfma_f32_16x16x32_bf16 v[122:125], v[166:169], v[190:193], v[122:125]
	v_mfma_f32_16x16x32_bf16 v[110:113], v[158:161], v[198:201], v[110:113]
	v_mfma_f32_16x16x32_bf16 v[106:109], v[166:169], v[198:201], v[106:109]
	v_mfma_f32_16x16x32_bf16 v[94:97], v[158:161], v[206:209], v[94:97]
	v_mfma_f32_16x16x32_bf16 v[90:93], v[166:169], v[206:209], v[90:93]
	v_mfma_f32_16x16x32_bf16 v[78:81], v[158:161], v[214:217], v[78:81]
	v_mfma_f32_16x16x32_bf16 v[74:77], v[166:169], v[214:217], v[74:77]
	v_mfma_f32_16x16x32_bf16 v[118:121], v[170:173], v[186:189], 0
	v_mfma_f32_16x16x32_bf16 v[114:117], v[178:181], v[186:189], 0
	v_mfma_f32_16x16x32_bf16 v[102:105], v[170:173], v[194:197], 0
	v_mfma_f32_16x16x32_bf16 v[98:101], v[178:181], v[194:197], 0
	v_mfma_f32_16x16x32_bf16 v[86:89], v[170:173], v[202:205], 0
	v_mfma_f32_16x16x32_bf16 v[82:85], v[178:181], v[202:205], 0
	v_mfma_f32_16x16x32_bf16 v[70:73], v[170:173], v[210:213], 0
	v_mfma_f32_16x16x32_bf16 v[66:69], v[178:181], v[210:213], 0
	v_mfma_f32_16x16x32_bf16 v[118:121], v[174:177], v[190:193], v[118:121]
	v_mfma_f32_16x16x32_bf16 v[114:117], v[182:185], v[190:193], v[114:117]
	v_mfma_f32_16x16x32_bf16 v[102:105], v[174:177], v[198:201], v[102:105]
	v_mfma_f32_16x16x32_bf16 v[98:101], v[182:185], v[198:201], v[98:101]
	v_mfma_f32_16x16x32_bf16 v[86:89], v[174:177], v[206:209], v[86:89]
	v_mfma_f32_16x16x32_bf16 v[82:85], v[182:185], v[206:209], v[82:85]
	v_mfma_f32_16x16x32_bf16 v[70:73], v[174:177], v[214:217], v[70:73]
	v_mfma_f32_16x16x32_bf16 v[66:69], v[182:185], v[214:217], v[66:69]
	s_barrier
	s_add_i32 s55, s44, s13
	s_add_u32 s98, s46, s20
	s_addc_u32 s99, s47, s21
	s_mov_b32 m0, s55
	ds_read_b128 v[186:189], v152 offset:16384
	ds_read_b128 v[190:193], v152 offset:17408
	ds_read_b128 v[194:197], v152 offset:18432
	ds_read_b128 v[198:201], v152 offset:19456
	ds_read_b128 v[202:205], v152 offset:20480
	ds_read_b128 v[206:209], v152 offset:21504
	ds_read_b128 v[210:213], v152 offset:22528
	ds_read_b128 v[214:217], v152 offset:23552
	global_load_lds_dwordx4 v132, s[46:47]
	s_add_i32 m0, s55, 0x2000
	s_add_u32 s56, s46, 0x40000
	s_addc_u32 s57, s47, 0
	s_add_i32 s55, s45, s13
	global_load_lds_dwordx4 v136, s[46:47]
	s_mov_b32 m0, s55
	s_nop 0
	global_load_lds_dwordx4 v132, s[56:57]
	s_add_i32 m0, s55, 0x2000
	s_nop 0
	global_load_lds_dwordx4 v136, s[56:57]
	s_add_u32 s100, s48, s20
	s_addc_u32 s101, s49, s21
	s_mov_b32 m0, s33
	s_nop 0
	global_load_lds_dwordx4 v130, s[48:49]
	s_mov_b32 m0, s14
	s_nop 0
	global_load_lds_dwordx4 v134, s[48:49]
	s_waitcnt vmcnt(8) lgkmcnt(0)
	s_barrier
	v_mfma_f32_16x16x32_bf16 v[62:65], v[154:157], v[186:189], 0
	v_mfma_f32_16x16x32_bf16 v[58:61], v[162:165], v[186:189], 0
	v_mfma_f32_16x16x32_bf16 v[46:49], v[154:157], v[194:197], 0
	v_mfma_f32_16x16x32_bf16 v[42:45], v[162:165], v[194:197], 0
	v_mfma_f32_16x16x32_bf16 v[30:33], v[154:157], v[202:205], 0
	v_mfma_f32_16x16x32_bf16 v[26:29], v[162:165], v[202:205], 0
	v_mfma_f32_16x16x32_bf16 v[14:17], v[154:157], v[210:213], 0
	v_mfma_f32_16x16x32_bf16 v[10:13], v[162:165], v[210:213], 0
	v_mfma_f32_16x16x32_bf16 v[62:65], v[158:161], v[190:193], v[62:65]
	v_mfma_f32_16x16x32_bf16 v[58:61], v[166:169], v[190:193], v[58:61]
	v_mfma_f32_16x16x32_bf16 v[46:49], v[158:161], v[198:201], v[46:49]
	v_mfma_f32_16x16x32_bf16 v[42:45], v[166:169], v[198:201], v[42:45]
	v_mfma_f32_16x16x32_bf16 v[30:33], v[158:161], v[206:209], v[30:33]
	v_mfma_f32_16x16x32_bf16 v[26:29], v[166:169], v[206:209], v[26:29]
	v_mfma_f32_16x16x32_bf16 v[14:17], v[158:161], v[214:217], v[14:17]
	v_mfma_f32_16x16x32_bf16 v[10:13], v[166:169], v[214:217], v[10:13]
	v_mfma_f32_16x16x32_bf16 v[54:57], v[170:173], v[186:189], 0
	v_mfma_f32_16x16x32_bf16 v[50:53], v[178:181], v[186:189], 0
	v_mfma_f32_16x16x32_bf16 v[38:41], v[170:173], v[194:197], 0
	v_mfma_f32_16x16x32_bf16 v[34:37], v[178:181], v[194:197], 0
	v_mfma_f32_16x16x32_bf16 v[22:25], v[170:173], v[202:205], 0
	v_mfma_f32_16x16x32_bf16 v[18:21], v[178:181], v[202:205], 0
	v_mfma_f32_16x16x32_bf16 v[6:9], v[170:173], v[210:213], 0
	v_mfma_f32_16x16x32_bf16 v[2:5], v[178:181], v[210:213], 0
	v_mfma_f32_16x16x32_bf16 v[54:57], v[174:177], v[190:193], v[54:57]
	v_mfma_f32_16x16x32_bf16 v[50:53], v[182:185], v[190:193], v[50:53]
	v_mfma_f32_16x16x32_bf16 v[38:41], v[174:177], v[198:201], v[38:41]
	v_mfma_f32_16x16x32_bf16 v[34:37], v[182:185], v[198:201], v[34:37]
	v_mfma_f32_16x16x32_bf16 v[22:25], v[174:177], v[206:209], v[22:25]
	v_mfma_f32_16x16x32_bf16 v[18:21], v[182:185], v[206:209], v[18:21]
	v_mfma_f32_16x16x32_bf16 v[6:9], v[174:177], v[214:217], v[6:9]
	v_mfma_f32_16x16x32_bf16 v[2:5], v[182:185], v[214:217], v[2:5]
	s_barrier
	s_branch .Lpeel7_p3

.Lpeel7_p3:
	s_add_i32 s55, 0, 0x18000
	v_add_u32_e32 v153, s55, v151
	s_add_i32 s56, 0, 0x1c000
	ds_read_b128 v[154:157], v153
	ds_read_b128 v[158:161], v153 offset:1024
	ds_read_b128 v[162:165], v153 offset:2048
	ds_read_b128 v[166:169], v153 offset:3072
	v_add_u32_e32 v153, s56, v151
	ds_read_b128 v[170:173], v153
	ds_read_b128 v[174:177], v153 offset:1024
	ds_read_b128 v[178:181], v153 offset:2048
	ds_read_b128 v[182:185], v153 offset:3072
	s_add_u32 s48, s48, 0x40000
	s_addc_u32 s49, s49, 0
	s_mov_b32 m0, s15
	ds_read_b128 v[186:189], v152 offset:32768
	ds_read_b128 v[190:193], v152 offset:33792
	ds_read_b128 v[194:197], v152 offset:34816
	ds_read_b128 v[198:201], v152 offset:35840
	ds_read_b128 v[202:205], v152 offset:36864
	ds_read_b128 v[206:209], v152 offset:37888
	ds_read_b128 v[210:213], v152 offset:38912
	ds_read_b128 v[214:217], v152 offset:39936
	global_load_lds_dwordx4 v130, s[48:49]
	s_mov_b32 m0, s40
	s_nop 0
	global_load_lds_dwordx4 v134, s[48:49]
	s_waitcnt vmcnt(8) lgkmcnt(0)
	s_barrier
	v_mfma_f32_16x16x32_bf16 v[126:129], v[154:157], v[186:189], v[126:129]
	v_mfma_f32_16x16x32_bf16 v[122:125], v[162:165], v[186:189], v[122:125]
	v_mfma_f32_16x16x32_bf16 v[110:113], v[154:157], v[194:197], v[110:113]
	v_mfma_f32_16x16x32_bf16 v[106:109], v[162:165], v[194:197], v[106:109]
	v_mfma_f32_16x16x32_bf16 v[94:97], v[154:157], v[202:205], v[94:97]
	v_mfma_f32_16x16x32_bf16 v[90:93], v[162:165], v[202:205], v[90:93]
	v_mfma_f32_16x16x32_bf16 v[78:81], v[154:157], v[210:213], v[78:81]
	v_mfma_f32_16x16x32_bf16 v[74:77], v[162:165], v[210:213], v[74:77]
	v_mfma_f32_16x16x32_bf16 v[126:129], v[158:161], v[190:193], v[126:129]
	v_mfma_f32_16x16x32_bf16 v[122:125], v[166:169], v[190:193], v[122:125]
	v_mfma_f32_16x16x32_bf16 v[110:113], v[158:161], v[198:201], v[110:113]
	v_mfma_f32_16x16x32_bf16 v[106:109], v[166:169], v[198:201], v[106:109]
	v_mfma_f32_16x16x32_bf16 v[94:97], v[158:161], v[206:209], v[94:97]
	v_mfma_f32_16x16x32_bf16 v[90:93], v[166:169], v[206:209], v[90:93]
	v_mfma_f32_16x16x32_bf16 v[78:81], v[158:161], v[214:217], v[78:81]
	v_mfma_f32_16x16x32_bf16 v[74:77], v[166:169], v[214:217], v[74:77]
	v_mfma_f32_16x16x32_bf16 v[118:121], v[170:173], v[186:189], v[118:121]
	v_mfma_f32_16x16x32_bf16 v[114:117], v[178:181], v[186:189], v[114:117]
	v_mfma_f32_16x16x32_bf16 v[102:105], v[170:173], v[194:197], v[102:105]
	v_mfma_f32_16x16x32_bf16 v[98:101], v[178:181], v[194:197], v[98:101]
	v_mfma_f32_16x16x32_bf16 v[86:89], v[170:173], v[202:205], v[86:89]
	v_mfma_f32_16x16x32_bf16 v[82:85], v[178:181], v[202:205], v[82:85]
	v_mfma_f32_16x16x32_bf16 v[70:73], v[170:173], v[210:213], v[70:73]
	v_mfma_f32_16x16x32_bf16 v[66:69], v[178:181], v[210:213], v[66:69]
	v_mfma_f32_16x16x32_bf16 v[118:121], v[174:177], v[190:193], v[118:121]
	v_mfma_f32_16x16x32_bf16 v[114:117], v[182:185], v[190:193], v[114:117]
	v_mfma_f32_16x16x32_bf16 v[102:105], v[174:177], v[198:201], v[102:105]
	v_mfma_f32_16x16x32_bf16 v[98:101], v[182:185], v[198:201], v[98:101]
	v_mfma_f32_16x16x32_bf16 v[86:89], v[174:177], v[206:209], v[86:89]
	v_mfma_f32_16x16x32_bf16 v[82:85], v[182:185], v[206:209], v[82:85]
	v_mfma_f32_16x16x32_bf16 v[70:73], v[174:177], v[214:217], v[70:73]
	v_mfma_f32_16x16x32_bf16 v[66:69], v[182:185], v[214:217], v[66:69]
	s_barrier
	s_add_i32 s48, s55, s13
	s_mov_b32 m0, s48
	ds_read_b128 v[186:189], v152 offset:49152
	ds_read_b128 v[190:193], v152 offset:50176
	ds_read_b128 v[194:197], v152 offset:51200
	ds_read_b128 v[198:201], v152 offset:52224
	ds_read_b128 v[202:205], v152 offset:53248
	ds_read_b128 v[206:209], v152 offset:54272
	ds_read_b128 v[210:213], v152 offset:55296
	ds_read_b128 v[214:217], v152 offset:56320
	global_load_lds_dwordx4 v132, s[98:99]
	s_add_i32 m0, s48, 0x2000
	s_add_u32 s46, s46, 0x40080
	s_addc_u32 s47, s47, 0
	s_add_i32 s48, s56, s13
	global_load_lds_dwordx4 v136, s[98:99]
	s_mov_b32 m0, s48
	s_nop 0
	global_load_lds_dwordx4 v132, s[46:47]
	s_add_i32 m0, s48, 0x2000
	s_nop 0
	global_load_lds_dwordx4 v136, s[46:47]
	s_mov_b32 m0, s42
	s_nop 0
	global_load_lds_dwordx4 v130, s[100:101]
	s_mov_b32 m0, s43
	s_nop 0
	global_load_lds_dwordx4 v134, s[100:101]
	s_waitcnt vmcnt(8) lgkmcnt(0)
	s_barrier
	v_mfma_f32_16x16x32_bf16 v[62:65], v[154:157], v[186:189], v[62:65]
	v_mfma_f32_16x16x32_bf16 v[58:61], v[162:165], v[186:189], v[58:61]
	v_mfma_f32_16x16x32_bf16 v[46:49], v[154:157], v[194:197], v[46:49]
	v_mfma_f32_16x16x32_bf16 v[42:45], v[162:165], v[194:197], v[42:45]
	v_mfma_f32_16x16x32_bf16 v[30:33], v[154:157], v[202:205], v[30:33]
	v_mfma_f32_16x16x32_bf16 v[26:29], v[162:165], v[202:205], v[26:29]
	v_mfma_f32_16x16x32_bf16 v[14:17], v[154:157], v[210:213], v[14:17]
	v_mfma_f32_16x16x32_bf16 v[10:13], v[162:165], v[210:213], v[10:13]
	v_mfma_f32_16x16x32_bf16 v[62:65], v[158:161], v[190:193], v[62:65]
	v_mfma_f32_16x16x32_bf16 v[58:61], v[166:169], v[190:193], v[58:61]
	v_mfma_f32_16x16x32_bf16 v[46:49], v[158:161], v[198:201], v[46:49]
	v_mfma_f32_16x16x32_bf16 v[42:45], v[166:169], v[198:201], v[42:45]
	v_mfma_f32_16x16x32_bf16 v[30:33], v[158:161], v[206:209], v[30:33]
	v_mfma_f32_16x16x32_bf16 v[26:29], v[166:169], v[206:209], v[26:29]
	v_mfma_f32_16x16x32_bf16 v[14:17], v[158:161], v[214:217], v[14:17]
	v_mfma_f32_16x16x32_bf16 v[10:13], v[166:169], v[214:217], v[10:13]
	v_mfma_f32_16x16x32_bf16 v[54:57], v[170:173], v[186:189], v[54:57]
	v_mfma_f32_16x16x32_bf16 v[50:53], v[178:181], v[186:189], v[50:53]
	v_mfma_f32_16x16x32_bf16 v[38:41], v[170:173], v[194:197], v[38:41]
	v_mfma_f32_16x16x32_bf16 v[34:37], v[178:181], v[194:197], v[34:37]
	v_mfma_f32_16x16x32_bf16 v[22:25], v[170:173], v[202:205], v[22:25]
	v_mfma_f32_16x16x32_bf16 v[18:21], v[178:181], v[202:205], v[18:21]
	v_mfma_f32_16x16x32_bf16 v[6:9], v[170:173], v[210:213], v[6:9]
	v_mfma_f32_16x16x32_bf16 v[2:5], v[178:181], v[210:213], v[2:5]
	v_mfma_f32_16x16x32_bf16 v[54:57], v[174:177], v[190:193], v[54:57]
	v_mfma_f32_16x16x32_bf16 v[50:53], v[182:185], v[190:193], v[50:53]
	v_mfma_f32_16x16x32_bf16 v[38:41], v[174:177], v[198:201], v[38:41]
	v_mfma_f32_16x16x32_bf16 v[34:37], v[182:185], v[198:201], v[34:37]
	v_mfma_f32_16x16x32_bf16 v[22:25], v[174:177], v[206:209], v[22:25]
	v_mfma_f32_16x16x32_bf16 v[18:21], v[182:185], v[206:209], v[18:21]
	v_mfma_f32_16x16x32_bf16 v[6:9], v[174:177], v[214:217], v[6:9]
	v_mfma_f32_16x16x32_bf16 v[2:5], v[182:185], v[214:217], v[2:5]
	s_barrier
	s_add_i32 s54, s54, 2
	s_add_u32 s30, s30, 0x100
	s_addc_u32 s31, s31, 0
	s_cmp_gt_u32 s54, 13
	s_cbranch_scc0 .LBB0_1631
	s_add_u32 s30, s50, 0xffffff00
	s_addc_u32 s31, s51, -1
	s_andn2_b64 vcc, exec, s[6:7]
	s_cbranch_vccnz .LBB0_1634
	v_mov_b32_e32 v2, 0
	s_mov_b32 s10, s22
	s_mov_b32 s16, s24
	s_mov_b64 s[18:19], s[28:29]
	s_mov_b32 s41, s2
	v_mov_b32_e32 v3, v2
	v_mov_b32_e32 v4, v2
	v_mov_b32_e32 v5, v2
	v_mov_b32_e32 v6, v2
	v_mov_b32_e32 v7, v2
	v_mov_b32_e32 v8, v2
	v_mov_b32_e32 v9, v2
	v_mov_b32_e32 v18, v2
	v_mov_b32_e32 v19, v2
	v_mov_b32_e32 v20, v2
	v_mov_b32_e32 v21, v2
	v_mov_b32_e32 v22, v2
	v_mov_b32_e32 v23, v2
	v_mov_b32_e32 v24, v2
	v_mov_b32_e32 v25, v2
	v_mov_b32_e32 v34, v2
	v_mov_b32_e32 v35, v2
	v_mov_b32_e32 v36, v2
	v_mov_b32_e32 v37, v2
	v_mov_b32_e32 v38, v2
	v_mov_b32_e32 v39, v2
	v_mov_b32_e32 v40, v2
	v_mov_b32_e32 v41, v2
	v_mov_b32_e32 v50, v2
	v_mov_b32_e32 v51, v2
	v_mov_b32_e32 v52, v2
	v_mov_b32_e32 v53, v2
	v_mov_b32_e32 v54, v2
	v_mov_b32_e32 v55, v2
	v_mov_b32_e32 v56, v2
	v_mov_b32_e32 v57, v2
	v_mov_b32_e32 v10, v2
	v_mov_b32_e32 v11, v2
	v_mov_b32_e32 v12, v2
	v_mov_b32_e32 v13, v2
	v_mov_b32_e32 v14, v2
	v_mov_b32_e32 v15, v2
	v_mov_b32_e32 v16, v2
	v_mov_b32_e32 v17, v2
	v_mov_b32_e32 v26, v2
	v_mov_b32_e32 v27, v2
	v_mov_b32_e32 v28, v2
	v_mov_b32_e32 v29, v2
	v_mov_b32_e32 v30, v2
	v_mov_b32_e32 v31, v2
	v_mov_b32_e32 v32, v2
	v_mov_b32_e32 v33, v2
	v_mov_b32_e32 v42, v2
	v_mov_b32_e32 v43, v2
	v_mov_b32_e32 v44, v2
	v_mov_b32_e32 v45, v2
	v_mov_b32_e32 v46, v2
	v_mov_b32_e32 v47, v2
	v_mov_b32_e32 v48, v2
	v_mov_b32_e32 v49, v2
	v_mov_b32_e32 v58, v2
	v_mov_b32_e32 v59, v2
	v_mov_b32_e32 v60, v2
	v_mov_b32_e32 v61, v2
	v_mov_b32_e32 v62, v2
	v_mov_b32_e32 v63, v2
	v_mov_b32_e32 v64, v2
	v_mov_b32_e32 v65, v2
	v_mov_b32_e32 v66, v2
	v_mov_b32_e32 v67, v2
	v_mov_b32_e32 v68, v2
	v_mov_b32_e32 v69, v2
	v_mov_b32_e32 v70, v2
	v_mov_b32_e32 v71, v2
	v_mov_b32_e32 v72, v2
	v_mov_b32_e32 v73, v2
	v_mov_b32_e32 v82, v2
	v_mov_b32_e32 v83, v2
	v_mov_b32_e32 v84, v2
	v_mov_b32_e32 v85, v2
	v_mov_b32_e32 v86, v2
	v_mov_b32_e32 v87, v2
	v_mov_b32_e32 v88, v2
	v_mov_b32_e32 v89, v2
	v_mov_b32_e32 v98, v2
	v_mov_b32_e32 v99, v2
	v_mov_b32_e32 v100, v2
	v_mov_b32_e32 v101, v2
	v_mov_b32_e32 v102, v2
	v_mov_b32_e32 v103, v2
	v_mov_b32_e32 v104, v2
	v_mov_b32_e32 v105, v2
	v_mov_b32_e32 v114, v2
	v_mov_b32_e32 v115, v2
	v_mov_b32_e32 v116, v2
	v_mov_b32_e32 v117, v2
	v_mov_b32_e32 v118, v2
	v_mov_b32_e32 v119, v2
	v_mov_b32_e32 v120, v2
	v_mov_b32_e32 v121, v2
	v_mov_b32_e32 v74, v2
	v_mov_b32_e32 v75, v2
	v_mov_b32_e32 v76, v2
	v_mov_b32_e32 v77, v2
	v_mov_b32_e32 v78, v2
	v_mov_b32_e32 v79, v2
	v_mov_b32_e32 v80, v2
	v_mov_b32_e32 v81, v2
	v_mov_b32_e32 v90, v2
	v_mov_b32_e32 v91, v2
	v_mov_b32_e32 v92, v2
	v_mov_b32_e32 v93, v2
	v_mov_b32_e32 v94, v2
	v_mov_b32_e32 v95, v2
	v_mov_b32_e32 v96, v2
	v_mov_b32_e32 v97, v2
	v_mov_b32_e32 v106, v2
	v_mov_b32_e32 v107, v2
	v_mov_b32_e32 v108, v2
	v_mov_b32_e32 v109, v2
	v_mov_b32_e32 v110, v2
	v_mov_b32_e32 v111, v2
	v_mov_b32_e32 v112, v2
	v_mov_b32_e32 v113, v2
	v_mov_b32_e32 v122, v2
	v_mov_b32_e32 v123, v2
	v_mov_b32_e32 v124, v2
	v_mov_b32_e32 v125, v2
	v_mov_b32_e32 v126, v2
	v_mov_b32_e32 v127, v2
	v_mov_b32_e32 v128, v2
	v_mov_b32_e32 v129, v2
	s_andn2_b64 vcc, exec, s[4:5]
	s_cbranch_vccnz .LBB0_1635
	s_branch .LBB0_1636

.LBB0_1882:
	v_and_b32_e32 v14, 15, v0
	v_and_b32_e32 v15, 48, v0
	v_lshlrev_b32_e32 v16, 2, v0
	v_lshl_or_b32 v1, s2, 6, v14
	v_lshl_or_b32 v14, v14, 6, v15
	s_lshl_b32 s2, s2, 13
	v_and_b32_e32 v16, 32, v16
	s_mov_b64 s[20:21], 0x80
	s_and_b32 s30, s4, 3
	v_bitop3_b32 v14, v14, s2, v16 bitop3:0xde
	v_lshlrev_b32_e32 v17, 6, v0
	s_movk_i32 s2, 0x3c0
	s_add_i32 m0, s33, 0x18000
	v_lshl_add_u64 v[8:9], v[8:9], 0, s[20:21]
	v_and_or_b32 v15, v17, s2, v15
	s_lshl_b32 s2, s30, 12
	s_waitcnt vmcnt(2)
	s_barrier
	global_load_lds_dwordx4 v[8:9], off
	v_lshl_add_u64 v[6:7], v[6:7], 0, s[20:21]
	s_add_i32 m0, s33, 0x1a000
	s_add_i32 s42, s33, 0x8000
	s_add_i32 s43, s33, 0xa000
	global_load_lds_dwordx4 v[6:7], off
	v_lshl_add_u64 v[4:5], v[4:5], 0, s[20:21]
	s_mov_b32 m0, s42
	s_add_u32 s6, s24, 0xb0080
	global_load_lds_dwordx4 v[4:5], off
	v_lshl_add_u64 v[2:3], v[2:3], 0, s[20:21]
	s_mov_b32 m0, s43
	s_addc_u32 s7, s25, 0
	global_load_lds_dwordx4 v[2:3], off
	s_add_i32 m0, s33, 0x1c000
	v_lshl_add_u64 v[2:3], s[6:7], 0, v[132:133]
	global_load_lds_dwordx4 v[2:3], off
	v_lshl_add_u64 v[2:3], s[6:7], 0, v[136:137]
	s_add_i32 m0, s33, 0x1e000
	s_sext_i32_i8 s16, s5
	global_load_lds_dwordx4 v[2:3], off
	v_add_u16_e32 v2, v10, v11
	v_lshrrev_b16_e32 v4, 1, v2
	s_mov_b64 s[4:5], 0xb0080
	s_waitcnt vmcnt(6)
	v_add_lshl_u32 v2, v12, v4, 1
	v_mov_b32_e32 v3, v133
	v_lshl_add_u64 v[138:139], v[2:3], 0, s[4:5]
	v_add_lshl_u32 v2, v13, v4, 1
	v_bitop3_b32 v151, s2, v15, v16 bitop3:0xf6
	v_lshl_add_u64 v[140:141], v[2:3], 0, s[4:5]
	v_mov_b64_e32 v[142:143], 0x100
	v_mov_b64_e32 v[144:145], 0xff
	s_add_i32 s44, 0, 0x10000
	s_add_i32 s45, 0, 0x14000
	v_add_u32_e32 v152, 0, v14
	v_mov_b32_e32 v2, v133
	v_mov_b32_e32 v4, v133
	v_mov_b32_e32 v13, v133
	v_mov_b32_e32 v14, v133
	v_mov_b32_e32 v15, v133
	v_mov_b32_e32 v16, v133
	s_barrier

.Lpeel9_p3:
	s_add_i32 s51, 0, 0x18000
	v_add_u32_e32 v153, s51, v151
	s_add_i32 s52, 0, 0x1c000
	ds_read_b128 v[154:157], v153
	ds_read_b128 v[158:161], v153 offset:1024
	ds_read_b128 v[162:165], v153 offset:2048
	ds_read_b128 v[166:169], v153 offset:3072
	v_add_u32_e32 v153, s52, v151
	ds_read_b128 v[170:173], v153
	ds_read_b128 v[174:177], v153 offset:1024
	ds_read_b128 v[178:181], v153 offset:2048
	ds_read_b128 v[182:185], v153 offset:3072
	s_add_u32 s28, s28, 0xb0000
	s_addc_u32 s29, s29, 0
	s_mov_b32 m0, s15
	ds_read_b128 v[186:189], v152 offset:32768
	ds_read_b128 v[190:193], v152 offset:33792
	ds_read_b128 v[194:197], v152 offset:34816
	ds_read_b128 v[198:201], v152 offset:35840
	ds_read_b128 v[202:205], v152 offset:36864
	ds_read_b128 v[206:209], v152 offset:37888
	ds_read_b128 v[210:213], v152 offset:38912
	ds_read_b128 v[214:217], v152 offset:39936
	global_load_lds_dwordx4 v130, s[28:29]
	s_mov_b32 m0, s40
	s_nop 0
	global_load_lds_dwordx4 v134, s[28:29]
	s_waitcnt vmcnt(8) lgkmcnt(0)
	s_barrier
	v_mfma_f32_16x16x32_bf16 v[126:129], v[154:157], v[186:189], v[126:129]
	v_mfma_f32_16x16x32_bf16 v[122:125], v[162:165], v[186:189], v[122:125]
	v_mfma_f32_16x16x32_bf16 v[110:113], v[154:157], v[194:197], v[110:113]
	v_mfma_f32_16x16x32_bf16 v[106:109], v[162:165], v[194:197], v[106:109]
	v_mfma_f32_16x16x32_bf16 v[94:97], v[154:157], v[202:205], v[94:97]
	v_mfma_f32_16x16x32_bf16 v[90:93], v[162:165], v[202:205], v[90:93]
	v_mfma_f32_16x16x32_bf16 v[78:81], v[154:157], v[210:213], v[78:81]
	v_mfma_f32_16x16x32_bf16 v[74:77], v[162:165], v[210:213], v[74:77]
	v_mfma_f32_16x16x32_bf16 v[126:129], v[158:161], v[190:193], v[126:129]
	v_mfma_f32_16x16x32_bf16 v[122:125], v[166:169], v[190:193], v[122:125]
	v_mfma_f32_16x16x32_bf16 v[110:113], v[158:161], v[198:201], v[110:113]
	v_mfma_f32_16x16x32_bf16 v[106:109], v[166:169], v[198:201], v[106:109]
	v_mfma_f32_16x16x32_bf16 v[94:97], v[158:161], v[206:209], v[94:97]
	v_mfma_f32_16x16x32_bf16 v[90:93], v[166:169], v[206:209], v[90:93]
	v_mfma_f32_16x16x32_bf16 v[78:81], v[158:161], v[214:217], v[78:81]
	v_mfma_f32_16x16x32_bf16 v[74:77], v[166:169], v[214:217], v[74:77]
	v_mfma_f32_16x16x32_bf16 v[118:121], v[170:173], v[186:189], v[118:121]
	v_mfma_f32_16x16x32_bf16 v[114:117], v[178:181], v[186:189], v[114:117]
	v_mfma_f32_16x16x32_bf16 v[102:105], v[170:173], v[194:197], v[102:105]
	v_mfma_f32_16x16x32_bf16 v[98:101], v[178:181], v[194:197], v[98:101]
	v_mfma_f32_16x16x32_bf16 v[86:89], v[170:173], v[202:205], v[86:89]
	v_mfma_f32_16x16x32_bf16 v[82:85], v[178:181], v[202:205], v[82:85]
	v_mfma_f32_16x16x32_bf16 v[70:73], v[170:173], v[210:213], v[70:73]
	v_mfma_f32_16x16x32_bf16 v[66:69], v[178:181], v[210:213], v[66:69]
	v_mfma_f32_16x16x32_bf16 v[118:121], v[174:177], v[190:193], v[118:121]
	v_mfma_f32_16x16x32_bf16 v[114:117], v[182:185], v[190:193], v[114:117]
	v_mfma_f32_16x16x32_bf16 v[102:105], v[174:177], v[198:201], v[102:105]
	v_mfma_f32_16x16x32_bf16 v[98:101], v[182:185], v[198:201], v[98:101]
	v_mfma_f32_16x16x32_bf16 v[86:89], v[174:177], v[206:209], v[86:89]
	v_mfma_f32_16x16x32_bf16 v[82:85], v[182:185], v[206:209], v[82:85]
	v_mfma_f32_16x16x32_bf16 v[70:73], v[174:177], v[214:217], v[70:73]
	v_mfma_f32_16x16x32_bf16 v[66:69], v[182:185], v[214:217], v[66:69]
	s_barrier
	s_add_i32 s28, s51, s13
	s_mov_b32 m0, s28
	ds_read_b128 v[186:189], v152 offset:49152
	ds_read_b128 v[190:193], v152 offset:50176
	ds_read_b128 v[194:197], v152 offset:51200
	ds_read_b128 v[198:201], v152 offset:52224
	ds_read_b128 v[202:205], v152 offset:53248
	ds_read_b128 v[206:209], v152 offset:54272
	ds_read_b128 v[210:213], v152 offset:55296
	ds_read_b128 v[214:217], v152 offset:56320
	global_load_lds_dwordx4 v132, s[98:99]
	s_add_i32 m0, s28, 0x2000
	s_add_u32 s26, s26, 0xb0080
	s_addc_u32 s27, s27, 0
	s_add_i32 s28, s52, s13
	global_load_lds_dwordx4 v136, s[98:99]
	s_mov_b32 m0, s28
	s_nop 0
	global_load_lds_dwordx4 v132, s[26:27]
	s_add_i32 m0, s28, 0x2000
	s_nop 0
	global_load_lds_dwordx4 v136, s[26:27]
	s_mov_b32 m0, s42
	s_nop 0
	global_load_lds_dwordx4 v130, s[100:101]
	s_mov_b32 m0, s43
	s_nop 0
	global_load_lds_dwordx4 v134, s[100:101]
	s_waitcnt vmcnt(8) lgkmcnt(0)
	s_barrier
	v_mfma_f32_16x16x32_bf16 v[62:65], v[154:157], v[186:189], v[62:65]
	v_mfma_f32_16x16x32_bf16 v[58:61], v[162:165], v[186:189], v[58:61]
	v_mfma_f32_16x16x32_bf16 v[46:49], v[154:157], v[194:197], v[46:49]
	v_mfma_f32_16x16x32_bf16 v[42:45], v[162:165], v[194:197], v[42:45]
	v_mfma_f32_16x16x32_bf16 v[30:33], v[154:157], v[202:205], v[30:33]
	v_mfma_f32_16x16x32_bf16 v[26:29], v[162:165], v[202:205], v[26:29]
	v_mfma_f32_16x16x32_bf16 v[14:17], v[154:157], v[210:213], v[14:17]
	v_mfma_f32_16x16x32_bf16 v[10:13], v[162:165], v[210:213], v[10:13]
	v_mfma_f32_16x16x32_bf16 v[62:65], v[158:161], v[190:193], v[62:65]
	v_mfma_f32_16x16x32_bf16 v[58:61], v[166:169], v[190:193], v[58:61]
	v_mfma_f32_16x16x32_bf16 v[46:49], v[158:161], v[198:201], v[46:49]
	v_mfma_f32_16x16x32_bf16 v[42:45], v[166:169], v[198:201], v[42:45]
	v_mfma_f32_16x16x32_bf16 v[30:33], v[158:161], v[206:209], v[30:33]
	v_mfma_f32_16x16x32_bf16 v[26:29], v[166:169], v[206:209], v[26:29]
	v_mfma_f32_16x16x32_bf16 v[14:17], v[158:161], v[214:217], v[14:17]
	v_mfma_f32_16x16x32_bf16 v[10:13], v[166:169], v[214:217], v[10:13]
	v_mfma_f32_16x16x32_bf16 v[54:57], v[170:173], v[186:189], v[54:57]
	v_mfma_f32_16x16x32_bf16 v[50:53], v[178:181], v[186:189], v[50:53]
	v_mfma_f32_16x16x32_bf16 v[38:41], v[170:173], v[194:197], v[38:41]
	v_mfma_f32_16x16x32_bf16 v[34:37], v[178:181], v[194:197], v[34:37]
	v_mfma_f32_16x16x32_bf16 v[22:25], v[170:173], v[202:205], v[22:25]
	v_mfma_f32_16x16x32_bf16 v[18:21], v[178:181], v[202:205], v[18:21]
	v_mfma_f32_16x16x32_bf16 v[6:9], v[170:173], v[210:213], v[6:9]
	v_mfma_f32_16x16x32_bf16 v[2:5], v[178:181], v[210:213], v[2:5]
	v_mfma_f32_16x16x32_bf16 v[54:57], v[174:177], v[190:193], v[54:57]
	v_mfma_f32_16x16x32_bf16 v[50:53], v[182:185], v[190:193], v[50:53]
	v_mfma_f32_16x16x32_bf16 v[38:41], v[174:177], v[198:201], v[38:41]
	v_mfma_f32_16x16x32_bf16 v[34:37], v[182:185], v[198:201], v[34:37]
	v_mfma_f32_16x16x32_bf16 v[22:25], v[174:177], v[206:209], v[22:25]
	v_mfma_f32_16x16x32_bf16 v[18:21], v[182:185], v[206:209], v[18:21]
	v_mfma_f32_16x16x32_bf16 v[6:9], v[174:177], v[214:217], v[6:9]
	v_mfma_f32_16x16x32_bf16 v[2:5], v[182:185], v[214:217], v[2:5]
	s_barrier
	s_add_i32 s50, s50, 2
	s_add_u32 s24, s24, 0x100
	s_addc_u32 s25, s25, 0
	s_cmp_gt_u32 s50, 41
	s_cbranch_scc0 .LBB0_1894
	s_add_u32 s24, s48, 0xffffff00
	s_addc_u32 s25, s49, -1
	s_and_b64 vcc, exec, s[6:7]
	s_cbranch_vccnz .LBB0_1897
	v_mov_b32_e32 v2, 0
	s_mov_b32 s16, s46
	s_mov_b32 s31, s47
	s_mov_b64 s[18:19], s[22:23]
	s_mov_b32 s41, s2
	v_mov_b32_e32 v3, v2
	v_mov_b32_e32 v4, v2
	v_mov_b32_e32 v5, v2
	v_mov_b32_e32 v6, v2
	v_mov_b32_e32 v7, v2
	v_mov_b32_e32 v8, v2
	v_mov_b32_e32 v9, v2
	v_mov_b32_e32 v18, v2
	v_mov_b32_e32 v19, v2
	v_mov_b32_e32 v20, v2
	v_mov_b32_e32 v21, v2
	v_mov_b32_e32 v22, v2
	v_mov_b32_e32 v23, v2
	v_mov_b32_e32 v24, v2
	v_mov_b32_e32 v25, v2
	v_mov_b32_e32 v34, v2
	v_mov_b32_e32 v35, v2
	v_mov_b32_e32 v36, v2
	v_mov_b32_e32 v37, v2
	v_mov_b32_e32 v38, v2
	v_mov_b32_e32 v39, v2
	v_mov_b32_e32 v40, v2
	v_mov_b32_e32 v41, v2
	v_mov_b32_e32 v50, v2
	v_mov_b32_e32 v51, v2
	v_mov_b32_e32 v52, v2
	v_mov_b32_e32 v53, v2
	v_mov_b32_e32 v54, v2
	v_mov_b32_e32 v55, v2
	v_mov_b32_e32 v56, v2
	v_mov_b32_e32 v57, v2
	v_mov_b32_e32 v10, v2
	v_mov_b32_e32 v11, v2
	v_mov_b32_e32 v12, v2
	v_mov_b32_e32 v13, v2
	v_mov_b32_e32 v14, v2
	v_mov_b32_e32 v15, v2
	v_mov_b32_e32 v16, v2
	v_mov_b32_e32 v17, v2
	v_mov_b32_e32 v26, v2
	v_mov_b32_e32 v27, v2
	v_mov_b32_e32 v28, v2
	v_mov_b32_e32 v29, v2
	v_mov_b32_e32 v30, v2
	v_mov_b32_e32 v31, v2
	v_mov_b32_e32 v32, v2
	v_mov_b32_e32 v33, v2
	v_mov_b32_e32 v42, v2
	v_mov_b32_e32 v43, v2
	v_mov_b32_e32 v44, v2
	v_mov_b32_e32 v45, v2
	v_mov_b32_e32 v46, v2
	v_mov_b32_e32 v47, v2
	v_mov_b32_e32 v48, v2
	v_mov_b32_e32 v49, v2
	v_mov_b32_e32 v58, v2
	v_mov_b32_e32 v59, v2
	v_mov_b32_e32 v60, v2
	v_mov_b32_e32 v61, v2
	v_mov_b32_e32 v62, v2
	v_mov_b32_e32 v63, v2
	v_mov_b32_e32 v64, v2
	v_mov_b32_e32 v65, v2
	v_mov_b32_e32 v66, v2
	v_mov_b32_e32 v67, v2
	v_mov_b32_e32 v68, v2
	v_mov_b32_e32 v69, v2
	v_mov_b32_e32 v70, v2
	v_mov_b32_e32 v71, v2
	v_mov_b32_e32 v72, v2
	v_mov_b32_e32 v73, v2
	v_mov_b32_e32 v82, v2
	v_mov_b32_e32 v83, v2
	v_mov_b32_e32 v84, v2
	v_mov_b32_e32 v85, v2
	v_mov_b32_e32 v86, v2
	v_mov_b32_e32 v87, v2
	v_mov_b32_e32 v88, v2
	v_mov_b32_e32 v89, v2
	v_mov_b32_e32 v98, v2
	v_mov_b32_e32 v99, v2
	v_mov_b32_e32 v100, v2
	v_mov_b32_e32 v101, v2
	v_mov_b32_e32 v102, v2
	v_mov_b32_e32 v103, v2
	v_mov_b32_e32 v104, v2
	v_mov_b32_e32 v105, v2
	v_mov_b32_e32 v114, v2
	v_mov_b32_e32 v115, v2
	v_mov_b32_e32 v116, v2
	v_mov_b32_e32 v117, v2
	v_mov_b32_e32 v118, v2
	v_mov_b32_e32 v119, v2
	v_mov_b32_e32 v120, v2
	v_mov_b32_e32 v121, v2
	v_mov_b32_e32 v74, v2
	v_mov_b32_e32 v75, v2
	v_mov_b32_e32 v76, v2
	v_mov_b32_e32 v77, v2
	v_mov_b32_e32 v78, v2
	v_mov_b32_e32 v79, v2
	v_mov_b32_e32 v80, v2
	v_mov_b32_e32 v81, v2
	v_mov_b32_e32 v90, v2
	v_mov_b32_e32 v91, v2
	v_mov_b32_e32 v92, v2
	v_mov_b32_e32 v93, v2
	v_mov_b32_e32 v94, v2
	v_mov_b32_e32 v95, v2
	v_mov_b32_e32 v96, v2
	v_mov_b32_e32 v97, v2
	v_mov_b32_e32 v106, v2
	v_mov_b32_e32 v107, v2
	v_mov_b32_e32 v108, v2
	v_mov_b32_e32 v109, v2
	v_mov_b32_e32 v110, v2
	v_mov_b32_e32 v111, v2
	v_mov_b32_e32 v112, v2
	v_mov_b32_e32 v113, v2
	v_mov_b32_e32 v122, v2
	v_mov_b32_e32 v123, v2
	v_mov_b32_e32 v124, v2
	v_mov_b32_e32 v125, v2
	v_mov_b32_e32 v126, v2
	v_mov_b32_e32 v127, v2
	v_mov_b32_e32 v128, v2
	v_mov_b32_e32 v129, v2
	s_andn2_b64 vcc, exec, s[4:5]
	s_cbranch_vccnz .LBB0_1898
	s_branch .LBB0_1899

.LBB0_2030:
	s_ashr_i32 s23, s22, 31
	s_lshl_b64 s[14:15], s[22:23], 19
	v_cmp_lt_i64_e32 vcc, s[24:25], v[252:253]
	s_add_u32 s24, s68, s14
	s_addc_u32 s25, s69, s15
	s_and_b64 s[14:15], vcc, exec
	s_cselect_b32 s14, s25, s31
	s_cselect_b32 s15, s24, s30
	s_ashr_i32 s21, s20, 31
	s_lshl_b64 s[26:27], s[20:21], 19
	s_add_u32 s26, s40, s26
	s_addc_u32 s27, s41, s27
	s_and_b64 s[38:39], vcc, exec
	s_cselect_b32 s21, s27, s35
	s_cselect_b32 s23, s26, s34
	s_add_u32 s30, s30, 0x40080
	s_addc_u32 s31, s31, 0
	s_add_u32 s61, s34, 0x100
	s_addc_u32 s62, s35, 0
	s_mov_b32 s63, -2
	ds_read_b128 v[36:39], v203
	ds_read_b128 v[44:47], v203 offset:1024
	ds_read_b128 v[48:51], v203 offset:2048
	ds_read_b128 v[56:59], v203 offset:3072
	ds_read_b128 v[144:147], v207
	ds_read_b128 v[148:151], v207 offset:1024
	ds_read_b128 v[152:155], v207 offset:2048
	ds_read_b128 v[156:159], v207 offset:3072
	s_add_u32 s34, s30, 0xfffc0080
	s_addc_u32 s35, s31, -1
	s_cmp_eq_u32 s63, 12
	s_cselect_b32 s39, s14, s35
	s_cselect_b32 s38, s15, s34
	s_cselect_b32 s35, s21, s62
	s_cselect_b32 s34, s23, s61
	s_add_i32 m0, s29, 0xc000
	ds_read_b128 v[172:175], v209
	ds_read_b128 v[176:179], v209 offset:1024
	ds_read_b128 v[180:183], v209 offset:2048
	ds_read_b128 v[184:187], v209 offset:3072
	ds_read_b128 v[188:191], v209 offset:4096
	ds_read_b128 v[192:195], v209 offset:5120
	ds_read_b128 v[196:199], v209 offset:6144
	ds_read_b128 v[214:217], v209 offset:7168
	global_load_lds_dwordx4 v168, s[30:31]
	s_add_i32 m0, s29, 0xe000
	s_nop 0
	global_load_lds_dwordx4 v170, s[30:31]
	s_waitcnt vmcnt(8) lgkmcnt(0)
	s_barrier
	v_mfma_f32_16x16x32_bf16 v[140:143], v[36:39], v[172:175], 0
	v_mfma_f32_16x16x32_bf16 v[136:139], v[48:51], v[172:175], 0
	v_mfma_f32_16x16x32_bf16 v[124:127], v[36:39], v[180:183], 0
	v_mfma_f32_16x16x32_bf16 v[120:123], v[48:51], v[180:183], 0
	v_mfma_f32_16x16x32_bf16 v[108:111], v[36:39], v[188:191], 0
	v_mfma_f32_16x16x32_bf16 v[104:107], v[48:51], v[188:191], 0
	v_mfma_f32_16x16x32_bf16 v[92:95], v[36:39], v[196:199], 0
	v_mfma_f32_16x16x32_bf16 v[88:91], v[48:51], v[196:199], 0
	v_mfma_f32_16x16x32_bf16 v[140:143], v[44:47], v[176:179], v[140:143]
	v_mfma_f32_16x16x32_bf16 v[136:139], v[56:59], v[176:179], v[136:139]
	v_mfma_f32_16x16x32_bf16 v[124:127], v[44:47], v[184:187], v[124:127]
	v_mfma_f32_16x16x32_bf16 v[120:123], v[56:59], v[184:187], v[120:123]
	v_mfma_f32_16x16x32_bf16 v[108:111], v[44:47], v[192:195], v[108:111]
	v_mfma_f32_16x16x32_bf16 v[104:107], v[56:59], v[192:195], v[104:107]
	v_mfma_f32_16x16x32_bf16 v[92:95], v[44:47], v[214:217], v[92:95]
	v_mfma_f32_16x16x32_bf16 v[88:91], v[56:59], v[214:217], v[88:91]
	v_mfma_f32_16x16x32_bf16 v[132:135], v[144:147], v[172:175], 0
	v_mfma_f32_16x16x32_bf16 v[128:131], v[152:155], v[172:175], 0
	v_mfma_f32_16x16x32_bf16 v[116:119], v[144:147], v[180:183], 0
	v_mfma_f32_16x16x32_bf16 v[112:115], v[152:155], v[180:183], 0
	v_mfma_f32_16x16x32_bf16 v[100:103], v[144:147], v[188:191], 0
	v_mfma_f32_16x16x32_bf16 v[96:99], v[152:155], v[188:191], 0
	v_mfma_f32_16x16x32_bf16 v[84:87], v[144:147], v[196:199], 0
	v_mfma_f32_16x16x32_bf16 v[80:83], v[152:155], v[196:199], 0
	v_mfma_f32_16x16x32_bf16 v[132:135], v[148:151], v[176:179], v[132:135]
	v_mfma_f32_16x16x32_bf16 v[128:131], v[156:159], v[176:179], v[128:131]
	v_mfma_f32_16x16x32_bf16 v[116:119], v[148:151], v[184:187], v[116:119]
	v_mfma_f32_16x16x32_bf16 v[112:115], v[156:159], v[184:187], v[112:115]
	v_mfma_f32_16x16x32_bf16 v[100:103], v[148:151], v[192:195], v[100:103]
	v_mfma_f32_16x16x32_bf16 v[96:99], v[156:159], v[192:195], v[96:99]
	v_mfma_f32_16x16x32_bf16 v[84:87], v[148:151], v[214:217], v[84:87]
	v_mfma_f32_16x16x32_bf16 v[80:83], v[156:159], v[214:217], v[80:83]
	s_barrier
	s_add_i32 s64, s55, s42
	s_add_u32 s98, s34, s16
	s_addc_u32 s99, s35, s17
	s_mov_b32 m0, s64
	ds_read_b128 v[172:175], v209 offset:16384
	ds_read_b128 v[176:179], v209 offset:17408
	ds_read_b128 v[180:183], v209 offset:18432
	ds_read_b128 v[184:187], v209 offset:19456
	ds_read_b128 v[188:191], v209 offset:20480
	ds_read_b128 v[192:195], v209 offset:21504
	ds_read_b128 v[196:199], v209 offset:22528
	ds_read_b128 v[214:217], v209 offset:23552
	global_load_lds_dwordx4 v162, s[34:35]
	s_add_i32 m0, s64, 0x2000
	s_add_u32 s64, s34, 0x40000
	s_addc_u32 s65, s35, 0
	s_add_i32 s66, s56, s42
	global_load_lds_dwordx4 v166, s[34:35]
	s_mov_b32 m0, s66
	s_nop 0
	global_load_lds_dwordx4 v162, s[64:65]
	s_add_i32 m0, s66, 0x2000
	s_nop 0
	global_load_lds_dwordx4 v166, s[64:65]
	s_add_u32 s100, s38, s16
	s_addc_u32 s101, s39, s17
	s_mov_b32 m0, s29
	s_nop 0
	global_load_lds_dwordx4 v160, s[38:39]
	s_mov_b32 m0, s43
	s_nop 0
	global_load_lds_dwordx4 v164, s[38:39]
	s_waitcnt vmcnt(8) lgkmcnt(0)
	s_barrier
	v_mfma_f32_16x16x32_bf16 v[76:79], v[36:39], v[172:175], 0
	v_mfma_f32_16x16x32_bf16 v[72:75], v[48:51], v[172:175], 0
	v_mfma_f32_16x16x32_bf16 v[60:63], v[36:39], v[180:183], 0
	v_mfma_f32_16x16x32_bf16 v[52:55], v[48:51], v[180:183], 0
	v_mfma_f32_16x16x32_bf16 v[28:31], v[36:39], v[188:191], 0
	v_mfma_f32_16x16x32_bf16 v[24:27], v[48:51], v[188:191], 0
	v_mfma_f32_16x16x32_bf16 v[12:15], v[36:39], v[196:199], 0
	v_mfma_f32_16x16x32_bf16 v[8:11], v[48:51], v[196:199], 0
	v_mfma_f32_16x16x32_bf16 v[76:79], v[44:47], v[176:179], v[76:79]
	v_mfma_f32_16x16x32_bf16 v[72:75], v[56:59], v[176:179], v[72:75]
	v_mfma_f32_16x16x32_bf16 v[60:63], v[44:47], v[184:187], v[60:63]
	v_mfma_f32_16x16x32_bf16 v[52:55], v[56:59], v[184:187], v[52:55]
	v_mfma_f32_16x16x32_bf16 v[28:31], v[44:47], v[192:195], v[28:31]
	v_mfma_f32_16x16x32_bf16 v[24:27], v[56:59], v[192:195], v[24:27]
	v_mfma_f32_16x16x32_bf16 v[12:15], v[44:47], v[214:217], v[12:15]
	v_mfma_f32_16x16x32_bf16 v[8:11], v[56:59], v[214:217], v[8:11]
	v_mfma_f32_16x16x32_bf16 v[40:43], v[144:147], v[180:183], 0
	v_mfma_f32_16x16x32_bf16 v[32:35], v[152:155], v[180:183], 0
	v_mfma_f32_16x16x32_bf16 v[20:23], v[144:147], v[188:191], 0
	v_mfma_f32_16x16x32_bf16 v[16:19], v[152:155], v[188:191], 0
	v_mfma_f32_16x16x32_bf16 v[4:7], v[144:147], v[196:199], 0
	v_mfma_f32_16x16x32_bf16 v[0:3], v[152:155], v[196:199], 0
	v_mfma_f32_16x16x32_bf16 v[36:39], v[144:147], v[172:175], 0
	v_mfma_f32_16x16x32_bf16 v[44:47], v[152:155], v[172:175], 0
	v_mfma_f32_16x16x32_bf16 v[40:43], v[148:151], v[184:187], v[40:43]
	v_mfma_f32_16x16x32_bf16 v[32:35], v[156:159], v[184:187], v[32:35]
	v_mfma_f32_16x16x32_bf16 v[20:23], v[148:151], v[192:195], v[20:23]
	v_mfma_f32_16x16x32_bf16 v[16:19], v[156:159], v[192:195], v[16:19]
	v_mfma_f32_16x16x32_bf16 v[4:7], v[148:151], v[214:217], v[4:7]
	v_mfma_f32_16x16x32_bf16 v[0:3], v[156:159], v[214:217], v[0:3]
	v_mfma_f32_16x16x32_bf16 v[36:39], v[148:151], v[176:179], v[36:39]
	v_mfma_f32_16x16x32_bf16 v[44:47], v[156:159], v[176:179], v[44:47]
	s_barrier
	s_branch .Lpeel10_p3

.Lpeel10_p3:
	s_add_i32 s64, 0, 0x18000
	s_add_i32 s65, 0, 0x1c000
	v_add_u32_e32 v68, s64, v201
	v_add_u32_e32 v156, s65, v201
	ds_read_b128 v[48:51], v68
	ds_read_b128 v[56:59], v68 offset:1024
	ds_read_b128 v[64:67], v68 offset:2048
	ds_read_b128 v[68:71], v68 offset:3072
	ds_read_b128 v[144:147], v156
	ds_read_b128 v[148:151], v156 offset:1024
	ds_read_b128 v[152:155], v156 offset:2048
	ds_read_b128 v[156:159], v156 offset:3072
	s_add_u32 s38, s38, 0x40000
	s_addc_u32 s39, s39, 0
	s_mov_b32 m0, s44
	ds_read_b128 v[172:175], v209 offset:32768
	ds_read_b128 v[176:179], v209 offset:33792
	ds_read_b128 v[180:183], v209 offset:34816
	ds_read_b128 v[184:187], v209 offset:35840
	ds_read_b128 v[188:191], v209 offset:36864
	ds_read_b128 v[192:195], v209 offset:37888
	ds_read_b128 v[196:199], v209 offset:38912
	ds_read_b128 v[214:217], v209 offset:39936
	global_load_lds_dwordx4 v160, s[38:39]
	s_mov_b32 m0, s45
	s_nop 0
	global_load_lds_dwordx4 v164, s[38:39]
	s_waitcnt vmcnt(8) lgkmcnt(0)
	s_barrier
	v_mfma_f32_16x16x32_bf16 v[140:143], v[48:51], v[172:175], v[140:143]
	v_mfma_f32_16x16x32_bf16 v[136:139], v[64:67], v[172:175], v[136:139]
	v_mfma_f32_16x16x32_bf16 v[124:127], v[48:51], v[180:183], v[124:127]
	v_mfma_f32_16x16x32_bf16 v[120:123], v[64:67], v[180:183], v[120:123]
	v_mfma_f32_16x16x32_bf16 v[108:111], v[48:51], v[188:191], v[108:111]
	v_mfma_f32_16x16x32_bf16 v[104:107], v[64:67], v[188:191], v[104:107]
	v_mfma_f32_16x16x32_bf16 v[92:95], v[48:51], v[196:199], v[92:95]
	v_mfma_f32_16x16x32_bf16 v[88:91], v[64:67], v[196:199], v[88:91]
	v_mfma_f32_16x16x32_bf16 v[140:143], v[56:59], v[176:179], v[140:143]
	v_mfma_f32_16x16x32_bf16 v[136:139], v[68:71], v[176:179], v[136:139]
	v_mfma_f32_16x16x32_bf16 v[124:127], v[56:59], v[184:187], v[124:127]
	v_mfma_f32_16x16x32_bf16 v[120:123], v[68:71], v[184:187], v[120:123]
	v_mfma_f32_16x16x32_bf16 v[108:111], v[56:59], v[192:195], v[108:111]
	v_mfma_f32_16x16x32_bf16 v[104:107], v[68:71], v[192:195], v[104:107]
	v_mfma_f32_16x16x32_bf16 v[92:95], v[56:59], v[214:217], v[92:95]
	v_mfma_f32_16x16x32_bf16 v[88:91], v[68:71], v[214:217], v[88:91]
	v_mfma_f32_16x16x32_bf16 v[132:135], v[144:147], v[172:175], v[132:135]
	v_mfma_f32_16x16x32_bf16 v[128:131], v[152:155], v[172:175], v[128:131]
	v_mfma_f32_16x16x32_bf16 v[116:119], v[144:147], v[180:183], v[116:119]
	v_mfma_f32_16x16x32_bf16 v[112:115], v[152:155], v[180:183], v[112:115]
	v_mfma_f32_16x16x32_bf16 v[100:103], v[144:147], v[188:191], v[100:103]
	v_mfma_f32_16x16x32_bf16 v[96:99], v[152:155], v[188:191], v[96:99]
	v_mfma_f32_16x16x32_bf16 v[84:87], v[144:147], v[196:199], v[84:87]
	v_mfma_f32_16x16x32_bf16 v[80:83], v[152:155], v[196:199], v[80:83]
	v_mfma_f32_16x16x32_bf16 v[132:135], v[148:151], v[176:179], v[132:135]
	v_mfma_f32_16x16x32_bf16 v[128:131], v[156:159], v[176:179], v[128:131]
	v_mfma_f32_16x16x32_bf16 v[116:119], v[148:151], v[184:187], v[116:119]
	v_mfma_f32_16x16x32_bf16 v[112:115], v[156:159], v[184:187], v[112:115]
	v_mfma_f32_16x16x32_bf16 v[100:103], v[148:151], v[192:195], v[100:103]
	v_mfma_f32_16x16x32_bf16 v[96:99], v[156:159], v[192:195], v[96:99]
	v_mfma_f32_16x16x32_bf16 v[84:87], v[148:151], v[214:217], v[84:87]
	v_mfma_f32_16x16x32_bf16 v[80:83], v[156:159], v[214:217], v[80:83]
	s_barrier
	s_add_i32 s38, s64, s42
	s_mov_b32 m0, s38
	ds_read_b128 v[172:175], v209 offset:49152
	ds_read_b128 v[176:179], v209 offset:50176
	ds_read_b128 v[180:183], v209 offset:51200
	ds_read_b128 v[184:187], v209 offset:52224
	ds_read_b128 v[188:191], v209 offset:53248
	ds_read_b128 v[192:195], v209 offset:54272
	ds_read_b128 v[196:199], v209 offset:55296
	ds_read_b128 v[214:217], v209 offset:56320
	global_load_lds_dwordx4 v162, s[98:99]
	s_add_i32 m0, s38, 0x2000
	s_add_u32 s34, s34, 0x40080
	s_addc_u32 s35, s35, 0
	s_add_i32 s38, s65, s42
	global_load_lds_dwordx4 v166, s[98:99]
	s_mov_b32 m0, s38
	s_nop 0
	global_load_lds_dwordx4 v162, s[34:35]
	s_add_i32 m0, s38, 0x2000
	s_nop 0
	global_load_lds_dwordx4 v166, s[34:35]
	s_mov_b32 m0, s50
	s_nop 0
	global_load_lds_dwordx4 v160, s[100:101]
	s_mov_b32 m0, s51
	s_nop 0
	global_load_lds_dwordx4 v164, s[100:101]
	s_waitcnt vmcnt(8) lgkmcnt(0)
	s_barrier
	v_mfma_f32_16x16x32_bf16 v[76:79], v[48:51], v[172:175], v[76:79]
	v_mfma_f32_16x16x32_bf16 v[72:75], v[64:67], v[172:175], v[72:75]
	v_mfma_f32_16x16x32_bf16 v[60:63], v[48:51], v[180:183], v[60:63]
	v_mfma_f32_16x16x32_bf16 v[52:55], v[64:67], v[180:183], v[52:55]
	v_mfma_f32_16x16x32_bf16 v[28:31], v[48:51], v[188:191], v[28:31]
	v_mfma_f32_16x16x32_bf16 v[24:27], v[64:67], v[188:191], v[24:27]
	v_mfma_f32_16x16x32_bf16 v[12:15], v[48:51], v[196:199], v[12:15]
	v_mfma_f32_16x16x32_bf16 v[8:11], v[64:67], v[196:199], v[8:11]
	v_mfma_f32_16x16x32_bf16 v[76:79], v[56:59], v[176:179], v[76:79]
	v_mfma_f32_16x16x32_bf16 v[72:75], v[68:71], v[176:179], v[72:75]
	v_mfma_f32_16x16x32_bf16 v[60:63], v[56:59], v[184:187], v[60:63]
	v_mfma_f32_16x16x32_bf16 v[52:55], v[68:71], v[184:187], v[52:55]
	v_mfma_f32_16x16x32_bf16 v[28:31], v[56:59], v[192:195], v[28:31]
	v_mfma_f32_16x16x32_bf16 v[24:27], v[68:71], v[192:195], v[24:27]
	v_mfma_f32_16x16x32_bf16 v[12:15], v[56:59], v[214:217], v[12:15]
	v_mfma_f32_16x16x32_bf16 v[8:11], v[68:71], v[214:217], v[8:11]
	v_mfma_f32_16x16x32_bf16 v[36:39], v[144:147], v[172:175], v[36:39]
	v_mfma_f32_16x16x32_bf16 v[68:71], v[148:151], v[176:179], v[36:39]
	v_mfma_f32_16x16x32_bf16 v[36:39], v[152:155], v[172:175], v[44:47]
	v_mfma_f32_16x16x32_bf16 v[64:67], v[156:159], v[176:179], v[36:39]
	v_mfma_f32_16x16x32_bf16 v[36:39], v[144:147], v[180:183], v[40:43]
	v_mfma_f32_16x16x32_bf16 v[32:35], v[152:155], v[180:183], v[32:35]
	v_mfma_f32_16x16x32_bf16 v[20:23], v[144:147], v[188:191], v[20:23]
	v_mfma_f32_16x16x32_bf16 v[16:19], v[152:155], v[188:191], v[16:19]
	v_mfma_f32_16x16x32_bf16 v[4:7], v[144:147], v[196:199], v[4:7]
	v_mfma_f32_16x16x32_bf16 v[0:3], v[152:155], v[196:199], v[0:3]
	v_mfma_f32_16x16x32_bf16 v[40:43], v[148:151], v[184:187], v[36:39]
	v_mfma_f32_16x16x32_bf16 v[32:35], v[156:159], v[184:187], v[32:35]
	v_mfma_f32_16x16x32_bf16 v[20:23], v[148:151], v[192:195], v[20:23]
	v_mfma_f32_16x16x32_bf16 v[16:19], v[156:159], v[192:195], v[16:19]
	v_mfma_f32_16x16x32_bf16 v[4:7], v[148:151], v[214:217], v[4:7]
	v_mfma_f32_16x16x32_bf16 v[0:3], v[156:159], v[214:217], v[0:3]
	s_barrier
	s_add_i32 s63, s63, 2
	s_add_u32 s30, s30, 0x100
	s_addc_u32 s31, s31, 0
	s_add_u32 s61, s61, 0x100
	s_addc_u32 s62, s62, 0
	s_cmp_gt_u32 s63, 13
	s_cbranch_scc0 .LBB0_2031
	s_lshl_b32 s2, s2, 8
	v_mov_b32_e32 v154, v229
	v_mov_b32_e32 v155, v231
	s_or_b32 s2, s2, s49
	s_mov_b64 s[34:35], s[26:27]
	v_lshl_add_u32 v144, v155, 3, s2
	v_ashrrev_i32_e32 v145, 31, v144
	v_lshlrev_b64 v[188:189], 2, v[144:145]
	v_lshl_add_u64 v[150:151], s[4:5], 0, v[188:189]
	global_load_dwordx4 v[36:39], v[150:151], off offset:16
	global_load_dwordx4 v[44:47], v[150:151], off
	v_lshl_add_u64 v[152:153], s[6:7], 0, v[188:189]
	global_load_dwordx4 v[48:51], v[152:153], off offset:16
	global_load_dwordx4 v[56:59], v[152:153], off
	s_lshl_b32 s2, s28, 8
	s_add_i32 s2, s2, s48
	s_mov_b32 s28, s22
	s_mov_b64 s[30:31], s[24:25]
	s_waitcnt vmcnt(0)
	v_pk_mul_f32 v[184:185], v[38:39], s[18:19] op_sel_hi:[1,0]
	v_pk_mul_f32 v[186:187], v[36:37], s[18:19] op_sel_hi:[1,0]
	global_load_dwordx4 v[146:149], v[150:151], off offset:528
	global_load_dwordx4 v[36:39], v[150:151], off offset:512
	v_pk_mul_f32 v[190:191], v[46:47], s[18:19] op_sel_hi:[1,0]
	v_pk_mul_f32 v[192:193], v[44:45], s[18:19] op_sel_hi:[1,0]
	s_waitcnt vmcnt(1)
	v_pk_mul_f32 v[176:177], v[148:149], s[18:19] op_sel_hi:[1,0]
	v_pk_mul_f32 v[178:179], v[146:147], s[18:19] op_sel_hi:[1,0]
	v_add_u32_e32 v146, s2, v154
	v_lshlrev_b32_e32 v148, 2, v155
	v_ashrrev_i32_e32 v149, 31, v148
	v_ashrrev_i32_e32 v147, 31, v146
	v_lshl_add_u64 v[194:195], v[148:149], 2, s[12:13]
	v_lshl_add_u64 v[148:149], v[146:147], 4, s[10:11]
	s_waitcnt vmcnt(0)
	v_pk_mul_f32 v[180:181], v[38:39], s[18:19] op_sel_hi:[1,0]
	v_pk_mul_f32 v[182:183], v[36:37], s[18:19] op_sel_hi:[1,0]
	global_load_dwordx4 v[36:39], v[152:153], off offset:528
	global_load_dwordx4 v[44:47], v[152:153], off offset:512
	v_lshlrev_b64 v[152:153], 6, v[146:147]
	global_load_dwordx4 v[148:151], v[148:149], off
	v_lshl_add_u64 v[152:153], v[194:195], 0, v[152:153]
	global_load_dwordx4 v[152:155], v[152:153], off
	v_add_u32_e32 v238, 16, v146
	v_ashrrev_i32_e32 v239, 31, v238
	v_lshl_add_u64 v[156:157], v[238:239], 4, s[10:11]
	global_load_dwordx4 v[156:159], v[156:157], off
	v_lshlrev_b64 v[172:173], 6, v[238:239]
	v_lshl_add_u64 v[172:173], v[194:195], 0, v[172:173]
	global_load_dwordx4 v[214:217], v[172:173], off
	v_add_u32_e32 v232, 32, v146
	v_ashrrev_i32_e32 v233, 31, v232
	v_lshl_add_u64 v[172:173], v[232:233], 4, s[10:11]
	global_load_dwordx4 v[218:221], v[172:173], off
	v_lshlrev_b64 v[172:173], 6, v[232:233]
	v_lshl_add_u64 v[172:173], v[194:195], 0, v[172:173]
	global_load_dwordx4 v[222:225], v[172:173], off
	v_add_u32_e32 v226, 48, v146
	v_ashrrev_i32_e32 v227, 31, v226
	v_lshl_add_u64 v[172:173], v[226:227], 4, s[10:11]
	global_load_dwordx4 v[244:247], v[172:173], off
	v_lshlrev_b64 v[172:173], 6, v[226:227]
	v_lshl_add_u64 v[172:173], v[194:195], 0, v[172:173]
	global_load_dwordx4 v[248:251], v[172:173], off
	v_add_u32_e32 v210, 0x90, v146
	v_ashrrev_i32_e32 v211, 31, v210
	v_add_u32_e32 v204, 0xa0, v146
	v_ashrrev_i32_e32 v205, 31, v204
	v_add_u32_e32 v198, 0xb0, v146
	v_ashrrev_i32_e32 v199, 31, v198
	v_lshlrev_b64 v[196:197], 6, v[198:199]
	s_mov_b32 s2, s20
	s_waitcnt vmcnt(7)
	v_mov_b32_e32 v172, v149
	v_mov_b32_e32 v173, v150
	v_mov_b32_e32 v149, v151
	v_pk_add_f32 v[148:149], v[172:173], v[148:149]
	v_lshlrev_b64 v[172:173], 6, v[210:211]
	v_add_f32_e32 v148, v148, v149
	v_fmamk_f32 v148, v148, 0x3a800000, v213
	v_rsq_f32_e32 v148, v148
	s_waitcnt vmcnt(6)
	v_add_f32_e32 v149, v154, v155
	v_lshl_add_u64 v[172:173], v[194:195], 0, v[172:173]
	v_mul_f32_e32 v242, 0xbfb8aa3b, v148
	v_add_f32_e32 v148, v152, v153
	v_add_f32_e32 v148, v148, v149
	v_mov_b32_e32 v149, v148
	s_nop 1
	v_permlane16_swap_b32_e32 v148, v149
	v_add_f32_e32 v148, v148, v149
	v_mov_b32_e32 v149, v148
	s_nop 1
	v_permlane32_swap_b32_e32 v148, v149
	v_add_f32_e32 v148, v148, v149
	v_fmamk_f32 v148, v148, 0x3a800000, v213
	v_rsq_f32_e32 v240, v148
	s_waitcnt vmcnt(5)
	v_mov_b32_e32 v148, v157
	v_mov_b32_e32 v149, v158
	v_mov_b32_e32 v157, v159
	v_pk_add_f32 v[148:149], v[148:149], v[156:157]
	v_lshl_add_u64 v[156:157], v[210:211], 4, s[10:11]
	v_add_f32_e32 v148, v148, v149
	v_fmamk_f32 v148, v148, 0x3a800000, v213
	v_rsq_f32_e32 v148, v148
	s_waitcnt vmcnt(4)
	v_add_f32_e32 v149, v216, v217
	global_load_dwordx4 v[156:159], v[156:157], off
	v_pk_fma_f32 v[142:143], v[142:143], v[242:243], v[190:191] op_sel_hi:[1,0,1]
	v_mul_f32_e32 v236, 0xbfb8aa3b, v148
	v_add_f32_e32 v148, v214, v215
	v_add_f32_e32 v148, v148, v149
	v_mov_b32_e32 v149, v148
	s_nop 1
	v_permlane16_swap_b32_e32 v148, v149
	v_add_f32_e32 v148, v148, v149
	v_mov_b32_e32 v149, v148
	s_nop 1
	v_permlane32_swap_b32_e32 v148, v149
	v_add_f32_e32 v148, v148, v149
	v_fmamk_f32 v148, v148, 0x3a800000, v213
	v_rsq_f32_e32 v234, v148
	s_waitcnt vmcnt(4)
	v_mov_b32_e32 v148, v219
	v_mov_b32_e32 v149, v220
	v_mov_b32_e32 v219, v221
	v_pk_add_f32 v[148:149], v[148:149], v[218:219]
	v_add_u32_e32 v220, 0x80, v146
	v_add_f32_e32 v148, v148, v149
	v_fmamk_f32 v148, v148, 0x3a800000, v213
	v_rsq_f32_e32 v148, v148
	s_waitcnt vmcnt(3)
	v_add_f32_e32 v149, v224, v225
	v_ashrrev_i32_e32 v221, 31, v220
	v_lshlrev_b64 v[152:153], 6, v[220:221]
	v_mul_f32_e32 v230, 0xbfb8aa3b, v148
	v_add_f32_e32 v148, v222, v223
	v_add_f32_e32 v148, v148, v149
	v_mov_b32_e32 v149, v148
	s_nop 1
	v_permlane16_swap_b32_e32 v148, v149
	v_add_f32_e32 v148, v148, v149
	v_mov_b32_e32 v149, v148
	s_nop 1
	v_permlane32_swap_b32_e32 v148, v149
	v_add_f32_e32 v148, v148, v149
	v_fmamk_f32 v148, v148, 0x3a800000, v213
	v_rsq_f32_e32 v228, v148
	s_waitcnt vmcnt(2)
	v_mov_b32_e32 v148, v245
	v_mov_b32_e32 v149, v246
	v_mov_b32_e32 v245, v247
	v_pk_add_f32 v[148:149], v[148:149], v[244:245]
	v_lshl_add_u64 v[152:153], v[194:195], 0, v[152:153]
	v_add_f32_e32 v148, v148, v149
	v_fmamk_f32 v148, v148, 0x3a800000, v213
	v_rsq_f32_e32 v148, v148
	s_waitcnt vmcnt(1)
	v_add_f32_e32 v149, v250, v251
	global_load_dwordx4 v[152:155], v[152:153], off
	v_pk_fma_f32 v[140:141], v[140:141], v[242:243], v[192:193] op_sel_hi:[1,0,1]
	v_mul_f32_e32 v224, 0xbfb8aa3b, v148
	v_add_f32_e32 v148, v248, v249
	v_add_f32_e32 v148, v148, v149
	v_mov_b32_e32 v149, v148
	s_nop 1
	v_permlane16_swap_b32_e32 v148, v149
	v_add_f32_e32 v148, v148, v149
	v_mov_b32_e32 v149, v148
	s_nop 1
	v_permlane32_swap_b32_e32 v148, v149
	v_add_f32_e32 v148, v148, v149
	v_fmamk_f32 v148, v148, 0x3a800000, v213
	v_rsq_f32_e32 v222, v148
	v_lshl_add_u64 v[148:149], v[220:221], 4, s[10:11]
	global_load_dwordx4 v[148:151], v[148:149], off
	v_exp_f32_e32 v142, v142
	global_load_dwordx4 v[216:219], v[172:173], off
	v_lshl_add_u64 v[172:173], v[204:205], 4, s[10:11]
	global_load_dwordx4 v[244:247], v[172:173], off
	v_lshlrev_b64 v[172:173], 6, v[204:205]
	v_lshl_add_u64 v[172:173], v[194:195], 0, v[172:173]
	global_load_dwordx4 v[248:251], v[172:173], off
	v_lshl_add_u64 v[194:195], v[194:195], 0, v[196:197]
	global_load_dwordx4 v[194:197], v[194:195], off
	v_lshl_add_u64 v[172:173], v[198:199], 4, s[10:11]
	global_load_dwordx4 v[172:175], v[172:173], off
	v_exp_f32_e32 v143, v143
	v_exp_f32_e32 v140, v140
	v_exp_f32_e32 v141, v141
	v_pk_fma_f32 v[138:139], v[138:139], v[242:243], v[184:185] op_sel_hi:[1,0,1]
	v_pk_add_f32 v[142:143], v[142:143], 1.0 op_sel_hi:[1,0]
	v_exp_f32_e32 v138, v138
	v_exp_f32_e32 v139, v139
	v_pk_fma_f32 v[136:137], v[136:137], v[242:243], v[186:187] op_sel_hi:[1,0,1]
	v_pk_add_f32 v[140:141], v[140:141], 1.0 op_sel_hi:[1,0]
	v_rcp_f32_e32 v142, v142
	v_rcp_f32_e32 v143, v143
	v_exp_f32_e32 v136, v136
	v_exp_f32_e32 v137, v137
	v_rcp_f32_e32 v140, v140
	v_rcp_f32_e32 v141, v141
	v_pk_add_f32 v[138:139], v[138:139], 1.0 op_sel_hi:[1,0]
	v_pk_add_f32 v[136:137], v[136:137], 1.0 op_sel_hi:[1,0]
	v_rcp_f32_e32 v138, v138
	v_rcp_f32_e32 v139, v139
	v_rcp_f32_e32 v136, v136
	v_rcp_f32_e32 v137, v137
	v_pk_fma_f32 v[132:133], v[132:133], v[242:243], v[182:183] op_sel_hi:[1,0,1]
	v_pk_fma_f32 v[134:135], v[134:135], v[242:243], v[180:181] op_sel_hi:[1,0,1]
	v_exp_f32_e32 v132, v132
	v_exp_f32_e32 v133, v133
	v_exp_f32_e32 v134, v134
	v_exp_f32_e32 v135, v135
	v_pk_fma_f32 v[128:129], v[128:129], v[242:243], v[178:179] op_sel_hi:[1,0,1]
	v_pk_fma_f32 v[130:131], v[130:131], v[242:243], v[176:177] op_sel_hi:[1,0,1]
	v_pk_add_f32 v[132:133], v[132:133], 1.0 op_sel_hi:[1,0]
	v_pk_add_f32 v[134:135], v[134:135], 1.0 op_sel_hi:[1,0]
	v_exp_f32_e32 v128, v128
	v_exp_f32_e32 v129, v129
	v_exp_f32_e32 v130, v130
	v_exp_f32_e32 v131, v131
	v_rcp_f32_e32 v132, v132
	v_rcp_f32_e32 v133, v133
	v_rcp_f32_e32 v134, v134
	v_rcp_f32_e32 v135, v135
	v_pk_add_f32 v[128:129], v[128:129], 1.0 op_sel_hi:[1,0]
	v_pk_add_f32 v[130:131], v[130:131], 1.0 op_sel_hi:[1,0]
	v_rcp_f32_e32 v128, v128
	v_rcp_f32_e32 v129, v129
	v_rcp_f32_e32 v130, v130
	v_rcp_f32_e32 v131, v131
	v_pk_fma_f32 v[126:127], v[126:127], v[236:237], v[190:191] op_sel_hi:[1,0,1]
	v_pk_fma_f32 v[124:125], v[124:125], v[236:237], v[192:193] op_sel_hi:[1,0,1]
	v_exp_f32_e32 v126, v126
	v_exp_f32_e32 v127, v127
	v_exp_f32_e32 v124, v124
	v_exp_f32_e32 v125, v125
	v_pk_fma_f32 v[122:123], v[122:123], v[236:237], v[184:185] op_sel_hi:[1,0,1]
	v_pk_add_f32 v[126:127], v[126:127], 1.0 op_sel_hi:[1,0]
	v_exp_f32_e32 v122, v122
	v_exp_f32_e32 v123, v123
	v_pk_fma_f32 v[120:121], v[120:121], v[236:237], v[186:187] op_sel_hi:[1,0,1]
	v_pk_add_f32 v[124:125], v[124:125], 1.0 op_sel_hi:[1,0]
	v_rcp_f32_e32 v126, v126
	v_rcp_f32_e32 v127, v127
	v_exp_f32_e32 v120, v120
	v_exp_f32_e32 v121, v121
	v_rcp_f32_e32 v124, v124
	v_rcp_f32_e32 v125, v125
	v_pk_add_f32 v[122:123], v[122:123], 1.0 op_sel_hi:[1,0]
	v_pk_add_f32 v[120:121], v[120:121], 1.0 op_sel_hi:[1,0]
	v_rcp_f32_e32 v122, v122
	v_rcp_f32_e32 v123, v123
	v_rcp_f32_e32 v120, v120
	s_waitcnt vmcnt(5)
	v_mov_b32_e32 v214, v149
	v_mov_b32_e32 v215, v150
	v_mov_b32_e32 v149, v151
	v_pk_add_f32 v[148:149], v[214:215], v[148:149]
	v_rcp_f32_e32 v121, v121
	v_add_f32_e32 v148, v148, v149
	v_fmamk_f32 v148, v148, 0x3a800000, v213
	v_rsq_f32_e32 v148, v148
	v_add_f32_e32 v149, v154, v155
	v_pk_fma_f32 v[116:117], v[116:117], v[236:237], v[182:183] op_sel_hi:[1,0,1]
	v_pk_fma_f32 v[118:119], v[118:119], v[236:237], v[180:181] op_sel_hi:[1,0,1]
	v_mul_f32_e32 v214, 0xbfb8aa3b, v148
	v_add_f32_e32 v148, v152, v153
	v_add_f32_e32 v148, v148, v149
	v_mov_b32_e32 v149, v148
	s_nop 1
	v_permlane16_swap_b32_e32 v148, v149
	v_add_f32_e32 v148, v148, v149
	v_mov_b32_e32 v149, v148
	s_nop 1
	v_permlane32_swap_b32_e32 v148, v149
	v_add_f32_e32 v148, v148, v149
	v_fmamk_f32 v148, v148, 0x3a800000, v213
	v_rsq_f32_e32 v212, v148
	v_mov_b32_e32 v148, v157
	v_mov_b32_e32 v149, v158
	v_mov_b32_e32 v157, v159
	v_pk_add_f32 v[148:149], v[148:149], v[156:157]
	v_exp_f32_e32 v116, v116
	v_add_f32_e32 v148, v148, v149
	v_fmamk_f32 v148, v148, 0x3a800000, v213
	v_rsq_f32_e32 v148, v148
	s_waitcnt vmcnt(4)
	v_add_f32_e32 v149, v218, v219
	v_exp_f32_e32 v117, v117
	v_exp_f32_e32 v118, v118
	v_mul_f32_e32 v208, 0xbfb8aa3b, v148
	v_add_f32_e32 v148, v216, v217
	v_add_f32_e32 v148, v148, v149
	v_mov_b32_e32 v149, v148
	s_nop 1
	v_permlane16_swap_b32_e32 v148, v149
	v_add_f32_e32 v148, v148, v149
	v_mov_b32_e32 v149, v148
	s_nop 1
	v_permlane32_swap_b32_e32 v148, v149
	v_add_f32_e32 v148, v148, v149
	v_fmamk_f32 v148, v148, 0x3a800000, v213
	v_rsq_f32_e32 v206, v148
	s_waitcnt vmcnt(3)
	v_mov_b32_e32 v148, v245
	v_mov_b32_e32 v149, v246
	v_mov_b32_e32 v245, v247
	v_pk_add_f32 v[148:149], v[148:149], v[244:245]
	v_lshlrev_b64 v[244:245], 12, v[146:147]
	v_add_f32_e32 v148, v148, v149
	v_fmamk_f32 v148, v148, 0x3a800000, v213
	v_rsq_f32_e32 v148, v148
	s_waitcnt vmcnt(2)
	v_add_f32_e32 v149, v250, v251
	v_exp_f32_e32 v119, v119
	v_pk_fma_f32 v[112:113], v[112:113], v[236:237], v[178:179] op_sel_hi:[1,0,1]
	v_mul_f32_e32 v202, 0xbfb8aa3b, v148
	v_add_f32_e32 v148, v248, v249
	v_add_f32_e32 v148, v148, v149
	v_mov_b32_e32 v149, v148
	s_nop 1
	v_permlane16_swap_b32_e32 v148, v149
	v_add_f32_e32 v148, v148, v149
	v_mov_b32_e32 v149, v148
	s_nop 1
	v_permlane32_swap_b32_e32 v148, v149
	v_add_f32_e32 v148, v148, v149
	v_fmamk_f32 v148, v148, 0x3a800000, v213
	v_rsq_f32_e32 v200, v148
	s_waitcnt vmcnt(0)
	v_mov_b32_e32 v148, v173
	v_mov_b32_e32 v149, v174
	v_mov_b32_e32 v173, v175
	v_pk_add_f32 v[148:149], v[148:149], v[172:173]
	v_pk_fma_f32 v[114:115], v[114:115], v[236:237], v[176:177] op_sel_hi:[1,0,1]
	v_add_f32_e32 v148, v148, v149
	v_fmamk_f32 v148, v148, 0x3a800000, v213
	v_rsq_f32_e32 v148, v148
	v_add_f32_e32 v149, v196, v197
	v_pk_add_f32 v[116:117], v[116:117], 1.0 op_sel_hi:[1,0]
	v_pk_add_f32 v[118:119], v[118:119], 1.0 op_sel_hi:[1,0]
	v_mul_f32_e32 v172, 0xbfb8aa3b, v148
	v_add_f32_e32 v148, v194, v195
	v_add_f32_e32 v148, v148, v149
	v_mov_b32_e32 v149, v148
	s_nop 1
	v_permlane16_swap_b32_e32 v148, v149
	v_add_f32_e32 v148, v148, v149
	v_mov_b32_e32 v149, v148
	s_nop 1
	v_permlane32_swap_b32_e32 v148, v149
	v_add_f32_e32 v148, v148, v149
	v_fmamk_f32 v148, v148, 0x3a800000, v213
	v_rsq_f32_e32 v194, v148
	v_lshlrev_b64 v[148:149], 10, v[146:147]
	v_lshl_add_u64 v[144:145], v[148:149], 0, v[144:145]
	v_lshlrev_b64 v[144:145], 1, v[144:145]
	v_lshl_add_u64 v[216:217], s[68:69], 0, v[144:145]
	v_lshl_add_u64 v[218:219], s[8:9], 0, v[144:145]
	global_load_dwordx4 v[152:155], v[216:217], off
	global_load_dwordx4 v[156:159], v[218:219], off
	global_load_dwordx4 v[148:151], v[216:217], off offset:256
	global_load_dwordx4 v[144:147], v[218:219], off offset:256
	v_exp_f32_e32 v112, v112
	v_exp_f32_e32 v113, v113
	v_exp_f32_e32 v114, v114
	v_exp_f32_e32 v115, v115
	v_rcp_f32_e32 v116, v116
	v_rcp_f32_e32 v117, v117
	v_rcp_f32_e32 v118, v118
	v_rcp_f32_e32 v119, v119
	v_pk_add_f32 v[112:113], v[112:113], 1.0 op_sel_hi:[1,0]
	v_pk_add_f32 v[114:115], v[114:115], 1.0 op_sel_hi:[1,0]
	v_rcp_f32_e32 v112, v112
	v_rcp_f32_e32 v113, v113
	v_rcp_f32_e32 v114, v114
	v_rcp_f32_e32 v115, v115
	v_pk_fma_f32 v[110:111], v[110:111], v[230:231], v[190:191] op_sel_hi:[1,0,1]
	v_pk_fma_f32 v[108:109], v[108:109], v[230:231], v[192:193] op_sel_hi:[1,0,1]
	v_exp_f32_e32 v110, v110
	v_exp_f32_e32 v111, v111
	v_exp_f32_e32 v108, v108
	v_exp_f32_e32 v109, v109
	v_pk_fma_f32 v[106:107], v[106:107], v[230:231], v[184:185] op_sel_hi:[1,0,1]
	v_pk_add_f32 v[110:111], v[110:111], 1.0 op_sel_hi:[1,0]
	v_exp_f32_e32 v106, v106
	v_exp_f32_e32 v107, v107
	v_pk_fma_f32 v[104:105], v[104:105], v[230:231], v[186:187] op_sel_hi:[1,0,1]
	v_pk_add_f32 v[108:109], v[108:109], 1.0 op_sel_hi:[1,0]
	v_rcp_f32_e32 v110, v110
	v_rcp_f32_e32 v111, v111
	v_exp_f32_e32 v104, v104
	v_exp_f32_e32 v105, v105
	v_rcp_f32_e32 v108, v108
	v_rcp_f32_e32 v109, v109
	v_pk_add_f32 v[106:107], v[106:107], 1.0 op_sel_hi:[1,0]
	v_pk_add_f32 v[104:105], v[104:105], 1.0 op_sel_hi:[1,0]
	v_rcp_f32_e32 v106, v106
	v_rcp_f32_e32 v107, v107
	v_rcp_f32_e32 v104, v104
	v_rcp_f32_e32 v105, v105
	v_pk_fma_f32 v[100:101], v[100:101], v[230:231], v[182:183] op_sel_hi:[1,0,1]
	v_pk_fma_f32 v[102:103], v[102:103], v[230:231], v[180:181] op_sel_hi:[1,0,1]
	v_exp_f32_e32 v100, v100
	v_exp_f32_e32 v101, v101
	v_exp_f32_e32 v102, v102
	v_exp_f32_e32 v103, v103
	v_pk_fma_f32 v[96:97], v[96:97], v[230:231], v[178:179] op_sel_hi:[1,0,1]
	v_pk_fma_f32 v[98:99], v[98:99], v[230:231], v[176:177] op_sel_hi:[1,0,1]
	v_pk_add_f32 v[100:101], v[100:101], 1.0 op_sel_hi:[1,0]
	v_pk_add_f32 v[102:103], v[102:103], 1.0 op_sel_hi:[1,0]
	v_exp_f32_e32 v96, v96
	v_exp_f32_e32 v97, v97
	v_exp_f32_e32 v98, v98
	v_exp_f32_e32 v99, v99
	v_rcp_f32_e32 v100, v100
	v_rcp_f32_e32 v101, v101
	v_rcp_f32_e32 v102, v102
	v_rcp_f32_e32 v103, v103
	v_pk_add_f32 v[96:97], v[96:97], 1.0 op_sel_hi:[1,0]
	v_pk_add_f32 v[98:99], v[98:99], 1.0 op_sel_hi:[1,0]
	v_rcp_f32_e32 v96, v96
	v_rcp_f32_e32 v97, v97
	v_rcp_f32_e32 v98, v98
	v_rcp_f32_e32 v99, v99
	v_pk_fma_f32 v[94:95], v[94:95], v[224:225], v[190:191] op_sel_hi:[1,0,1]
	v_pk_fma_f32 v[92:93], v[92:93], v[224:225], v[192:193] op_sel_hi:[1,0,1]
	v_exp_f32_e32 v94, v94
	v_exp_f32_e32 v95, v95
	v_exp_f32_e32 v92, v92
	v_exp_f32_e32 v93, v93
	v_pk_fma_f32 v[90:91], v[90:91], v[224:225], v[184:185] op_sel_hi:[1,0,1]
	v_pk_add_f32 v[94:95], v[94:95], 1.0 op_sel_hi:[1,0]
	v_exp_f32_e32 v90, v90
	v_exp_f32_e32 v91, v91
	v_pk_fma_f32 v[88:89], v[88:89], v[224:225], v[186:187] op_sel_hi:[1,0,1]
	v_pk_add_f32 v[92:93], v[92:93], 1.0 op_sel_hi:[1,0]
	v_rcp_f32_e32 v94, v94
	v_rcp_f32_e32 v95, v95
	s_waitcnt vmcnt(3)
	v_lshlrev_b32_e32 v246, 16, v152
	s_waitcnt vmcnt(2)
	v_lshlrev_b32_e32 v174, 16, v156
	v_and_b32_e32 v175, 0xffff0000, v156
	v_lshlrev_b32_e32 v156, 16, v157
	v_and_b32_e32 v157, 0xffff0000, v157
	v_pk_mul_f32 v[156:157], v[240:241], v[156:157] op_sel_hi:[0,1]
	v_and_b32_e32 v247, 0xffff0000, v152
	v_lshlrev_b32_e32 v152, 16, v153
	v_and_b32_e32 v153, 0xffff0000, v153
	v_pk_mul_f32 v[174:175], v[240:241], v[174:175] op_sel_hi:[0,1]
	v_pk_mul_f32 v[156:157], v[58:59], v[156:157]
	v_pk_mul_f32 v[174:175], v[56:57], v[174:175]
	v_pk_fma_f32 v[142:143], v[142:143], v[156:157], v[152:153]
	v_lshl_add_u64 v[152:153], s[36:37], 0, v[244:245]
	v_lshlrev_b32_e32 v156, 16, v159
	v_and_b32_e32 v157, 0xffff0000, v159
	v_pk_fma_f32 v[140:141], v[140:141], v[174:175], v[246:247]
	v_lshl_add_u64 v[152:153], v[152:153], 0, v[188:189]
	v_pk_mul_f32 v[156:157], v[240:241], v[156:157] op_sel_hi:[0,1]
	global_store_dwordx4 v[152:153], v[140:143], off nt
	v_pk_mul_f32 v[156:157], v[50:51], v[156:157]
	s_waitcnt vmcnt(1)
	v_lshlrev_b32_e32 v174, 16, v144
	v_lshlrev_b32_e32 v140, 16, v154
	v_and_b32_e32 v141, 0xffff0000, v154
	v_lshlrev_b32_e32 v142, 16, v158
	v_and_b32_e32 v143, 0xffff0000, v158
	v_lshlrev_b32_e32 v154, 16, v155
	v_and_b32_e32 v155, 0xffff0000, v155
	v_pk_mul_f32 v[142:143], v[240:241], v[142:143] op_sel_hi:[0,1]
	v_pk_fma_f32 v[138:139], v[138:139], v[156:157], v[154:155]
	v_add_co_u32_e32 v154, vcc, s53, v216
	v_pk_mul_f32 v[142:143], v[48:49], v[142:143]
	s_nop 0
	v_addc_co_u32_e32 v155, vcc, 0, v217, vcc
	v_pk_fma_f32 v[136:137], v[136:137], v[142:143], v[140:141]
	v_add_co_u32_e32 v156, vcc, s53, v218
	global_store_dwordx4 v[152:153], v[136:139], off offset:16 nt
	s_nop 0
	v_addc_co_u32_e32 v157, vcc, 0, v219, vcc
	global_load_dwordx4 v[136:139], v[154:155], off
	global_load_dwordx4 v[140:143], v[156:157], off
	v_and_b32_e32 v175, 0xffff0000, v144
	v_lshlrev_b32_e32 v144, 16, v145
	v_and_b32_e32 v145, 0xffff0000, v145
	v_pk_mul_f32 v[144:145], v[240:241], v[144:145] op_sel_hi:[0,1]
	v_pk_mul_f32 v[174:175], v[240:241], v[174:175] op_sel_hi:[0,1]
	v_lshlrev_b32_e32 v158, 16, v148
	v_and_b32_e32 v159, 0xffff0000, v148
	v_lshlrev_b32_e32 v148, 16, v149
	v_and_b32_e32 v149, 0xffff0000, v149
	v_pk_mul_f32 v[174:175], v[44:45], v[174:175]
	v_pk_mul_f32 v[144:145], v[46:47], v[144:145]
	v_pk_fma_f32 v[132:133], v[132:133], v[174:175], v[158:159]
	v_pk_fma_f32 v[134:135], v[134:135], v[144:145], v[148:149]
	global_store_dwordx4 v[152:153], v[132:135], off offset:512 nt
	v_lshlrev_b32_e32 v144, 16, v151
	v_and_b32_e32 v145, 0xffff0000, v151
	v_lshlrev_b32_e32 v134, 16, v146
	v_and_b32_e32 v135, 0xffff0000, v146
	v_lshlrev_b32_e32 v146, 16, v147
	v_and_b32_e32 v147, 0xffff0000, v147
	v_pk_mul_f32 v[146:147], v[240:241], v[146:147] op_sel_hi:[0,1]
	v_pk_mul_f32 v[134:135], v[240:241], v[134:135] op_sel_hi:[0,1]
	v_lshlrev_b32_e32 v132, 16, v150
	v_and_b32_e32 v133, 0xffff0000, v150
	v_pk_mul_f32 v[134:135], v[36:37], v[134:135]
	v_pk_mul_f32 v[146:147], v[38:39], v[146:147]
	v_pk_fma_f32 v[128:129], v[128:129], v[134:135], v[132:133]
	v_pk_fma_f32 v[130:131], v[130:131], v[146:147], v[144:145]
	global_store_dwordx4 v[152:153], v[128:131], off offset:528 nt
	global_load_dwordx4 v[132:135], v[154:155], off offset:256
	s_nop 0
	global_load_dwordx4 v[128:131], v[156:157], off offset:256
	v_lshlrev_b64 v[144:145], 12, v[238:239]
	v_exp_f32_e32 v88, v88
	v_exp_f32_e32 v89, v89
	v_rcp_f32_e32 v92, v92
	v_rcp_f32_e32 v93, v93
	v_pk_add_f32 v[90:91], v[90:91], 1.0 op_sel_hi:[1,0]
	v_pk_add_f32 v[88:89], v[88:89], 1.0 op_sel_hi:[1,0]
	v_rcp_f32_e32 v90, v90
	v_rcp_f32_e32 v91, v91
	v_rcp_f32_e32 v88, v88
	v_rcp_f32_e32 v89, v89
	v_pk_fma_f32 v[84:85], v[84:85], v[224:225], v[182:183] op_sel_hi:[1,0,1]
	v_pk_fma_f32 v[86:87], v[86:87], v[224:225], v[180:181] op_sel_hi:[1,0,1]
	v_exp_f32_e32 v84, v84
	v_exp_f32_e32 v85, v85
	v_exp_f32_e32 v86, v86
	v_exp_f32_e32 v87, v87
	v_pk_fma_f32 v[80:81], v[80:81], v[224:225], v[178:179] op_sel_hi:[1,0,1]
	v_pk_fma_f32 v[82:83], v[82:83], v[224:225], v[176:177] op_sel_hi:[1,0,1]
	v_pk_add_f32 v[84:85], v[84:85], 1.0 op_sel_hi:[1,0]
	v_pk_add_f32 v[86:87], v[86:87], 1.0 op_sel_hi:[1,0]
	v_exp_f32_e32 v80, v80
	v_exp_f32_e32 v81, v81
	v_exp_f32_e32 v82, v82
	v_exp_f32_e32 v83, v83
	v_rcp_f32_e32 v84, v84
	v_rcp_f32_e32 v85, v85
	v_rcp_f32_e32 v86, v86
	v_rcp_f32_e32 v87, v87
	v_pk_add_f32 v[80:81], v[80:81], 1.0 op_sel_hi:[1,0]
	v_pk_add_f32 v[82:83], v[82:83], 1.0 op_sel_hi:[1,0]
	v_rcp_f32_e32 v80, v80
	v_rcp_f32_e32 v81, v81
	v_rcp_f32_e32 v82, v82
	v_rcp_f32_e32 v83, v83
	v_pk_fma_f32 v[78:79], v[78:79], v[214:215], v[190:191] op_sel_hi:[1,0,1]
	v_pk_fma_f32 v[76:77], v[76:77], v[214:215], v[192:193] op_sel_hi:[1,0,1]
	v_exp_f32_e32 v78, v78
	v_exp_f32_e32 v79, v79
	v_exp_f32_e32 v76, v76
	v_exp_f32_e32 v77, v77
	v_pk_fma_f32 v[74:75], v[74:75], v[214:215], v[184:185] op_sel_hi:[1,0,1]
	v_pk_add_f32 v[78:79], v[78:79], 1.0 op_sel_hi:[1,0]
	v_exp_f32_e32 v74, v74
	v_exp_f32_e32 v75, v75
	v_pk_fma_f32 v[72:73], v[72:73], v[214:215], v[186:187] op_sel_hi:[1,0,1]
	s_waitcnt vmcnt(5)
	v_lshlrev_b32_e32 v146, 16, v136
	s_waitcnt vmcnt(4)
	v_lshlrev_b32_e32 v148, 16, v140
	v_and_b32_e32 v149, 0xffff0000, v140
	v_lshlrev_b32_e32 v140, 16, v141
	v_and_b32_e32 v141, 0xffff0000, v141
	v_pk_mul_f32 v[140:141], v[234:235], v[140:141] op_sel_hi:[0,1]
	v_and_b32_e32 v147, 0xffff0000, v136
	v_lshlrev_b32_e32 v136, 16, v137
	v_and_b32_e32 v137, 0xffff0000, v137
	v_pk_mul_f32 v[148:149], v[234:235], v[148:149] op_sel_hi:[0,1]
	v_pk_mul_f32 v[140:141], v[58:59], v[140:141]
	v_pk_mul_f32 v[148:149], v[56:57], v[148:149]
	v_pk_fma_f32 v[126:127], v[126:127], v[140:141], v[136:137]
	v_lshl_add_u64 v[136:137], s[36:37], 0, v[144:145]
	v_lshlrev_b32_e32 v140, 16, v143
	v_and_b32_e32 v141, 0xffff0000, v143
	v_pk_fma_f32 v[124:125], v[124:125], v[148:149], v[146:147]
	v_lshl_add_u64 v[136:137], v[136:137], 0, v[188:189]
	v_pk_mul_f32 v[140:141], v[234:235], v[140:141] op_sel_hi:[0,1]
	global_store_dwordx4 v[136:137], v[124:127], off nt
	v_pk_mul_f32 v[140:141], v[50:51], v[140:141]
	v_pk_add_f32 v[76:77], v[76:77], 1.0 op_sel_hi:[1,0]
	v_lshlrev_b32_e32 v124, 16, v138
	v_and_b32_e32 v125, 0xffff0000, v138
	v_lshlrev_b32_e32 v126, 16, v142
	v_and_b32_e32 v127, 0xffff0000, v142
	v_lshlrev_b32_e32 v138, 16, v139
	v_and_b32_e32 v139, 0xffff0000, v139
	v_pk_mul_f32 v[126:127], v[234:235], v[126:127] op_sel_hi:[0,1]
	v_pk_fma_f32 v[122:123], v[122:123], v[140:141], v[138:139]
	v_add_co_u32_e32 v138, vcc, s47, v216
	v_pk_mul_f32 v[126:127], v[48:49], v[126:127]
	s_nop 0
	v_addc_co_u32_e32 v139, vcc, 0, v217, vcc
	v_pk_fma_f32 v[120:121], v[120:121], v[126:127], v[124:125]
	v_add_co_u32_e32 v140, vcc, s47, v218
	global_store_dwordx4 v[136:137], v[120:123], off offset:16 nt
	s_nop 0
	v_addc_co_u32_e32 v141, vcc, 0, v219, vcc
	global_load_dwordx4 v[120:123], v[138:139], off
	global_load_dwordx4 v[124:127], v[140:141], off
	s_waitcnt vmcnt(4)
	v_lshlrev_b32_e32 v144, 16, v128
	v_and_b32_e32 v145, 0xffff0000, v128
	v_lshlrev_b32_e32 v128, 16, v129
	v_and_b32_e32 v129, 0xffff0000, v129
	v_pk_mul_f32 v[128:129], v[234:235], v[128:129] op_sel_hi:[0,1]
	v_pk_mul_f32 v[144:145], v[234:235], v[144:145] op_sel_hi:[0,1]
	v_lshlrev_b32_e32 v142, 16, v132
	v_and_b32_e32 v143, 0xffff0000, v132
	v_lshlrev_b32_e32 v132, 16, v133
	v_and_b32_e32 v133, 0xffff0000, v133
	v_pk_mul_f32 v[144:145], v[44:45], v[144:145]
	v_pk_mul_f32 v[128:129], v[46:47], v[128:129]
	v_pk_fma_f32 v[116:117], v[116:117], v[144:145], v[142:143]
	v_pk_fma_f32 v[118:119], v[118:119], v[128:129], v[132:133]
	global_store_dwordx4 v[136:137], v[116:119], off offset:512 nt
	v_lshlrev_b32_e32 v128, 16, v135
	v_and_b32_e32 v129, 0xffff0000, v135
	v_lshlrev_b32_e32 v118, 16, v130
	v_and_b32_e32 v119, 0xffff0000, v130
	v_lshlrev_b32_e32 v130, 16, v131
	v_and_b32_e32 v131, 0xffff0000, v131
	v_pk_mul_f32 v[130:131], v[234:235], v[130:131] op_sel_hi:[0,1]
	v_pk_mul_f32 v[118:119], v[234:235], v[118:119] op_sel_hi:[0,1]
	v_lshlrev_b32_e32 v116, 16, v134
	v_and_b32_e32 v117, 0xffff0000, v134
	v_pk_mul_f32 v[118:119], v[36:37], v[118:119]
	v_pk_mul_f32 v[130:131], v[38:39], v[130:131]
	v_pk_fma_f32 v[112:113], v[112:113], v[118:119], v[116:117]
	v_pk_fma_f32 v[114:115], v[114:115], v[130:131], v[128:129]
	global_store_dwordx4 v[136:137], v[112:115], off offset:528 nt
	global_load_dwordx4 v[116:119], v[138:139], off offset:256
	s_nop 0
	global_load_dwordx4 v[112:115], v[140:141], off offset:256
	v_lshlrev_b64 v[128:129], 12, v[232:233]
	v_rcp_f32_e32 v78, v78
	v_rcp_f32_e32 v79, v79
	v_exp_f32_e32 v72, v72
	v_exp_f32_e32 v73, v73
	v_rcp_f32_e32 v76, v76
	v_rcp_f32_e32 v77, v77
	v_pk_add_f32 v[74:75], v[74:75], 1.0 op_sel_hi:[1,0]
	v_pk_add_f32 v[72:73], v[72:73], 1.0 op_sel_hi:[1,0]
	v_rcp_f32_e32 v74, v74
	v_rcp_f32_e32 v75, v75
	v_pk_fma_f32 v[68:69], v[68:69], v[214:215], v[182:183] op_sel_hi:[1,0,1]
	v_pk_fma_f32 v[70:71], v[70:71], v[214:215], v[180:181] op_sel_hi:[1,0,1]
	v_rcp_f32_e32 v72, v72
	v_rcp_f32_e32 v73, v73
	v_exp_f32_e32 v68, v68
	v_exp_f32_e32 v69, v69
	v_exp_f32_e32 v70, v70
	v_exp_f32_e32 v71, v71
	v_pk_fma_f32 v[64:65], v[64:65], v[214:215], v[178:179] op_sel_hi:[1,0,1]
	v_pk_fma_f32 v[66:67], v[66:67], v[214:215], v[176:177] op_sel_hi:[1,0,1]
	v_pk_add_f32 v[68:69], v[68:69], 1.0 op_sel_hi:[1,0]
	v_pk_add_f32 v[70:71], v[70:71], 1.0 op_sel_hi:[1,0]
	v_exp_f32_e32 v64, v64
	v_exp_f32_e32 v65, v65
	v_exp_f32_e32 v66, v66
	v_exp_f32_e32 v67, v67
	v_rcp_f32_e32 v68, v68
	v_rcp_f32_e32 v69, v69
	v_rcp_f32_e32 v70, v70
	v_rcp_f32_e32 v71, v71
	v_pk_add_f32 v[64:65], v[64:65], 1.0 op_sel_hi:[1,0]
	v_pk_add_f32 v[66:67], v[66:67], 1.0 op_sel_hi:[1,0]
	v_rcp_f32_e32 v64, v64
	v_rcp_f32_e32 v65, v65
	v_rcp_f32_e32 v66, v66
	v_rcp_f32_e32 v67, v67
	v_pk_fma_f32 v[62:63], v[62:63], v[208:209], v[190:191] op_sel_hi:[1,0,1]
	v_pk_fma_f32 v[60:61], v[60:61], v[208:209], v[192:193] op_sel_hi:[1,0,1]
	v_exp_f32_e32 v62, v62
	v_exp_f32_e32 v63, v63
	v_exp_f32_e32 v60, v60
	v_exp_f32_e32 v61, v61
	v_pk_fma_f32 v[54:55], v[54:55], v[208:209], v[184:185] op_sel_hi:[1,0,1]
	v_pk_add_f32 v[62:63], v[62:63], 1.0 op_sel_hi:[1,0]
	s_waitcnt vmcnt(5)
	v_lshlrev_b32_e32 v130, 16, v120
	s_waitcnt vmcnt(4)
	v_lshlrev_b32_e32 v132, 16, v124
	v_and_b32_e32 v133, 0xffff0000, v124
	v_lshlrev_b32_e32 v124, 16, v125
	v_and_b32_e32 v125, 0xffff0000, v125
	v_pk_mul_f32 v[124:125], v[228:229], v[124:125] op_sel_hi:[0,1]
	v_and_b32_e32 v131, 0xffff0000, v120
	v_lshlrev_b32_e32 v120, 16, v121
	v_and_b32_e32 v121, 0xffff0000, v121
	v_pk_mul_f32 v[132:133], v[228:229], v[132:133] op_sel_hi:[0,1]
	v_pk_mul_f32 v[124:125], v[58:59], v[124:125]
	v_pk_mul_f32 v[132:133], v[56:57], v[132:133]
	v_pk_fma_f32 v[110:111], v[110:111], v[124:125], v[120:121]
	v_lshl_add_u64 v[120:121], s[36:37], 0, v[128:129]
	v_lshlrev_b32_e32 v124, 16, v127
	v_and_b32_e32 v125, 0xffff0000, v127
	v_pk_fma_f32 v[108:109], v[108:109], v[132:133], v[130:131]
	v_lshl_add_u64 v[120:121], v[120:121], 0, v[188:189]
	v_pk_mul_f32 v[124:125], v[228:229], v[124:125] op_sel_hi:[0,1]
	global_store_dwordx4 v[120:121], v[108:111], off nt
	v_pk_mul_f32 v[124:125], v[50:51], v[124:125]
	v_exp_f32_e32 v54, v54
	v_lshlrev_b32_e32 v108, 16, v122
	v_and_b32_e32 v109, 0xffff0000, v122
	v_lshlrev_b32_e32 v110, 16, v126
	v_and_b32_e32 v111, 0xffff0000, v126
	v_lshlrev_b32_e32 v122, 16, v123
	v_and_b32_e32 v123, 0xffff0000, v123
	v_pk_mul_f32 v[110:111], v[228:229], v[110:111] op_sel_hi:[0,1]
	v_pk_fma_f32 v[106:107], v[106:107], v[124:125], v[122:123]
	v_add_co_u32_e32 v122, vcc, s52, v216
	v_pk_mul_f32 v[110:111], v[48:49], v[110:111]
	s_nop 0
	v_addc_co_u32_e32 v123, vcc, 0, v217, vcc
	v_pk_fma_f32 v[104:105], v[104:105], v[110:111], v[108:109]
	v_add_co_u32_e32 v124, vcc, s52, v218
	global_store_dwordx4 v[120:121], v[104:107], off offset:16 nt
	s_nop 0
	v_addc_co_u32_e32 v125, vcc, 0, v219, vcc
	global_load_dwordx4 v[104:107], v[122:123], off
	global_load_dwordx4 v[108:111], v[124:125], off
	s_waitcnt vmcnt(4)
	v_lshlrev_b32_e32 v128, 16, v112
	v_and_b32_e32 v129, 0xffff0000, v112
	v_lshlrev_b32_e32 v112, 16, v113
	v_and_b32_e32 v113, 0xffff0000, v113
	v_pk_mul_f32 v[112:113], v[228:229], v[112:113] op_sel_hi:[0,1]
	v_pk_mul_f32 v[128:129], v[228:229], v[128:129] op_sel_hi:[0,1]
	v_lshlrev_b32_e32 v126, 16, v116
	v_and_b32_e32 v127, 0xffff0000, v116
	v_lshlrev_b32_e32 v116, 16, v117
	v_and_b32_e32 v117, 0xffff0000, v117
	v_pk_mul_f32 v[128:129], v[44:45], v[128:129]
	v_pk_mul_f32 v[112:113], v[46:47], v[112:113]
	v_pk_fma_f32 v[100:101], v[100:101], v[128:129], v[126:127]
	v_pk_fma_f32 v[102:103], v[102:103], v[112:113], v[116:117]
	global_store_dwordx4 v[120:121], v[100:103], off offset:512 nt
	v_lshlrev_b32_e32 v112, 16, v119
	v_and_b32_e32 v113, 0xffff0000, v119
	v_lshlrev_b32_e32 v102, 16, v114
	v_and_b32_e32 v103, 0xffff0000, v114
	v_lshlrev_b32_e32 v114, 16, v115
	v_and_b32_e32 v115, 0xffff0000, v115
	v_pk_mul_f32 v[114:115], v[228:229], v[114:115] op_sel_hi:[0,1]
	v_pk_mul_f32 v[102:103], v[228:229], v[102:103] op_sel_hi:[0,1]
	v_lshlrev_b32_e32 v100, 16, v118
	v_and_b32_e32 v101, 0xffff0000, v118
	v_pk_mul_f32 v[102:103], v[36:37], v[102:103]
	v_pk_mul_f32 v[114:115], v[38:39], v[114:115]
	v_pk_fma_f32 v[96:97], v[96:97], v[102:103], v[100:101]
	v_pk_fma_f32 v[98:99], v[98:99], v[114:115], v[112:113]
	global_store_dwordx4 v[120:121], v[96:99], off offset:528 nt
	global_load_dwordx4 v[100:103], v[122:123], off offset:256
	s_nop 0
	global_load_dwordx4 v[96:99], v[124:125], off offset:256
	v_lshlrev_b64 v[112:113], 12, v[226:227]
	v_exp_f32_e32 v55, v55
	v_pk_fma_f32 v[52:53], v[52:53], v[208:209], v[186:187] op_sel_hi:[1,0,1]
	v_pk_add_f32 v[60:61], v[60:61], 1.0 op_sel_hi:[1,0]
	v_rcp_f32_e32 v62, v62
	v_rcp_f32_e32 v63, v63
	v_exp_f32_e32 v52, v52
	v_exp_f32_e32 v53, v53
	v_rcp_f32_e32 v60, v60
	v_rcp_f32_e32 v61, v61
	v_pk_add_f32 v[54:55], v[54:55], 1.0 op_sel_hi:[1,0]
	v_pk_fma_f32 v[40:41], v[40:41], v[208:209], v[182:183] op_sel_hi:[1,0,1]
	v_rcp_f32_e32 v54, v54
	v_rcp_f32_e32 v55, v55
	v_pk_fma_f32 v[42:43], v[42:43], v[208:209], v[180:181] op_sel_hi:[1,0,1]
	v_pk_add_f32 v[52:53], v[52:53], 1.0 op_sel_hi:[1,0]
	v_exp_f32_e32 v40, v40
	v_exp_f32_e32 v41, v41
	v_exp_f32_e32 v42, v42
	v_exp_f32_e32 v43, v43
	v_rcp_f32_e32 v52, v52
	v_rcp_f32_e32 v53, v53
	v_pk_fma_f32 v[32:33], v[32:33], v[208:209], v[178:179] op_sel_hi:[1,0,1]
	v_pk_fma_f32 v[34:35], v[34:35], v[208:209], v[176:177] op_sel_hi:[1,0,1]
	v_pk_add_f32 v[40:41], v[40:41], 1.0 op_sel_hi:[1,0]
	v_pk_add_f32 v[42:43], v[42:43], 1.0 op_sel_hi:[1,0]
	v_exp_f32_e32 v32, v32
	v_exp_f32_e32 v33, v33
	v_exp_f32_e32 v34, v34
	v_exp_f32_e32 v35, v35
	v_rcp_f32_e32 v40, v40
	v_rcp_f32_e32 v41, v41
	v_rcp_f32_e32 v42, v42
	v_rcp_f32_e32 v43, v43
	v_pk_add_f32 v[32:33], v[32:33], 1.0 op_sel_hi:[1,0]
	v_pk_add_f32 v[34:35], v[34:35], 1.0 op_sel_hi:[1,0]
	v_rcp_f32_e32 v32, v32
	v_rcp_f32_e32 v33, v33
	v_rcp_f32_e32 v34, v34
	v_rcp_f32_e32 v35, v35
	v_pk_fma_f32 v[30:31], v[30:31], v[202:203], v[190:191] op_sel_hi:[1,0,1]
	v_pk_fma_f32 v[28:29], v[28:29], v[202:203], v[192:193] op_sel_hi:[1,0,1]
	v_exp_f32_e32 v30, v30
	v_exp_f32_e32 v31, v31
	v_exp_f32_e32 v28, v28
	s_waitcnt vmcnt(5)
	v_lshlrev_b32_e32 v114, 16, v104
	s_waitcnt vmcnt(4)
	v_lshlrev_b32_e32 v116, 16, v108
	v_and_b32_e32 v117, 0xffff0000, v108
	v_lshlrev_b32_e32 v108, 16, v109
	v_and_b32_e32 v109, 0xffff0000, v109
	v_pk_mul_f32 v[108:109], v[222:223], v[108:109] op_sel_hi:[0,1]
	v_and_b32_e32 v115, 0xffff0000, v104
	v_lshlrev_b32_e32 v104, 16, v105
	v_and_b32_e32 v105, 0xffff0000, v105
	v_pk_mul_f32 v[116:117], v[222:223], v[116:117] op_sel_hi:[0,1]
	v_pk_mul_f32 v[108:109], v[58:59], v[108:109]
	v_pk_mul_f32 v[116:117], v[56:57], v[116:117]
	v_pk_fma_f32 v[94:95], v[94:95], v[108:109], v[104:105]
	v_lshl_add_u64 v[104:105], s[36:37], 0, v[112:113]
	v_lshlrev_b32_e32 v108, 16, v111
	v_and_b32_e32 v109, 0xffff0000, v111
	v_pk_fma_f32 v[92:93], v[92:93], v[116:117], v[114:115]
	v_lshl_add_u64 v[104:105], v[104:105], 0, v[188:189]
	v_pk_mul_f32 v[108:109], v[222:223], v[108:109] op_sel_hi:[0,1]
	global_store_dwordx4 v[104:105], v[92:95], off nt
	v_pk_mul_f32 v[108:109], v[50:51], v[108:109]
	v_exp_f32_e32 v29, v29
	v_lshlrev_b32_e32 v92, 16, v106
	v_and_b32_e32 v93, 0xffff0000, v106
	v_lshlrev_b32_e32 v94, 16, v110
	v_and_b32_e32 v95, 0xffff0000, v110
	v_lshlrev_b32_e32 v106, 16, v107
	v_and_b32_e32 v107, 0xffff0000, v107
	v_pk_mul_f32 v[94:95], v[222:223], v[94:95] op_sel_hi:[0,1]
	v_pk_fma_f32 v[90:91], v[90:91], v[108:109], v[106:107]
	v_add_co_u32_e32 v106, vcc, s57, v216
	v_pk_mul_f32 v[94:95], v[48:49], v[94:95]
	s_nop 0
	v_addc_co_u32_e32 v107, vcc, 0, v217, vcc
	v_pk_fma_f32 v[88:89], v[88:89], v[94:95], v[92:93]
	v_add_co_u32_e32 v108, vcc, s57, v218
	global_store_dwordx4 v[104:105], v[88:91], off offset:16 nt
	s_nop 0
	v_addc_co_u32_e32 v109, vcc, 0, v219, vcc
	global_load_dwordx4 v[88:91], v[106:107], off
	global_load_dwordx4 v[92:95], v[108:109], off
	s_waitcnt vmcnt(4)
	v_lshlrev_b32_e32 v112, 16, v96
	v_and_b32_e32 v113, 0xffff0000, v96
	v_lshlrev_b32_e32 v96, 16, v97
	v_and_b32_e32 v97, 0xffff0000, v97
	v_pk_mul_f32 v[96:97], v[222:223], v[96:97] op_sel_hi:[0,1]
	v_pk_mul_f32 v[112:113], v[222:223], v[112:113] op_sel_hi:[0,1]
	v_lshlrev_b32_e32 v110, 16, v100
	v_and_b32_e32 v111, 0xffff0000, v100
	v_lshlrev_b32_e32 v100, 16, v101
	v_and_b32_e32 v101, 0xffff0000, v101
	v_pk_mul_f32 v[112:113], v[44:45], v[112:113]
	v_pk_mul_f32 v[96:97], v[46:47], v[96:97]
	v_pk_fma_f32 v[84:85], v[84:85], v[112:113], v[110:111]
	v_pk_fma_f32 v[86:87], v[86:87], v[96:97], v[100:101]
	global_store_dwordx4 v[104:105], v[84:87], off offset:512 nt
	v_lshlrev_b32_e32 v96, 16, v103
	v_and_b32_e32 v97, 0xffff0000, v103
	v_lshlrev_b32_e32 v86, 16, v98
	v_and_b32_e32 v87, 0xffff0000, v98
	v_lshlrev_b32_e32 v98, 16, v99
	v_and_b32_e32 v99, 0xffff0000, v99
	v_pk_mul_f32 v[98:99], v[222:223], v[98:99] op_sel_hi:[0,1]
	v_pk_mul_f32 v[86:87], v[222:223], v[86:87] op_sel_hi:[0,1]
	v_lshlrev_b32_e32 v84, 16, v102
	v_and_b32_e32 v85, 0xffff0000, v102
	v_pk_mul_f32 v[86:87], v[36:37], v[86:87]
	v_pk_mul_f32 v[98:99], v[38:39], v[98:99]
	v_pk_fma_f32 v[80:81], v[80:81], v[86:87], v[84:85]
	v_pk_fma_f32 v[82:83], v[82:83], v[98:99], v[96:97]
	global_store_dwordx4 v[104:105], v[80:83], off offset:528 nt
	global_load_dwordx4 v[84:87], v[106:107], off offset:256
	s_nop 0
	global_load_dwordx4 v[80:83], v[108:109], off offset:256
	v_lshlrev_b64 v[96:97], 12, v[220:221]
	v_pk_fma_f32 v[26:27], v[26:27], v[202:203], v[184:185] op_sel_hi:[1,0,1]
	v_pk_add_f32 v[30:31], v[30:31], 1.0 op_sel_hi:[1,0]
	v_exp_f32_e32 v26, v26
	v_exp_f32_e32 v27, v27
	v_pk_fma_f32 v[24:25], v[24:25], v[202:203], v[186:187] op_sel_hi:[1,0,1]
	v_pk_add_f32 v[28:29], v[28:29], 1.0 op_sel_hi:[1,0]
	v_rcp_f32_e32 v30, v30
	v_rcp_f32_e32 v31, v31
	v_exp_f32_e32 v24, v24
	v_exp_f32_e32 v25, v25
	v_rcp_f32_e32 v28, v28
	v_rcp_f32_e32 v29, v29
	v_pk_add_f32 v[26:27], v[26:27], 1.0 op_sel_hi:[1,0]
	v_pk_fma_f32 v[20:21], v[20:21], v[202:203], v[182:183] op_sel_hi:[1,0,1]
	v_pk_fma_f32 v[22:23], v[22:23], v[202:203], v[180:181] op_sel_hi:[1,0,1]
	v_rcp_f32_e32 v26, v26
	v_rcp_f32_e32 v27, v27
	v_exp_f32_e32 v20, v20
	v_exp_f32_e32 v21, v21
	v_exp_f32_e32 v22, v22
	v_exp_f32_e32 v23, v23
	v_pk_add_f32 v[24:25], v[24:25], 1.0 op_sel_hi:[1,0]
	v_pk_fma_f32 v[16:17], v[16:17], v[202:203], v[178:179] op_sel_hi:[1,0,1]
	v_rcp_f32_e32 v24, v24
	v_rcp_f32_e32 v25, v25
	v_pk_fma_f32 v[18:19], v[18:19], v[202:203], v[176:177] op_sel_hi:[1,0,1]
	v_pk_add_f32 v[20:21], v[20:21], 1.0 op_sel_hi:[1,0]
	v_pk_add_f32 v[22:23], v[22:23], 1.0 op_sel_hi:[1,0]
	v_exp_f32_e32 v16, v16
	v_exp_f32_e32 v17, v17
	v_exp_f32_e32 v18, v18
	v_exp_f32_e32 v19, v19
	v_rcp_f32_e32 v20, v20
	v_rcp_f32_e32 v21, v21
	v_rcp_f32_e32 v22, v22
	v_rcp_f32_e32 v23, v23
	v_pk_add_f32 v[16:17], v[16:17], 1.0 op_sel_hi:[1,0]
	v_pk_add_f32 v[18:19], v[18:19], 1.0 op_sel_hi:[1,0]
	v_rcp_f32_e32 v16, v16
	v_rcp_f32_e32 v17, v17
	v_rcp_f32_e32 v18, v18
	v_rcp_f32_e32 v19, v19
	v_pk_fma_f32 v[14:15], v[14:15], v[172:173], v[190:191] op_sel_hi:[1,0,1]
	v_pk_fma_f32 v[12:13], v[12:13], v[172:173], v[192:193] op_sel_hi:[1,0,1]
	s_waitcnt vmcnt(5)
	v_lshlrev_b32_e32 v98, 16, v88
	s_waitcnt vmcnt(4)
	v_lshlrev_b32_e32 v100, 16, v92
	v_and_b32_e32 v101, 0xffff0000, v92
	v_lshlrev_b32_e32 v92, 16, v93
	v_and_b32_e32 v93, 0xffff0000, v93
	v_pk_mul_f32 v[92:93], v[212:213], v[92:93] op_sel_hi:[0,1]
	v_and_b32_e32 v99, 0xffff0000, v88
	v_lshlrev_b32_e32 v88, 16, v89
	v_and_b32_e32 v89, 0xffff0000, v89
	v_pk_mul_f32 v[100:101], v[212:213], v[100:101] op_sel_hi:[0,1]
	v_pk_mul_f32 v[92:93], v[58:59], v[92:93]
	v_pk_mul_f32 v[100:101], v[56:57], v[100:101]
	v_pk_fma_f32 v[78:79], v[78:79], v[92:93], v[88:89]
	v_lshl_add_u64 v[88:89], s[36:37], 0, v[96:97]
	v_lshlrev_b32_e32 v92, 16, v95
	v_and_b32_e32 v93, 0xffff0000, v95
	v_pk_fma_f32 v[76:77], v[76:77], v[100:101], v[98:99]
	v_lshl_add_u64 v[88:89], v[88:89], 0, v[188:189]
	v_pk_mul_f32 v[92:93], v[212:213], v[92:93] op_sel_hi:[0,1]
	global_store_dwordx4 v[88:89], v[76:79], off nt
	v_pk_mul_f32 v[92:93], v[50:51], v[92:93]
	v_exp_f32_e32 v14, v14
	v_lshlrev_b32_e32 v76, 16, v90
	v_and_b32_e32 v77, 0xffff0000, v90
	v_lshlrev_b32_e32 v78, 16, v94
	v_and_b32_e32 v79, 0xffff0000, v94
	v_lshlrev_b32_e32 v90, 16, v91
	v_and_b32_e32 v91, 0xffff0000, v91
	v_pk_mul_f32 v[78:79], v[212:213], v[78:79] op_sel_hi:[0,1]
	v_pk_fma_f32 v[74:75], v[74:75], v[92:93], v[90:91]
	v_add_co_u32_e32 v90, vcc, s58, v216
	v_pk_mul_f32 v[78:79], v[48:49], v[78:79]
	s_nop 0
	v_addc_co_u32_e32 v91, vcc, 0, v217, vcc
	v_pk_fma_f32 v[72:73], v[72:73], v[78:79], v[76:77]
	v_add_co_u32_e32 v92, vcc, s58, v218
	global_store_dwordx4 v[88:89], v[72:75], off offset:16 nt
	s_nop 0
	v_addc_co_u32_e32 v93, vcc, 0, v219, vcc
	global_load_dwordx4 v[72:75], v[90:91], off
	global_load_dwordx4 v[76:79], v[92:93], off
	s_waitcnt vmcnt(4)
	v_lshlrev_b32_e32 v96, 16, v80
	v_and_b32_e32 v97, 0xffff0000, v80
	v_lshlrev_b32_e32 v80, 16, v81
	v_and_b32_e32 v81, 0xffff0000, v81
	v_pk_mul_f32 v[80:81], v[212:213], v[80:81] op_sel_hi:[0,1]
	v_pk_mul_f32 v[96:97], v[212:213], v[96:97] op_sel_hi:[0,1]
	v_lshlrev_b32_e32 v94, 16, v84
	v_and_b32_e32 v95, 0xffff0000, v84
	v_lshlrev_b32_e32 v84, 16, v85
	v_and_b32_e32 v85, 0xffff0000, v85
	v_pk_mul_f32 v[96:97], v[44:45], v[96:97]
	v_pk_mul_f32 v[80:81], v[46:47], v[80:81]
	v_pk_fma_f32 v[68:69], v[68:69], v[96:97], v[94:95]
	v_pk_fma_f32 v[70:71], v[70:71], v[80:81], v[84:85]
	global_store_dwordx4 v[88:89], v[68:71], off offset:512 nt
	v_lshlrev_b32_e32 v80, 16, v87
	v_and_b32_e32 v81, 0xffff0000, v87
	v_lshlrev_b32_e32 v70, 16, v82
	v_and_b32_e32 v71, 0xffff0000, v82
	v_lshlrev_b32_e32 v82, 16, v83
	v_and_b32_e32 v83, 0xffff0000, v83
	v_pk_mul_f32 v[82:83], v[212:213], v[82:83] op_sel_hi:[0,1]
	v_pk_mul_f32 v[70:71], v[212:213], v[70:71] op_sel_hi:[0,1]
	v_lshlrev_b32_e32 v68, 16, v86
	v_and_b32_e32 v69, 0xffff0000, v86
	v_pk_mul_f32 v[70:71], v[36:37], v[70:71]
	v_pk_mul_f32 v[82:83], v[38:39], v[82:83]
	v_pk_fma_f32 v[64:65], v[64:65], v[70:71], v[68:69]
	v_pk_fma_f32 v[66:67], v[66:67], v[82:83], v[80:81]
	global_store_dwordx4 v[88:89], v[64:67], off offset:528 nt
	global_load_dwordx4 v[64:67], v[90:91], off offset:256
	s_nop 0
	global_load_dwordx4 v[68:71], v[92:93], off offset:256
	v_lshlrev_b64 v[80:81], 12, v[210:211]
	v_exp_f32_e32 v15, v15
	v_exp_f32_e32 v12, v12
	v_exp_f32_e32 v13, v13
	v_pk_fma_f32 v[8:9], v[8:9], v[172:173], v[186:187] op_sel_hi:[1,0,1]
	v_pk_fma_f32 v[10:11], v[10:11], v[172:173], v[184:185] op_sel_hi:[1,0,1]
	v_exp_f32_e32 v8, v8
	v_exp_f32_e32 v9, v9
	v_exp_f32_e32 v10, v10
	v_exp_f32_e32 v11, v11
	v_pk_add_f32 v[14:15], v[14:15], 1.0 op_sel_hi:[1,0]
	v_pk_add_f32 v[12:13], v[12:13], 1.0 op_sel_hi:[1,0]
	v_rcp_f32_e32 v14, v14
	v_rcp_f32_e32 v15, v15
	v_pk_fma_f32 v[4:5], v[4:5], v[172:173], v[182:183] op_sel_hi:[1,0,1]
	v_pk_fma_f32 v[6:7], v[6:7], v[172:173], v[180:181] op_sel_hi:[1,0,1]
	v_rcp_f32_e32 v12, v12
	v_rcp_f32_e32 v13, v13
	v_pk_add_f32 v[8:9], v[8:9], 1.0 op_sel_hi:[1,0]
	v_pk_add_f32 v[10:11], v[10:11], 1.0 op_sel_hi:[1,0]
	v_exp_f32_e32 v4, v4
	v_exp_f32_e32 v5, v5
	v_exp_f32_e32 v6, v6
	v_exp_f32_e32 v7, v7
	v_rcp_f32_e32 v8, v8
	v_rcp_f32_e32 v9, v9
	v_rcp_f32_e32 v10, v10
	v_rcp_f32_e32 v11, v11
	v_pk_fma_f32 v[0:1], v[0:1], v[172:173], v[178:179] op_sel_hi:[1,0,1]
	v_pk_fma_f32 v[2:3], v[2:3], v[172:173], v[176:177] op_sel_hi:[1,0,1]
	v_pk_add_f32 v[4:5], v[4:5], 1.0 op_sel_hi:[1,0]
	v_pk_add_f32 v[6:7], v[6:7], 1.0 op_sel_hi:[1,0]
	v_exp_f32_e32 v0, v0
	v_exp_f32_e32 v1, v1
	v_exp_f32_e32 v2, v2
	v_exp_f32_e32 v3, v3
	v_rcp_f32_e32 v4, v4
	v_rcp_f32_e32 v5, v5
	v_rcp_f32_e32 v6, v6
	v_rcp_f32_e32 v7, v7
	v_pk_add_f32 v[0:1], v[0:1], 1.0 op_sel_hi:[1,0]
	v_pk_add_f32 v[2:3], v[2:3], 1.0 op_sel_hi:[1,0]
	v_rcp_f32_e32 v0, v0
	v_rcp_f32_e32 v1, v1
	v_rcp_f32_e32 v2, v2
	s_waitcnt vmcnt(5)
	v_lshlrev_b32_e32 v82, 16, v72
	s_waitcnt vmcnt(4)
	v_lshlrev_b32_e32 v84, 16, v76
	v_and_b32_e32 v85, 0xffff0000, v76
	v_lshlrev_b32_e32 v76, 16, v77
	v_and_b32_e32 v77, 0xffff0000, v77
	v_pk_mul_f32 v[76:77], v[206:207], v[76:77] op_sel_hi:[0,1]
	v_and_b32_e32 v83, 0xffff0000, v72
	v_lshlrev_b32_e32 v72, 16, v73
	v_and_b32_e32 v73, 0xffff0000, v73
	v_pk_mul_f32 v[84:85], v[206:207], v[84:85] op_sel_hi:[0,1]
	v_pk_mul_f32 v[76:77], v[58:59], v[76:77]
	v_pk_mul_f32 v[84:85], v[56:57], v[84:85]
	v_pk_fma_f32 v[62:63], v[62:63], v[76:77], v[72:73]
	v_lshl_add_u64 v[72:73], s[36:37], 0, v[80:81]
	v_lshlrev_b32_e32 v76, 16, v79
	v_and_b32_e32 v77, 0xffff0000, v79
	v_pk_fma_f32 v[60:61], v[60:61], v[84:85], v[82:83]
	v_lshl_add_u64 v[72:73], v[72:73], 0, v[188:189]
	v_pk_mul_f32 v[76:77], v[206:207], v[76:77] op_sel_hi:[0,1]
	global_store_dwordx4 v[72:73], v[60:63], off nt
	v_pk_mul_f32 v[76:77], v[50:51], v[76:77]
	v_rcp_f32_e32 v3, v3
	v_lshlrev_b32_e32 v60, 16, v74
	v_and_b32_e32 v61, 0xffff0000, v74
	v_lshlrev_b32_e32 v62, 16, v78
	v_and_b32_e32 v63, 0xffff0000, v78
	v_lshlrev_b32_e32 v74, 16, v75
	v_and_b32_e32 v75, 0xffff0000, v75
	v_pk_mul_f32 v[62:63], v[206:207], v[62:63] op_sel_hi:[0,1]
	v_pk_fma_f32 v[54:55], v[54:55], v[76:77], v[74:75]
	v_add_co_u32_e32 v74, vcc, s59, v216
	v_pk_mul_f32 v[62:63], v[48:49], v[62:63]
	s_nop 0
	v_addc_co_u32_e32 v75, vcc, 0, v217, vcc
	v_pk_fma_f32 v[52:53], v[52:53], v[62:63], v[60:61]
	v_add_co_u32_e32 v76, vcc, s59, v218
	global_store_dwordx4 v[72:73], v[52:55], off offset:16 nt
	s_nop 0
	v_addc_co_u32_e32 v77, vcc, 0, v219, vcc
	s_waitcnt vmcnt(2)
	v_lshlrev_b32_e32 v80, 16, v68
	v_and_b32_e32 v81, 0xffff0000, v68
	v_lshlrev_b32_e32 v68, 16, v69
	v_and_b32_e32 v69, 0xffff0000, v69
	global_load_dwordx4 v[52:55], v[74:75], off
	global_load_dwordx4 v[60:63], v[76:77], off
	v_pk_mul_f32 v[68:69], v[206:207], v[68:69] op_sel_hi:[0,1]
	v_pk_mul_f32 v[80:81], v[206:207], v[80:81] op_sel_hi:[0,1]
	v_lshlrev_b32_e32 v78, 16, v64
	v_and_b32_e32 v79, 0xffff0000, v64
	v_lshlrev_b32_e32 v64, 16, v65
	v_and_b32_e32 v65, 0xffff0000, v65
	v_pk_mul_f32 v[80:81], v[44:45], v[80:81]
	v_pk_mul_f32 v[68:69], v[46:47], v[68:69]
	v_pk_fma_f32 v[40:41], v[40:41], v[80:81], v[78:79]
	v_pk_fma_f32 v[42:43], v[42:43], v[68:69], v[64:65]
	global_store_dwordx4 v[72:73], v[40:43], off offset:512 nt
	v_lshlrev_b32_e32 v64, 16, v67
	v_and_b32_e32 v65, 0xffff0000, v67
	v_lshlrev_b32_e32 v40, 16, v66
	v_and_b32_e32 v41, 0xffff0000, v66
	v_lshlrev_b32_e32 v42, 16, v70
	v_and_b32_e32 v43, 0xffff0000, v70
	v_lshlrev_b32_e32 v66, 16, v71
	v_and_b32_e32 v67, 0xffff0000, v71
	v_pk_mul_f32 v[66:67], v[206:207], v[66:67] op_sel_hi:[0,1]
	v_pk_mul_f32 v[42:43], v[206:207], v[42:43] op_sel_hi:[0,1]
	v_pk_mul_f32 v[42:43], v[36:37], v[42:43]
	v_pk_mul_f32 v[66:67], v[38:39], v[66:67]
	v_pk_fma_f32 v[32:33], v[32:33], v[42:43], v[40:41]
	v_pk_fma_f32 v[34:35], v[34:35], v[66:67], v[64:65]
	global_store_dwordx4 v[72:73], v[32:35], off offset:528 nt
	global_load_dwordx4 v[32:35], v[74:75], off offset:256
	s_nop 0
	global_load_dwordx4 v[40:43], v[76:77], off offset:256
	v_lshlrev_b64 v[64:65], 12, v[204:205]
	s_waitcnt vmcnt(5)
	v_lshlrev_b32_e32 v66, 16, v52
	s_waitcnt vmcnt(4)
	v_lshlrev_b32_e32 v68, 16, v60
	v_and_b32_e32 v69, 0xffff0000, v60
	v_lshlrev_b32_e32 v60, 16, v61
	v_and_b32_e32 v61, 0xffff0000, v61
	v_pk_mul_f32 v[60:61], v[200:201], v[60:61] op_sel_hi:[0,1]
	v_and_b32_e32 v67, 0xffff0000, v52
	v_lshlrev_b32_e32 v52, 16, v53
	v_and_b32_e32 v53, 0xffff0000, v53
	v_pk_mul_f32 v[68:69], v[200:201], v[68:69] op_sel_hi:[0,1]
	v_pk_mul_f32 v[60:61], v[58:59], v[60:61]
	v_pk_mul_f32 v[68:69], v[56:57], v[68:69]
	v_pk_fma_f32 v[30:31], v[30:31], v[60:61], v[52:53]
	v_lshl_add_u64 v[52:53], s[36:37], 0, v[64:65]
	v_lshlrev_b32_e32 v60, 16, v63
	v_and_b32_e32 v61, 0xffff0000, v63
	v_pk_fma_f32 v[28:29], v[28:29], v[68:69], v[66:67]
	v_lshl_add_u64 v[52:53], v[52:53], 0, v[188:189]
	v_pk_mul_f32 v[60:61], v[200:201], v[60:61] op_sel_hi:[0,1]
	global_store_dwordx4 v[52:53], v[28:31], off nt
	v_pk_mul_f32 v[60:61], v[50:51], v[60:61]
	s_waitcnt vmcnt(2)
	v_and_b32_e32 v63, 0xffff0000, v32
	v_lshlrev_b32_e32 v28, 16, v54
	v_and_b32_e32 v29, 0xffff0000, v54
	v_lshlrev_b32_e32 v30, 16, v62
	v_and_b32_e32 v31, 0xffff0000, v62
	v_lshlrev_b32_e32 v54, 16, v55
	v_and_b32_e32 v55, 0xffff0000, v55
	v_pk_mul_f32 v[30:31], v[200:201], v[30:31] op_sel_hi:[0,1]
	v_pk_fma_f32 v[26:27], v[26:27], v[60:61], v[54:55]
	v_add_co_u32_e32 v54, vcc, s60, v216
	v_pk_mul_f32 v[30:31], v[48:49], v[30:31]
	s_nop 0
	v_addc_co_u32_e32 v55, vcc, 0, v217, vcc
	v_pk_fma_f32 v[24:25], v[24:25], v[30:31], v[28:29]
	v_add_co_u32_e32 v60, vcc, s60, v218
	s_waitcnt vmcnt(1)
	v_lshlrev_b32_e32 v64, 16, v40
	v_and_b32_e32 v65, 0xffff0000, v40
	v_lshlrev_b32_e32 v40, 16, v41
	v_and_b32_e32 v41, 0xffff0000, v41
	global_store_dwordx4 v[52:53], v[24:27], off offset:16 nt
	v_addc_co_u32_e32 v61, vcc, 0, v219, vcc
	v_pk_mul_f32 v[40:41], v[200:201], v[40:41] op_sel_hi:[0,1]
	v_pk_mul_f32 v[64:65], v[200:201], v[64:65] op_sel_hi:[0,1]
	global_load_dwordx4 v[24:27], v[54:55], off
	global_load_dwordx4 v[28:31], v[60:61], off
	v_lshlrev_b32_e32 v62, 16, v32
	v_lshlrev_b32_e32 v32, 16, v33
	v_and_b32_e32 v33, 0xffff0000, v33
	v_pk_mul_f32 v[64:65], v[44:45], v[64:65]
	v_pk_mul_f32 v[40:41], v[46:47], v[40:41]
	v_pk_fma_f32 v[20:21], v[20:21], v[64:65], v[62:63]
	v_pk_fma_f32 v[22:23], v[22:23], v[40:41], v[32:33]
	global_store_dwordx4 v[52:53], v[20:23], off offset:512 nt
	v_lshlrev_b32_e32 v32, 16, v35
	v_and_b32_e32 v33, 0xffff0000, v35
	v_lshlrev_b32_e32 v20, 16, v34
	v_and_b32_e32 v21, 0xffff0000, v34
	v_lshlrev_b32_e32 v22, 16, v42
	v_and_b32_e32 v23, 0xffff0000, v42
	v_lshlrev_b32_e32 v34, 16, v43
	v_and_b32_e32 v35, 0xffff0000, v43
	v_pk_mul_f32 v[34:35], v[200:201], v[34:35] op_sel_hi:[0,1]
	v_pk_mul_f32 v[22:23], v[200:201], v[22:23] op_sel_hi:[0,1]
	v_pk_mul_f32 v[22:23], v[36:37], v[22:23]
	v_pk_mul_f32 v[34:35], v[38:39], v[34:35]
	v_pk_fma_f32 v[16:17], v[16:17], v[22:23], v[20:21]
	v_pk_fma_f32 v[18:19], v[18:19], v[34:35], v[32:33]
	global_store_dwordx4 v[52:53], v[16:19], off offset:528 nt
	global_load_dwordx4 v[16:19], v[54:55], off offset:256
	s_nop 0
	global_load_dwordx4 v[20:23], v[60:61], off offset:256
	v_lshlrev_b64 v[40:41], 12, v[198:199]
	s_and_b64 vcc, exec, s[0:1]
	s_waitcnt vmcnt(5)
	v_lshlrev_b32_e32 v32, 16, v24
	s_waitcnt vmcnt(4)
	v_lshlrev_b32_e32 v34, 16, v28
	v_and_b32_e32 v35, 0xffff0000, v28
	v_lshlrev_b32_e32 v28, 16, v29
	v_and_b32_e32 v29, 0xffff0000, v29
	v_pk_mul_f32 v[28:29], v[194:195], v[28:29] op_sel_hi:[0,1]
	v_and_b32_e32 v33, 0xffff0000, v24
	v_lshlrev_b32_e32 v24, 16, v25
	v_and_b32_e32 v25, 0xffff0000, v25
	v_pk_mul_f32 v[34:35], v[194:195], v[34:35] op_sel_hi:[0,1]
	v_pk_mul_f32 v[28:29], v[58:59], v[28:29]
	v_pk_mul_f32 v[42:43], v[56:57], v[34:35]
	v_pk_fma_f32 v[34:35], v[14:15], v[28:29], v[24:25]
	v_lshlrev_b32_e32 v24, 16, v30
	v_and_b32_e32 v25, 0xffff0000, v30
	v_lshlrev_b32_e32 v28, 16, v31
	v_and_b32_e32 v29, 0xffff0000, v31
	v_pk_mul_f32 v[28:29], v[194:195], v[28:29] op_sel_hi:[0,1]
	v_pk_mul_f32 v[24:25], v[194:195], v[24:25] op_sel_hi:[0,1]
	v_pk_fma_f32 v[32:33], v[12:13], v[42:43], v[32:33]
	v_lshl_add_u64 v[12:13], s[36:37], 0, v[40:41]
	v_lshlrev_b32_e32 v14, 16, v26
	v_and_b32_e32 v15, 0xffff0000, v26
	v_lshlrev_b32_e32 v26, 16, v27
	v_and_b32_e32 v27, 0xffff0000, v27
	v_pk_mul_f32 v[24:25], v[48:49], v[24:25]
	v_pk_mul_f32 v[28:29], v[50:51], v[28:29]
	v_lshl_add_u64 v[12:13], v[12:13], 0, v[188:189]
	v_pk_fma_f32 v[10:11], v[10:11], v[28:29], v[26:27]
	v_pk_fma_f32 v[8:9], v[8:9], v[24:25], v[14:15]
	global_store_dwordx4 v[12:13], v[8:11], off offset:16 nt
	s_waitcnt vmcnt(2)
	v_lshlrev_b32_e32 v14, 16, v17
	v_and_b32_e32 v15, 0xffff0000, v17
	v_lshlrev_b32_e32 v8, 16, v16
	v_and_b32_e32 v9, 0xffff0000, v16
	s_waitcnt vmcnt(1)
	v_lshlrev_b32_e32 v10, 16, v20
	v_and_b32_e32 v11, 0xffff0000, v20
	v_lshlrev_b32_e32 v16, 16, v21
	v_and_b32_e32 v17, 0xffff0000, v21
	v_pk_mul_f32 v[16:17], v[194:195], v[16:17] op_sel_hi:[0,1]
	v_pk_mul_f32 v[10:11], v[194:195], v[10:11] op_sel_hi:[0,1]
	v_pk_mul_f32 v[10:11], v[44:45], v[10:11]
	v_pk_mul_f32 v[16:17], v[46:47], v[16:17]
	v_pk_fma_f32 v[4:5], v[4:5], v[10:11], v[8:9]
	v_pk_fma_f32 v[6:7], v[6:7], v[16:17], v[14:15]
	global_store_dwordx4 v[12:13], v[4:7], off offset:512 nt
	v_lshlrev_b32_e32 v10, 16, v23
	v_and_b32_e32 v11, 0xffff0000, v23
	v_lshlrev_b32_e32 v6, 16, v22
	v_and_b32_e32 v7, 0xffff0000, v22
	v_pk_mul_f32 v[10:11], v[194:195], v[10:11] op_sel_hi:[0,1]
	v_pk_mul_f32 v[6:7], v[194:195], v[6:7] op_sel_hi:[0,1]
	v_lshlrev_b32_e32 v4, 16, v18
	v_and_b32_e32 v5, 0xffff0000, v18
	v_lshlrev_b32_e32 v8, 16, v19
	v_and_b32_e32 v9, 0xffff0000, v19
	v_pk_mul_f32 v[6:7], v[36:37], v[6:7]
	v_pk_mul_f32 v[10:11], v[38:39], v[10:11]
	v_pk_fma_f32 v[0:1], v[0:1], v[6:7], v[4:5]
	v_pk_fma_f32 v[2:3], v[2:3], v[10:11], v[8:9]
	global_store_dwordx4 v[12:13], v[32:35], off nt
	global_store_dwordx4 v[12:13], v[0:3], off offset:528 nt
	s_cbranch_vccz .LBB0_2024
	s_waitcnt vmcnt(0)
	s_cmpk_gt_u32 s19, 0xff
	s_cbranch_scc1 .LBB0_2035
	s_barrier
